# k46: row-phase gain / mix vectors loaded once before the row loop into dedicated VGPRs (consumers read them directly, 104 reloads per trip set removed, counted waits re-derived)
# speedup vs baseline: 1.0221x; 1.0022x over previous
.LBB0_55:
	s_or_b64 exec, exec, s[6:7]
	s_add_u32 s86, s92, 0x7900000
	s_addc_u32 s87, s93, 0
	s_add_u32 s0, s92, 0x27d00000
	s_addc_u32 s1, s93, 0
	v_writelane_b32 v254, s0, 62
	s_and_b32 s85, s88, 0xf8
	s_nop 0
	v_writelane_b32 v254, s1, 63
	s_lshl_b32 s0, s84, 6
	s_and_b32 s0, s0, 0xfffff800
	s_or_b32 s1, s85, s0
	s_add_i32 s1, s18, s1
	s_addk_i32 s1, 0x700
	v_readlane_b32 s36, v254, 46
	s_cmp_ge_i32 s1, s0
	v_readlane_b32 s37, v254, 47
	v_readlane_b32 s40, v254, 50
	v_readlane_b32 s41, v254, 51
	v_readlane_b32 s44, v254, 54
	v_readlane_b32 s45, v254, 55
	v_readlane_b32 s38, v254, 48
	v_readlane_b32 s39, v254, 49
	v_readlane_b32 s42, v254, 52
	v_readlane_b32 s43, v254, 53
	v_readlane_b32 s46, v254, 56
	v_readlane_b32 s47, v254, 57
	v_readlane_b32 s48, v254, 58
	v_readlane_b32 s49, v254, 59
	v_readlane_b32 s50, v254, 60
	v_readlane_b32 s51, v254, 61
	s_cbranch_scc0 .LBB0_58
	v_lshlrev_b32_e32 v20, 5, v1
	global_load_dwordx4 v[2:5], v20, s[40:41] offset:16
	global_load_dwordx4 v[6:9], v20, s[40:41]
	global_load_dwordx4 v[10:13], v20, s[40:41] offset:2064
	global_load_dwordx4 v[14:17], v20, s[40:41] offset:2048
	v_mov_b32_e32 v21, 0
	v_readlane_b32 s6, v254, 62
	v_lshlrev_b32_e32 v24, 4, v1
	v_mov_b32_e32 v25, v21
	v_readlane_b32 s7, v254, 63
	v_or_b32_e32 v22, 0x200, v18
	v_lshl_add_u64 v[100:101], s[86:87], 0, v[24:25]
	v_lshl_add_u64 v[98:99], s[6:7], 0, v[24:25]
	s_add_u32 s6, s44, 0x1000
	s_addc_u32 s7, s45, 0
	v_lshlrev_b32_e32 v24, 2, v22
	v_lshl_add_u64 v[104:105], s[6:7], 0, v[20:21]
	v_lshl_add_u64 v[106:107], s[6:7], 0, v[24:25]
	s_add_u32 s6, s44, 0x2000
	s_addc_u32 s7, s45, 0
	v_lshl_add_u64 v[108:109], s[6:7], 0, v[20:21]
	v_lshl_add_u64 v[110:111], s[6:7], 0, v[24:25]
	s_add_u32 s6, s44, 0x3000
	s_addc_u32 s7, s45, 0
	v_lshl_add_u64 v[102:103], s[44:45], 0, v[20:21]
	v_lshl_add_u64 v[112:113], s[6:7], 0, v[20:21]
	v_lshl_add_u64 v[114:115], s[6:7], 0, v[24:25]
	v_lshl_add_u64 v[116:117], s[36:37], 0, v[20:21]
	s_lshl_b32 s6, s1, 2
	v_lshlrev_b32_e32 v1, 2, v18
	v_lshlrev_b32_e32 v172, 2, v22
	v_mov_b32_e32 v173, 0x358637bd
	s_mov_b32 s14, 0x8100000
	s_mov_b32 s15, 0x10200000
	s_mov_b32 s16, 0x18300000
	global_load_dwordx4 v[228:231], v[102:103], off
	global_load_dwordx4 v[232:235], v[102:103], off offset:16
	global_load_dwordx4 v[236:239], v[102:103], off offset:2048
	global_load_dwordx4 v[240:243], v[102:103], off offset:2064
	global_load_dwordx4 v[244:247], v[104:105], off
	global_load_dwordx4 v[248:251], v[104:105], off offset:16
	s_waitcnt vmcnt(0)
.LBB0_57:
	s_and_b32 s17, s1, 0x7ff
	s_ashr_i32 s7, s6, 31
	s_cmp_lg_u32 s17, 0
	s_cselect_b64 s[8:9], -1, 0
	v_cndmask_b32_e64 v18, 0, 1, s[8:9]
	v_mov_b32_e32 v19, s7
	s_lshl_b64 s[8:9], s[6:7], 12
	v_sub_co_u32_e32 v18, vcc, s6, v18
	s_add_u32 s8, s36, s8
	s_nop 0
	v_subbrev_co_u32_e32 v19, vcc, 0, v19, vcc
	v_lshlrev_b64 v[18:19], 12, v[18:19]
	s_addc_u32 s9, s37, s9
	global_load_dwordx4 v[50:53], v1, s[8:9] nt
	global_load_dwordx4 v[66:69], v1, s[8:9] offset:16 nt
	global_load_dwordx4 v[74:77], v1, s[8:9] offset:2064 nt
	global_load_dwordx4 v[70:73], v1, s[8:9] offset:2048 nt
	v_lshl_add_u64 v[18:19], v[116:117], 0, v[18:19]
	s_add_u32 s10, s8, 0x1000
	global_load_dwordx4 v[62:65], v[18:19], off nt
	global_load_dwordx4 v[54:57], v[18:19], off offset:16 nt
	global_load_dwordx4 v[46:49], v[18:19], off offset:2064 nt
	global_load_dwordx4 v[58:61], v[18:19], off offset:2048 nt
	s_addc_u32 s11, s9, 0
	global_load_dwordx4 v[30:33], v1, s[10:11] nt
	global_load_dwordx4 v[34:37], v1, s[10:11] offset:16 nt
	global_load_dwordx4 v[42:45], v172, s[10:11] offset:16 nt
	global_load_dwordx4 v[38:41], v172, s[10:11] nt
	s_add_u32 s10, s8, 0x2000
	s_addc_u32 s11, s9, 0
	global_load_dwordx4 v[18:21], v1, s[10:11] nt
	global_load_dwordx4 v[22:25], v1, s[10:11] offset:16 nt
	global_load_dwordx4 v[26:29], v172, s[10:11] nt
	global_load_dwordx4 v[86:89], v172, s[10:11] offset:16 nt
	s_add_u32 s8, s8, 0x3000
	s_addc_u32 s9, s9, 0
	global_load_dwordx4 v[78:81], v1, s[8:9] offset:16 nt
	global_load_dwordx4 v[82:85], v1, s[8:9] nt
	global_load_dwordx4 v[90:93], v172, s[8:9] nt
	global_load_dwordx4 v[94:97], v172, s[8:9] offset:16 nt
	s_cmp_eq_u32 s17, 0
	s_waitcnt vmcnt(19)
	v_pk_mul_f32 v[118:119], v[52:53], v[52:53]
	v_pk_mul_f32 v[120:121], v[50:51], v[50:51]
	s_waitcnt vmcnt(18)
	v_pk_mul_f32 v[122:123], v[68:69], v[68:69]
	v_pk_mul_f32 v[124:125], v[66:67], v[66:67]
	s_waitcnt vmcnt(16)
	v_mul_f32_e32 v126, v71, v71
	v_mul_f32_e32 v128, v73, v73
	v_mul_f32_e32 v141, v76, v76
	v_mul_f32_e32 v144, v77, v77
	s_waitcnt vmcnt(15)
	v_pk_mul_f32 v[130:131], v[64:65], v[64:65]
	v_pk_mul_f32 v[132:133], v[62:63], v[62:63]
	s_waitcnt vmcnt(14)
	v_pk_mul_f32 v[134:135], v[56:57], v[56:57]
	v_pk_mul_f32 v[136:137], v[54:55], v[54:55]
	v_pk_mov_b32 v[138:139], v[120:121], v[118:119] op_sel:[1,0]
	v_mov_b32_e32 v121, v119
	v_pk_mov_b32 v[118:119], v[124:125], v[122:123] op_sel:[1,0]
	v_mov_b32_e32 v125, v123
	s_waitcnt vmcnt(12)
	v_mul_f32_e32 v122, v59, v59
	v_mul_f32_e32 v140, v61, v61
	v_pk_fma_f32 v[126:127], v[70:71], v[70:71], v[126:127] op_sel_hi:[1,1,0]
	v_pk_fma_f32 v[128:129], v[72:73], v[72:73], v[128:129] op_sel_hi:[1,1,0]
	v_mul_f32_e32 v156, v48, v48
	v_mul_f32_e32 v157, v49, v49
	v_mul_f32_e32 v147, v46, v46
	v_mul_f32_e32 v149, v47, v47
	v_pk_mov_b32 v[142:143], v[132:133], v[130:131] op_sel:[1,0]
	v_mov_b32_e32 v133, v131
	v_pk_mov_b32 v[130:131], v[136:137], v[134:135] op_sel:[1,0]
	v_mov_b32_e32 v137, v135
	v_pk_add_f32 v[134:135], v[138:139], v[120:121]
	v_pk_add_f32 v[118:119], v[118:119], v[124:125]
	v_pk_fma_f32 v[122:123], v[58:59], v[58:59], v[122:123] op_sel_hi:[1,1,0]
	v_pk_fma_f32 v[138:139], v[60:61], v[60:61], v[140:141] op_sel_hi:[1,1,0]
	v_mov_b32_e32 v127, v141
	v_mov_b32_e32 v129, v144
	s_waitcnt vmcnt(11)
	v_pk_mul_f32 v[124:125], v[32:33], v[32:33]
	v_pk_mul_f32 v[140:141], v[30:31], v[30:31]
	s_waitcnt vmcnt(10)
	v_pk_mul_f32 v[144:145], v[36:37], v[36:37]
	v_pk_mul_f32 v[152:153], v[34:35], v[34:35]
	s_waitcnt vmcnt(8)
	v_mul_f32_e32 v146, v39, v39
	v_mul_f32_e32 v148, v41, v41
	v_mul_f32_e32 v158, v74, v74
	v_mul_f32_e32 v159, v75, v75
	v_mul_f32_e32 v160, v44, v44
	v_mul_f32_e32 v161, v45, v45
	v_pk_add_f32 v[142:143], v[142:143], v[132:133]
	v_pk_add_f32 v[154:155], v[130:131], v[136:137]
	v_mov_b32_e32 v123, v156
	v_mov_b32_e32 v139, v157
	v_pk_add_f32 v[120:121], v[126:127], v[128:129]
	v_pk_mov_b32 v[126:127], v[140:141], v[124:125] op_sel:[1,0]
	v_mov_b32_e32 v141, v125
	v_pk_mov_b32 v[156:157], v[152:153], v[144:145] op_sel:[1,0]
	v_mov_b32_e32 v153, v145
	v_pk_add_f32 v[124:125], v[134:135], v[134:135] op_sel:[0,1] op_sel_hi:[1,0]
	v_pk_add_f32 v[132:133], v[118:119], v[118:119] op_sel:[0,1] op_sel_hi:[1,0]
	v_pk_fma_f32 v[130:131], v[38:39], v[38:39], v[146:147] op_sel_hi:[1,1,0]
	v_pk_fma_f32 v[136:137], v[40:41], v[40:41], v[148:149] op_sel_hi:[1,1,0]
	v_pk_add_f32 v[118:119], v[122:123], v[138:139]
	v_pk_add_f32 v[128:129], v[126:127], v[140:141]
	v_mov_b32_e32 v125, v158
	v_pk_add_f32 v[134:135], v[156:157], v[152:153]
	v_mov_b32_e32 v133, v159
	v_mov_b32_e32 v131, v160
	v_mov_b32_e32 v137, v161
	v_pk_add_f32 v[122:123], v[142:143], v[142:143] op_sel:[0,1] op_sel_hi:[1,0]
	v_pk_add_f32 v[126:127], v[154:155], v[154:155] op_sel:[0,1] op_sel_hi:[1,0]
	s_waitcnt vmcnt(7)
	v_pk_mul_f32 v[142:143], v[20:21], v[20:21]
	v_pk_mul_f32 v[138:139], v[18:19], v[18:19]
	s_waitcnt vmcnt(6)
	v_pk_mul_f32 v[144:145], v[24:25], v[24:25]
	v_pk_mul_f32 v[140:141], v[22:23], v[22:23]
	v_mul_f32_e32 v150, v42, v42
	v_mul_f32_e32 v151, v43, v43
	s_waitcnt vmcnt(5)
	v_mul_f32_e32 v146, v27, v27
	v_pk_add_f32 v[124:125], v[124:125], v[132:133]
	v_pk_add_f32 v[130:131], v[130:131], v[136:137]
	v_mov_b32_e32 v123, v147
	v_mov_b32_e32 v127, v149
	v_pk_add_f32 v[128:129], v[128:129], v[128:129] op_sel:[0,1] op_sel_hi:[1,0]
	v_pk_add_f32 v[132:133], v[134:135], v[134:135] op_sel:[0,1] op_sel_hi:[1,0]
	v_pk_mov_b32 v[134:135], v[138:139], v[142:143] op_sel:[1,0]
	v_mov_b32_e32 v139, v143
	v_pk_mov_b32 v[136:137], v[140:141], v[144:145] op_sel:[1,0]
	v_mov_b32_e32 v141, v145
	s_waitcnt vmcnt(4)
	v_mul_f32_e32 v152, v88, v88
	v_mul_f32_e32 v148, v29, v29
	v_pk_fma_f32 v[142:143], v[26:27], v[26:27], v[146:147] op_sel_hi:[1,1,0]
	v_pk_add_f32 v[122:123], v[122:123], v[126:127]
	v_pk_add_f32 v[120:121], v[124:125], v[120:121]
	v_mov_b32_e32 v129, v150
	v_mov_b32_e32 v133, v151
	v_pk_add_f32 v[124:125], v[134:135], v[138:139]
	v_pk_add_f32 v[126:127], v[136:137], v[140:141]
	v_mul_f32_e32 v153, v89, v89
	v_mul_f32_e32 v154, v86, v86
	v_mul_f32_e32 v155, v87, v87
	v_pk_fma_f32 v[144:145], v[28:29], v[28:29], v[148:149] op_sel_hi:[1,1,0]
	v_mov_b32_e32 v143, v152
	s_waitcnt vmcnt(2)
	v_pk_mul_f32 v[134:135], v[84:85], v[84:85]
	v_pk_mul_f32 v[136:137], v[82:83], v[82:83]
	v_pk_mul_f32 v[138:139], v[80:81], v[80:81]
	v_pk_mul_f32 v[140:141], v[78:79], v[78:79]
	v_pk_add_f32 v[118:119], v[122:123], v[118:119]
	v_add_f32_e32 v152, v120, v121
	v_pk_add_f32 v[120:121], v[128:129], v[132:133]
	v_pk_add_f32 v[124:125], v[124:125], v[124:125] op_sel:[0,1] op_sel_hi:[1,0]
	v_pk_add_f32 v[126:127], v[126:127], v[126:127] op_sel:[0,1] op_sel_hi:[1,0]
	v_mov_b32_e32 v145, v153
	v_pk_mov_b32 v[128:129], v[136:137], v[134:135] op_sel:[1,0]
	v_mov_b32_e32 v137, v135
	v_pk_mov_b32 v[132:133], v[140:141], v[138:139] op_sel:[1,0]
	v_mov_b32_e32 v141, v139
	v_pk_add_f32 v[120:121], v[120:121], v[130:131]
	v_add_f32_e32 v130, v118, v119
	v_add_f32_dpp v131, v152, v152 quad_perm:[1,0,3,2] row_mask:0xf bank_mask:0xf bound_ctrl:1
	v_mov_b32_e32 v125, v154
	v_mov_b32_e32 v127, v155
	s_waitcnt vmcnt(1)
	v_mul_f32_e32 v146, v91, v91
	s_waitcnt vmcnt(0)
	v_mul_f32_e32 v147, v96, v96
	v_mul_f32_e32 v148, v93, v93
	v_mul_f32_e32 v149, v97, v97
	v_pk_add_f32 v[122:123], v[142:143], v[144:145]
	v_pk_add_f32 v[118:119], v[128:129], v[136:137]
	v_pk_add_f32 v[128:129], v[132:133], v[140:141]
	v_add_f32_dpp v130, v130, v130 quad_perm:[1,0,3,2] row_mask:0xf bank_mask:0xf bound_ctrl:1
	v_add_f32_dpp v131, v131, v131 quad_perm:[2,3,0,1] row_mask:0xf bank_mask:0xf bound_ctrl:1
	v_add_f32_e32 v132, v120, v121
	v_pk_add_f32 v[120:121], v[124:125], v[126:127]
	v_mul_f32_e32 v150, v94, v94
	v_mul_f32_e32 v151, v95, v95
	v_pk_fma_f32 v[134:135], v[90:91], v[90:91], v[146:147] op_sel_hi:[1,1,0]
	v_pk_fma_f32 v[138:139], v[92:93], v[92:93], v[148:149] op_sel_hi:[1,1,0]
	v_pk_add_f32 v[118:119], v[118:119], v[118:119] op_sel:[0,1] op_sel_hi:[1,0]
	v_pk_add_f32 v[126:127], v[128:129], v[128:129] op_sel:[0,1] op_sel_hi:[1,0]
	v_add_f32_dpp v128, v130, v130 quad_perm:[2,3,0,1] row_mask:0xf bank_mask:0xf bound_ctrl:1
	v_add_f32_dpp v129, v131, v131 row_half_mirror row_mask:0xf bank_mask:0xf bound_ctrl:1
	v_add_f32_dpp v130, v132, v132 quad_perm:[1,0,3,2] row_mask:0xf bank_mask:0xf bound_ctrl:1
	v_pk_add_f32 v[120:121], v[120:121], v[122:123]
	v_mov_b32_e32 v135, v147
	v_mov_b32_e32 v139, v149
	v_mov_b32_e32 v119, v150
	v_mov_b32_e32 v127, v151
	v_add_f32_dpp v122, v128, v128 row_half_mirror row_mask:0xf bank_mask:0xf bound_ctrl:1
	v_add_f32_dpp v123, v129, v129 row_mirror row_mask:0xf bank_mask:0xf bound_ctrl:1
	v_add_f32_dpp v128, v130, v130 quad_perm:[2,3,0,1] row_mask:0xf bank_mask:0xf bound_ctrl:1
	v_add_f32_e32 v120, v120, v121
	v_pk_add_f32 v[124:125], v[134:135], v[138:139]
	v_pk_add_f32 v[118:119], v[118:119], v[126:127]
	v_add_f32_dpp v121, v122, v122 row_mirror row_mask:0xf bank_mask:0xf bound_ctrl:1
	v_readlane_b32 s8, v123, 0
	v_readlane_b32 s17, v123, 16
	v_readlane_b32 s9, v123, 32
	v_readlane_b32 s18, v123, 48
	v_add_f32_dpp v122, v128, v128 row_half_mirror row_mask:0xf bank_mask:0xf bound_ctrl:1
	v_add_f32_dpp v123, v120, v120 quad_perm:[1,0,3,2] row_mask:0xf bank_mask:0xf bound_ctrl:1
	v_pk_add_f32 v[118:119], v[118:119], v[124:125]
	v_readlane_b32 s10, v121, 0
	v_readlane_b32 s19, v121, 16
	v_readlane_b32 s11, v121, 32
	v_readlane_b32 s20, v121, 48
	v_mov_b32_e32 v120, s17
	v_mov_b32_e32 v121, s18
	v_add_f32_dpp v122, v122, v122 row_mirror row_mask:0xf bank_mask:0xf bound_ctrl:1
	v_add_f32_dpp v123, v123, v123 quad_perm:[2,3,0,1] row_mask:0xf bank_mask:0xf bound_ctrl:1
	v_add_f32_e32 v124, v118, v119
	v_pk_add_f32 v[118:119], s[8:9], v[120:121]
	v_mov_b32_e32 v120, s19
	v_mov_b32_e32 v121, s20
	v_readlane_b32 s8, v122, 0
	v_readlane_b32 s17, v122, 16
	v_readlane_b32 s9, v122, 32
	v_readlane_b32 s18, v122, 48
	v_add_f32_dpp v122, v123, v123 row_half_mirror row_mask:0xf bank_mask:0xf bound_ctrl:1
	v_add_f32_dpp v123, v124, v124 quad_perm:[1,0,3,2] row_mask:0xf bank_mask:0xf bound_ctrl:1
	v_add_f32_e32 v124, v118, v119
	v_pk_add_f32 v[118:119], s[10:11], v[120:121]
	v_mov_b32_e32 v120, s17
	v_mov_b32_e32 v121, s18
	v_add_f32_dpp v122, v122, v122 row_mirror row_mask:0xf bank_mask:0xf bound_ctrl:1
	v_add_f32_dpp v123, v123, v123 quad_perm:[2,3,0,1] row_mask:0xf bank_mask:0xf bound_ctrl:1
	v_add_f32_e32 v125, v118, v119
	v_pk_add_f32 v[118:119], s[8:9], v[120:121]
	v_readlane_b32 s10, v122, 16
	v_readlane_b32 s11, v122, 48
	v_fmamk_f32 v124, v124, 0x3a800000, v173
	v_readlane_b32 s8, v122, 0
	v_readlane_b32 s9, v122, 32
	v_add_f32_dpp v121, v123, v123 row_half_mirror row_mask:0xf bank_mask:0xf bound_ctrl:1
	v_fmamk_f32 v122, v125, 0x3a800000, v173
	v_add_f32_e32 v123, v118, v119
	v_mov_b32_e32 v118, s10
	v_mov_b32_e32 v119, s11
	v_rsq_f32_e32 v120, v124
	v_add_f32_dpp v121, v121, v121 row_mirror row_mask:0xf bank_mask:0xf bound_ctrl:1
	v_rsq_f32_e32 v122, v122
	v_fmamk_f32 v123, v123, 0x3a800000, v173
	v_pk_add_f32 v[118:119], s[8:9], v[118:119]
	v_readlane_b32 s10, v121, 0
	v_readlane_b32 s17, v121, 16
	v_readlane_b32 s11, v121, 32
	v_readlane_b32 s18, v121, 48
	v_rsq_f32_e32 v124, v123
	v_add_f32_e32 v121, v118, v119
	v_fmamk_f32 v121, v121, 0x3a800000, v173
	v_mov_b32_e32 v118, s17
	v_mov_b32_e32 v119, s18
	v_rsq_f32_e32 v174, v121
	v_pk_add_f32 v[118:119], s[10:11], v[118:119]
	v_pk_mul_f32 v[168:169], v[120:121], v[68:69] op_sel_hi:[0,1]
	v_pk_mul_f32 v[66:67], v[120:121], v[66:67] op_sel_hi:[0,1]
	v_pk_mul_f32 v[52:53], v[120:121], v[52:53] op_sel_hi:[0,1]
	v_pk_mul_f32 v[50:51], v[120:121], v[50:51] op_sel_hi:[0,1]
	v_pk_mul_f32 v[64:65], v[122:123], v[64:65] op_sel_hi:[0,1]
	v_pk_mul_f32 v[62:63], v[122:123], v[62:63] op_sel_hi:[0,1]
	s_cselect_b64 s[10:11], -1, 0
	s_lshl_b64 s[8:9], s[6:7], 11
	v_pk_mul_f32 v[76:77], v[120:121], v[76:77] op_sel_hi:[0,1]
	v_pk_mul_f32 v[142:143], v[120:121], v[74:75] op_sel_hi:[0,1]
	v_pk_mul_f32 v[164:165], v[120:121], v[72:73] op_sel_hi:[0,1]
	v_pk_mul_f32 v[166:167], v[120:121], v[70:71] op_sel_hi:[0,1]
	v_pk_mul_f32 v[152:153], v[50:51], v[6:7]
	v_pk_mul_f32 v[160:161], v[52:53], v[8:9]
	v_pk_mul_f32 v[150:151], v[66:67], v[2:3]
	v_pk_mul_f32 v[158:159], v[168:169], v[4:5]
	v_pk_mul_f32 v[198:199], v[124:125], v[36:37] op_sel_hi:[0,1]
	v_pk_mul_f32 v[200:201], v[124:125], v[34:35] op_sel_hi:[0,1]
	v_pk_mul_f32 v[202:203], v[124:125], v[32:33] op_sel_hi:[0,1]
	v_pk_mul_f32 v[204:205], v[124:125], v[30:31] op_sel_hi:[0,1]
	v_pk_mul_f32 v[34:35], v[64:65], v[8:9]
	v_cvt_pk_bf16_f32 v30, v152, v153
	v_cvt_pk_bf16_f32 v31, v160, v161
	v_cvt_pk_bf16_f32 v32, v150, v151
	v_cvt_pk_bf16_f32 v33, v158, v159
	v_pk_mul_f32 v[36:37], v[62:63], v[6:7]
	v_lshl_add_u64 v[162:163], v[98:99], 0, s[8:9]
	v_pk_mul_f32 v[148:149], v[166:167], v[14:15]
	v_pk_mul_f32 v[156:157], v[164:165], v[16:17]
	v_pk_mul_f32 v[146:147], v[142:143], v[10:11]
	v_pk_mul_f32 v[154:155], v[76:77], v[12:13]
	v_cndmask_b32_e64 v35, v35, 0, s[10:11]
	v_cndmask_b32_e64 v34, v34, 0, s[10:11]
	v_cndmask_b32_e64 v37, v37, 0, s[10:11]
	v_cndmask_b32_e64 v36, v36, 0, s[10:11]
	global_store_dwordx4 v[162:163], v[30:33], off
	v_pk_fma_f32 v[208:209], v[50:51], v[6:7], v[36:37] neg_lo:[1,0,0] neg_hi:[1,0,0]
	v_pk_fma_f32 v[210:211], v[52:53], v[8:9], v[34:35] neg_lo:[1,0,0] neg_hi:[1,0,0]
	v_cvt_pk_bf16_f32 v30, v148, v149
	v_cvt_pk_bf16_f32 v31, v156, v157
	v_cvt_pk_bf16_f32 v32, v146, v147
	v_cvt_pk_bf16_f32 v33, v154, v155
	global_store_dwordx4 v[162:163], v[30:33], off offset:1024
	v_pk_mul_f32 v[36:37], v[174:175], v[86:87] op_sel_hi:[0,1]
	v_pk_mul_f32 v[34:35], v[174:175], v[88:89] op_sel_hi:[0,1]
	v_pk_mul_f32 v[26:27], v[174:175], v[26:27] op_sel_hi:[0,1]
	v_pk_mul_f32 v[28:29], v[174:175], v[28:29] op_sel_hi:[0,1]
	v_pk_mul_f32 v[22:23], v[174:175], v[22:23] op_sel_hi:[0,1]
	v_pk_mul_f32 v[24:25], v[174:175], v[24:25] op_sel_hi:[0,1]
	v_pk_mul_f32 v[18:19], v[174:175], v[18:19] op_sel_hi:[0,1]
	v_pk_mul_f32 v[20:21], v[174:175], v[20:21] op_sel_hi:[0,1]
	v_pk_mul_f32 v[56:57], v[122:123], v[56:57] op_sel_hi:[0,1]
	v_pk_mul_f32 v[54:55], v[122:123], v[54:55] op_sel_hi:[0,1]
	v_pk_mul_f32 v[60:61], v[122:123], v[60:61] op_sel_hi:[0,1]
	v_pk_mul_f32 v[58:59], v[122:123], v[58:59] op_sel_hi:[0,1]
	v_pk_mul_f32 v[48:49], v[122:123], v[48:49] op_sel_hi:[0,1]
	v_pk_mul_f32 v[46:47], v[122:123], v[46:47] op_sel_hi:[0,1]
	v_pk_mul_f32 v[194:195], v[124:125], v[40:41] op_sel_hi:[0,1]
	v_pk_mul_f32 v[196:197], v[124:125], v[38:39] op_sel_hi:[0,1]
	v_pk_mul_f32 v[38:39], v[56:57], v[4:5]
	v_pk_mul_f32 v[40:41], v[54:55], v[2:3]
	v_pk_mul_f32 v[190:191], v[124:125], v[44:45] op_sel_hi:[0,1]
	v_pk_mul_f32 v[192:193], v[124:125], v[42:43] op_sel_hi:[0,1]
	v_pk_mul_f32 v[42:43], v[60:61], v[16:17]
	v_pk_mul_f32 v[44:45], v[58:59], v[14:15]
	v_pk_mul_f32 v[48:49], v[48:49], v[12:13]
	v_pk_mul_f32 v[46:47], v[46:47], v[10:11]
	v_cndmask_b32_e64 v39, v39, 0, s[10:11]
	v_cndmask_b32_e64 v38, v38, 0, s[10:11]
	v_cndmask_b32_e64 v41, v41, 0, s[10:11]
	v_cndmask_b32_e64 v40, v40, 0, s[10:11]
	v_cndmask_b32_e64 v43, v43, 0, s[10:11]
	v_cndmask_b32_e64 v42, v42, 0, s[10:11]
	v_cndmask_b32_e64 v45, v45, 0, s[10:11]
	v_cndmask_b32_e64 v44, v44, 0, s[10:11]
	v_cndmask_b32_e64 v49, v49, 0, s[10:11]
	v_cndmask_b32_e64 v48, v48, 0, s[10:11]
	v_cndmask_b32_e64 v47, v47, 0, s[10:11]
	v_cndmask_b32_e64 v46, v46, 0, s[10:11]
	v_pk_fma_f32 v[212:213], v[66:67], v[2:3], v[40:41] neg_lo:[1,0,0] neg_hi:[1,0,0]
	v_pk_fma_f32 v[214:215], v[168:169], v[4:5], v[38:39] neg_lo:[1,0,0] neg_hi:[1,0,0]
	v_lshl_add_u64 v[144:145], v[100:101], 0, s[8:9]
	v_pk_fma_f32 v[216:217], v[166:167], v[14:15], v[44:45] neg_lo:[1,0,0] neg_hi:[1,0,0]
	v_pk_fma_f32 v[218:219], v[164:165], v[16:17], v[42:43] neg_lo:[1,0,0] neg_hi:[1,0,0]
	v_pk_fma_f32 v[220:221], v[142:143], v[10:11], v[46:47] neg_lo:[1,0,0] neg_hi:[1,0,0]
	v_pk_fma_f32 v[222:223], v[76:77], v[12:13], v[48:49] neg_lo:[1,0,0] neg_hi:[1,0,0]
	v_add_co_u32_e32 v170, vcc, s14, v144
	v_add_f32_e32 v68, v118, v119
	s_nop 0
	v_addc_co_u32_e32 v171, vcc, 0, v145, vcc
	v_add_co_u32_e32 v168, vcc, s15, v144
	v_pk_fma_f32 v[126:127], v[204:205], v[6:7], v[152:153] neg_lo:[1,0,0] neg_hi:[1,0,0]
	s_nop 0
	v_addc_co_u32_e32 v169, vcc, 0, v145, vcc
	v_add_co_u32_e32 v164, vcc, s16, v144
	v_pk_fma_f32 v[134:135], v[202:203], v[8:9], v[160:161] neg_lo:[1,0,0] neg_hi:[1,0,0]
	v_pk_fma_f32 v[128:129], v[200:201], v[2:3], v[150:151] neg_lo:[1,0,0] neg_hi:[1,0,0]
	v_pk_fma_f32 v[136:137], v[198:199], v[4:5], v[158:159] neg_lo:[1,0,0] neg_hi:[1,0,0]
	v_pk_fma_f32 v[130:131], v[196:197], v[14:15], v[148:149] neg_lo:[1,0,0] neg_hi:[1,0,0]
	v_pk_fma_f32 v[132:133], v[192:193], v[10:11], v[146:147] neg_lo:[1,0,0] neg_hi:[1,0,0]
	v_addc_co_u32_e32 v165, vcc, 0, v145, vcc
	v_fmamk_f32 v68, v68, 0x3a800000, v173
	v_pk_fma_f32 v[138:139], v[194:195], v[16:17], v[156:157] neg_lo:[1,0,0] neg_hi:[1,0,0]
	v_pk_fma_f32 v[140:141], v[190:191], v[12:13], v[154:155] neg_lo:[1,0,0] neg_hi:[1,0,0]
	v_rsq_f32_e32 v206, v68
	v_pk_mul_f32 v[68:69], v[200:201], v[2:3]
	v_pk_mul_f32 v[74:75], v[204:205], v[6:7]
	v_pk_mul_f32 v[124:125], v[202:203], v[8:9]
	v_pk_mul_f32 v[122:123], v[198:199], v[4:5]
	v_pk_mul_f32 v[72:73], v[196:197], v[14:15]
	v_pk_mul_f32 v[120:121], v[194:195], v[16:17]
	v_pk_mul_f32 v[70:71], v[192:193], v[10:11]
	v_pk_mul_f32 v[118:119], v[190:191], v[12:13]
	s_or_b32 s10, s8, 0x1000
	s_mov_b32 s11, s9
	v_lshl_add_u64 v[166:167], v[98:99], 0, s[10:11]
	v_pk_mul_f32 v[42:43], v[24:25], v[4:5]
	v_pk_mul_f32 v[44:45], v[22:23], v[2:3]
	v_pk_mul_f32 v[46:47], v[20:21], v[8:9]
	v_pk_mul_f32 v[48:49], v[18:19], v[6:7]
	v_pk_mul_f32 v[34:35], v[34:35], v[12:13]
	v_pk_mul_f32 v[36:37], v[36:37], v[10:11]
	v_pk_mul_f32 v[38:39], v[28:29], v[16:17]
	v_pk_fma_f32 v[176:177], v[230:231], v[210:211], v[160:161]
	v_pk_fma_f32 v[174:175], v[228:229], v[208:209], v[152:153]
	v_pk_fma_f32 v[180:181], v[234:235], v[214:215], v[158:159]
	v_pk_fma_f32 v[178:179], v[232:233], v[212:213], v[150:151]
	v_cvt_pk_bf16_f32 v174, v174, v175
	v_cvt_pk_bf16_f32 v175, v176, v177
	v_pk_fma_f32 v[184:185], v[238:239], v[218:219], v[156:157]
	v_cvt_pk_bf16_f32 v176, v178, v179
	v_cvt_pk_bf16_f32 v177, v180, v181
	v_pk_fma_f32 v[182:183], v[236:237], v[216:217], v[148:149]
	v_pk_fma_f32 v[188:189], v[242:243], v[222:223], v[154:155]
	v_pk_fma_f32 v[186:187], v[240:241], v[220:221], v[146:147]
	global_store_dwordx4 v[144:145], v[174:177], off
	v_pk_mul_f32 v[40:41], v[26:27], v[14:15]
	v_pk_mul_f32 v[58:59], v[206:207], v[90:91] op_sel_hi:[0,1]
	v_cvt_pk_bf16_f32 v174, v182, v183
	v_cvt_pk_bf16_f32 v175, v184, v185
	v_cvt_pk_bf16_f32 v176, v186, v187
	v_cvt_pk_bf16_f32 v177, v188, v189
	global_store_dwordx4 v[144:145], v[174:177], off offset:1024
	s_nop 0
	global_load_dwordx4 v[182:185], v[106:107], off
	global_load_dwordx4 v[186:189], v[106:107], off offset:16
	v_pk_mul_f32 v[62:63], v[206:207], v[78:79] op_sel_hi:[0,1]
	v_pk_fma_f32 v[78:79], v[204:205], v[6:7], v[48:49] neg_lo:[0,0,1] neg_hi:[0,0,1]
	v_pk_fma_f32 v[90:91], v[202:203], v[8:9], v[46:47] neg_lo:[0,0,1] neg_hi:[0,0,1]
	v_pk_mul_f32 v[54:55], v[206:207], v[92:93] op_sel_hi:[0,1]
	v_pk_mul_f32 v[60:61], v[206:207], v[80:81] op_sel_hi:[0,1]
	v_pk_fma_f32 v[80:81], v[200:201], v[2:3], v[44:45] neg_lo:[0,0,1] neg_hi:[0,0,1]
	v_pk_fma_f32 v[92:93], v[198:199], v[4:5], v[42:43] neg_lo:[0,0,1] neg_hi:[0,0,1]
	v_lshl_add_u64 v[142:143], v[100:101], 0, s[10:11]
	v_pk_mul_f32 v[50:51], v[206:207], v[96:97] op_sel_hi:[0,1]
	v_pk_mul_f32 v[52:53], v[206:207], v[94:95] op_sel_hi:[0,1]
	v_pk_mul_f32 v[64:65], v[206:207], v[84:85] op_sel_hi:[0,1]
	v_pk_mul_f32 v[66:67], v[206:207], v[82:83] op_sel_hi:[0,1]
	v_pk_fma_f32 v[82:83], v[196:197], v[14:15], v[40:41] neg_lo:[0,0,1] neg_hi:[0,0,1]
	v_pk_fma_f32 v[94:95], v[194:195], v[16:17], v[38:39] neg_lo:[0,0,1] neg_hi:[0,0,1]
	v_pk_fma_f32 v[84:85], v[192:193], v[10:11], v[36:37] neg_lo:[0,0,1] neg_hi:[0,0,1]
	v_pk_fma_f32 v[96:97], v[190:191], v[12:13], v[34:35] neg_lo:[0,0,1] neg_hi:[0,0,1]
	v_add_co_u32_e32 v88, vcc, s14, v142
	s_or_b32 s8, s8, 0x1800
	s_nop 0
	v_addc_co_u32_e32 v89, vcc, 0, v143, vcc
	v_add_co_u32_e32 v86, vcc, s15, v142
	v_lshl_add_u64 v[56:57], v[98:99], 0, s[8:9]
	s_nop 0
	v_addc_co_u32_e32 v87, vcc, 0, v143, vcc
	v_add_co_u32_e32 v76, vcc, s16, v142
	v_pk_mul_f32 v[26:27], v[62:63], v[2:3]
	s_nop 0
	v_addc_co_u32_e32 v77, vcc, 0, v143, vcc
	v_pk_mul_f32 v[28:29], v[60:61], v[4:5]
	v_pk_mul_f32 v[30:31], v[66:67], v[6:7]
	v_pk_mul_f32 v[32:33], v[64:65], v[8:9]
	v_pk_mul_f32 v[18:19], v[52:53], v[10:11]
	v_pk_mul_f32 v[20:21], v[50:51], v[12:13]
	v_pk_mul_f32 v[22:23], v[58:59], v[14:15]
	v_pk_mul_f32 v[24:25], v[54:55], v[16:17]
	s_addk_i32 s1, 0xff00
	s_addk_i32 s6, 0xfc00
	s_cmp_lt_i32 s1, s0
	v_pk_fma_f32 v[176:177], v[246:247], v[210:211], v[160:161]
	v_pk_fma_f32 v[174:175], v[244:245], v[208:209], v[152:153]
	v_pk_fma_f32 v[180:181], v[250:251], v[214:215], v[158:159]
	v_pk_fma_f32 v[178:179], v[248:249], v[212:213], v[150:151]
	v_cvt_pk_bf16_f32 v174, v174, v175
	v_cvt_pk_bf16_f32 v175, v176, v177
	s_waitcnt vmcnt(1)
	v_pk_fma_f32 v[184:185], v[184:185], v[218:219], v[156:157]
	v_cvt_pk_bf16_f32 v176, v178, v179
	v_cvt_pk_bf16_f32 v177, v180, v181
	v_pk_fma_f32 v[182:183], v[182:183], v[216:217], v[148:149]
	s_waitcnt vmcnt(0)
	v_pk_fma_f32 v[188:189], v[188:189], v[222:223], v[154:155]
	v_pk_fma_f32 v[186:187], v[186:187], v[220:221], v[146:147]
	global_store_dwordx4 v[170:171], v[174:177], off
	s_nop 1
	v_cvt_pk_bf16_f32 v174, v182, v183
	v_cvt_pk_bf16_f32 v175, v184, v185
	v_cvt_pk_bf16_f32 v176, v186, v187
	v_cvt_pk_bf16_f32 v177, v188, v189
	global_store_dwordx4 v[170:171], v[174:177], off offset:1024
	global_load_dwordx4 v[174:177], v[108:109], off
	s_nop 0
	global_load_dwordx4 v[178:181], v[108:109], off offset:16
	global_load_dwordx4 v[182:185], v[110:111], off
	global_load_dwordx4 v[186:189], v[110:111], off offset:16
	s_waitcnt vmcnt(3)
	v_pk_fma_f32 v[176:177], v[176:177], v[210:211], v[160:161]
	v_pk_fma_f32 v[174:175], v[174:175], v[208:209], v[152:153]
	s_waitcnt vmcnt(2)
	v_pk_fma_f32 v[180:181], v[180:181], v[214:215], v[158:159]
	v_pk_fma_f32 v[178:179], v[178:179], v[212:213], v[150:151]
	v_cvt_pk_bf16_f32 v174, v174, v175
	v_cvt_pk_bf16_f32 v175, v176, v177
	s_waitcnt vmcnt(1)
	v_pk_fma_f32 v[184:185], v[184:185], v[218:219], v[156:157]
	v_cvt_pk_bf16_f32 v176, v178, v179
	v_cvt_pk_bf16_f32 v177, v180, v181
	v_pk_fma_f32 v[182:183], v[182:183], v[216:217], v[148:149]
	s_waitcnt vmcnt(0)
	v_pk_fma_f32 v[188:189], v[188:189], v[222:223], v[154:155]
	v_pk_fma_f32 v[186:187], v[186:187], v[220:221], v[146:147]
	global_store_dwordx4 v[168:169], v[174:177], off
	s_nop 1
	v_cvt_pk_bf16_f32 v174, v182, v183
	v_cvt_pk_bf16_f32 v175, v184, v185
	v_cvt_pk_bf16_f32 v176, v186, v187
	v_cvt_pk_bf16_f32 v177, v188, v189
	global_store_dwordx4 v[168:169], v[174:177], off offset:1024
	global_load_dwordx4 v[174:177], v[112:113], off
	s_nop 0
	global_load_dwordx4 v[178:181], v[112:113], off offset:16
	global_load_dwordx4 v[182:185], v[114:115], off
	global_load_dwordx4 v[186:189], v[114:115], off offset:16
	s_waitcnt vmcnt(3)
	v_pk_fma_f32 v[160:161], v[176:177], v[210:211], v[160:161]
	v_pk_fma_f32 v[152:153], v[174:175], v[208:209], v[152:153]
	s_waitcnt vmcnt(2)
	v_pk_fma_f32 v[158:159], v[180:181], v[214:215], v[158:159]
	v_pk_fma_f32 v[150:151], v[178:179], v[212:213], v[150:151]
	s_waitcnt vmcnt(1)
	v_pk_fma_f32 v[174:175], v[182:183], v[216:217], v[148:149]
	s_waitcnt vmcnt(0)
	v_pk_fma_f32 v[176:177], v[186:187], v[220:221], v[146:147]
	v_cvt_pk_bf16_f32 v146, v152, v153
	v_cvt_pk_bf16_f32 v147, v160, v161
	v_cvt_pk_bf16_f32 v148, v150, v151
	v_cvt_pk_bf16_f32 v149, v158, v159
	v_pk_fma_f32 v[156:157], v[184:185], v[218:219], v[156:157]
	v_pk_fma_f32 v[154:155], v[188:189], v[222:223], v[154:155]
	global_store_dwordx4 v[164:165], v[146:149], off
	s_nop 1
	v_cvt_pk_bf16_f32 v146, v174, v175
	v_cvt_pk_bf16_f32 v147, v156, v157
	v_cvt_pk_bf16_f32 v148, v176, v177
	v_cvt_pk_bf16_f32 v149, v154, v155
	global_store_dwordx4 v[164:165], v[146:149], off offset:1024
	s_nop 1
	v_cvt_pk_bf16_f32 v146, v74, v75
	v_cvt_pk_bf16_f32 v147, v124, v125
	v_cvt_pk_bf16_f32 v148, v68, v69
	v_cvt_pk_bf16_f32 v149, v122, v123
	global_store_dwordx4 v[162:163], v[146:149], off offset:2048
	s_nop 1
	v_cvt_pk_bf16_f32 v146, v72, v73
	v_cvt_pk_bf16_f32 v147, v120, v121
	v_cvt_pk_bf16_f32 v148, v70, v71
	v_cvt_pk_bf16_f32 v149, v118, v119
	global_store_dwordx4 v[162:163], v[146:149], off offset:3072
	s_nop 0
	s_nop 0
	v_pk_fma_f32 v[148:149], v[230:231], v[134:135], v[124:125]
	v_pk_fma_f32 v[146:147], v[228:229], v[126:127], v[74:75]
	v_pk_fma_f32 v[152:153], v[234:235], v[136:137], v[122:123]
	v_pk_fma_f32 v[150:151], v[232:233], v[128:129], v[68:69]
	v_cvt_pk_bf16_f32 v146, v146, v147
	v_cvt_pk_bf16_f32 v147, v148, v149
	v_pk_fma_f32 v[156:157], v[238:239], v[138:139], v[120:121]
	v_cvt_pk_bf16_f32 v148, v150, v151
	v_cvt_pk_bf16_f32 v149, v152, v153
	v_pk_fma_f32 v[154:155], v[236:237], v[130:131], v[72:73]
	v_pk_fma_f32 v[160:161], v[242:243], v[140:141], v[118:119]
	v_pk_fma_f32 v[158:159], v[240:241], v[132:133], v[70:71]
	global_store_dwordx4 v[144:145], v[146:149], off offset:2048
	s_nop 1
	v_cvt_pk_bf16_f32 v146, v154, v155
	v_cvt_pk_bf16_f32 v147, v156, v157
	v_cvt_pk_bf16_f32 v148, v158, v159
	v_cvt_pk_bf16_f32 v149, v160, v161
	global_store_dwordx4 v[144:145], v[146:149], off offset:3072
	s_nop 0
	global_load_dwordx4 v[152:155], v[106:107], off
	global_load_dwordx4 v[156:159], v[106:107], off offset:16
	v_pk_fma_f32 v[146:147], v[246:247], v[134:135], v[124:125]
	v_pk_fma_f32 v[144:145], v[244:245], v[126:127], v[74:75]
	v_pk_fma_f32 v[150:151], v[250:251], v[136:137], v[122:123]
	v_pk_fma_f32 v[148:149], v[248:249], v[128:129], v[68:69]
	v_cvt_pk_bf16_f32 v144, v144, v145
	v_cvt_pk_bf16_f32 v145, v146, v147
	s_waitcnt vmcnt(1)
	v_pk_fma_f32 v[154:155], v[154:155], v[138:139], v[120:121]
	v_cvt_pk_bf16_f32 v146, v148, v149
	v_cvt_pk_bf16_f32 v147, v150, v151
	v_pk_fma_f32 v[152:153], v[152:153], v[130:131], v[72:73]
	s_waitcnt vmcnt(0)
	v_pk_fma_f32 v[158:159], v[158:159], v[140:141], v[118:119]
	v_pk_fma_f32 v[156:157], v[156:157], v[132:133], v[70:71]
	global_store_dwordx4 v[170:171], v[144:147], off offset:2048
	s_nop 1
	v_cvt_pk_bf16_f32 v144, v152, v153
	v_cvt_pk_bf16_f32 v145, v154, v155
	v_cvt_pk_bf16_f32 v146, v156, v157
	v_cvt_pk_bf16_f32 v147, v158, v159
	global_store_dwordx4 v[170:171], v[144:147], off offset:3072
	global_load_dwordx4 v[144:147], v[108:109], off
	s_nop 0
	global_load_dwordx4 v[148:151], v[108:109], off offset:16
	global_load_dwordx4 v[152:155], v[110:111], off
	global_load_dwordx4 v[156:159], v[110:111], off offset:16
	s_waitcnt vmcnt(3)
	v_pk_fma_f32 v[146:147], v[146:147], v[134:135], v[124:125]
	v_pk_fma_f32 v[144:145], v[144:145], v[126:127], v[74:75]
	s_waitcnt vmcnt(2)
	v_pk_fma_f32 v[150:151], v[150:151], v[136:137], v[122:123]
	v_pk_fma_f32 v[148:149], v[148:149], v[128:129], v[68:69]
	v_cvt_pk_bf16_f32 v144, v144, v145
	v_cvt_pk_bf16_f32 v145, v146, v147
	s_waitcnt vmcnt(1)
	v_pk_fma_f32 v[154:155], v[154:155], v[138:139], v[120:121]
	v_cvt_pk_bf16_f32 v146, v148, v149
	v_cvt_pk_bf16_f32 v147, v150, v151
	v_pk_fma_f32 v[152:153], v[152:153], v[130:131], v[72:73]
	s_waitcnt vmcnt(0)
	v_pk_fma_f32 v[158:159], v[158:159], v[140:141], v[118:119]
	v_pk_fma_f32 v[156:157], v[156:157], v[132:133], v[70:71]
	global_store_dwordx4 v[168:169], v[144:147], off offset:2048
	s_nop 1
	v_cvt_pk_bf16_f32 v144, v152, v153
	v_cvt_pk_bf16_f32 v145, v154, v155
	v_cvt_pk_bf16_f32 v146, v156, v157
	v_cvt_pk_bf16_f32 v147, v158, v159
	global_store_dwordx4 v[168:169], v[144:147], off offset:3072
	global_load_dwordx4 v[144:147], v[112:113], off
	s_nop 0
	global_load_dwordx4 v[148:151], v[112:113], off offset:16
	global_load_dwordx4 v[152:155], v[114:115], off
	global_load_dwordx4 v[156:159], v[114:115], off offset:16
	s_waitcnt vmcnt(3)
	v_pk_fma_f32 v[124:125], v[146:147], v[134:135], v[124:125]
	v_pk_fma_f32 v[74:75], v[144:145], v[126:127], v[74:75]
	s_waitcnt vmcnt(2)
	v_pk_fma_f32 v[122:123], v[150:151], v[136:137], v[122:123]
	v_pk_fma_f32 v[126:127], v[148:149], v[128:129], v[68:69]
	s_waitcnt vmcnt(0)
	v_pk_fma_f32 v[128:129], v[156:157], v[132:133], v[70:71]
	v_cvt_pk_bf16_f32 v68, v74, v75
	v_cvt_pk_bf16_f32 v69, v124, v125
	v_cvt_pk_bf16_f32 v70, v126, v127
	v_cvt_pk_bf16_f32 v71, v122, v123
	v_pk_fma_f32 v[120:121], v[154:155], v[138:139], v[120:121]
	v_pk_fma_f32 v[72:73], v[152:153], v[130:131], v[72:73]
	v_pk_fma_f32 v[118:119], v[158:159], v[140:141], v[118:119]
	global_store_dwordx4 v[164:165], v[68:71], off offset:2048
	s_nop 1
	v_cvt_pk_bf16_f32 v68, v72, v73
	v_cvt_pk_bf16_f32 v69, v120, v121
	v_cvt_pk_bf16_f32 v70, v128, v129
	v_cvt_pk_bf16_f32 v71, v118, v119
	global_store_dwordx4 v[164:165], v[68:71], off offset:3072
	s_nop 1
	v_cvt_pk_bf16_f32 v68, v48, v49
	v_cvt_pk_bf16_f32 v69, v46, v47
	v_cvt_pk_bf16_f32 v70, v44, v45
	v_cvt_pk_bf16_f32 v71, v42, v43
	global_store_dwordx4 v[166:167], v[68:71], off
	s_nop 1
	v_cvt_pk_bf16_f32 v68, v40, v41
	v_cvt_pk_bf16_f32 v69, v38, v39
	v_cvt_pk_bf16_f32 v70, v36, v37
	v_cvt_pk_bf16_f32 v71, v34, v35
	global_store_dwordx4 v[166:167], v[68:71], off offset:1024
	s_nop 0
	s_nop 0
	v_pk_fma_f32 v[70:71], v[230:231], v[90:91], v[46:47]
	v_pk_fma_f32 v[68:69], v[228:229], v[78:79], v[48:49]
	v_pk_fma_f32 v[74:75], v[234:235], v[92:93], v[42:43]
	v_pk_fma_f32 v[72:73], v[232:233], v[80:81], v[44:45]
	v_cvt_pk_bf16_f32 v68, v68, v69
	v_cvt_pk_bf16_f32 v69, v70, v71
	v_pk_fma_f32 v[120:121], v[238:239], v[94:95], v[38:39]
	v_cvt_pk_bf16_f32 v70, v72, v73
	v_cvt_pk_bf16_f32 v71, v74, v75
	v_pk_fma_f32 v[118:119], v[236:237], v[82:83], v[40:41]
	v_pk_fma_f32 v[124:125], v[242:243], v[96:97], v[34:35]
	v_pk_fma_f32 v[122:123], v[240:241], v[84:85], v[36:37]
	global_store_dwordx4 v[142:143], v[68:71], off
	s_nop 1
	v_cvt_pk_bf16_f32 v68, v118, v119
	v_cvt_pk_bf16_f32 v69, v120, v121
	v_cvt_pk_bf16_f32 v70, v122, v123
	v_cvt_pk_bf16_f32 v71, v124, v125
	global_store_dwordx4 v[142:143], v[68:71], off offset:1024
	s_nop 0
	global_load_dwordx4 v[118:121], v[106:107], off
	global_load_dwordx4 v[122:125], v[106:107], off offset:16
	v_pk_fma_f32 v[70:71], v[246:247], v[90:91], v[46:47]
	v_pk_fma_f32 v[68:69], v[244:245], v[78:79], v[48:49]
	v_pk_fma_f32 v[74:75], v[250:251], v[92:93], v[42:43]
	v_pk_fma_f32 v[72:73], v[248:249], v[80:81], v[44:45]
	v_cvt_pk_bf16_f32 v68, v68, v69
	v_cvt_pk_bf16_f32 v69, v70, v71
	s_waitcnt vmcnt(1)
	v_pk_fma_f32 v[120:121], v[120:121], v[94:95], v[38:39]
	v_cvt_pk_bf16_f32 v70, v72, v73
	v_cvt_pk_bf16_f32 v71, v74, v75
	v_pk_fma_f32 v[118:119], v[118:119], v[82:83], v[40:41]
	s_waitcnt vmcnt(0)
	v_pk_fma_f32 v[124:125], v[124:125], v[96:97], v[34:35]
	v_pk_fma_f32 v[122:123], v[122:123], v[84:85], v[36:37]
	global_store_dwordx4 v[88:89], v[68:71], off
	s_nop 1
	v_cvt_pk_bf16_f32 v68, v118, v119
	v_cvt_pk_bf16_f32 v69, v120, v121
	v_cvt_pk_bf16_f32 v70, v122, v123
	v_cvt_pk_bf16_f32 v71, v124, v125
	global_store_dwordx4 v[88:89], v[68:71], off offset:1024
	global_load_dwordx4 v[68:71], v[108:109], off
	s_nop 0
	global_load_dwordx4 v[72:75], v[108:109], off offset:16
	global_load_dwordx4 v[118:121], v[110:111], off
	global_load_dwordx4 v[122:125], v[110:111], off offset:16
	s_waitcnt vmcnt(3)
	v_pk_fma_f32 v[70:71], v[70:71], v[90:91], v[46:47]
	v_pk_fma_f32 v[68:69], v[68:69], v[78:79], v[48:49]
	s_waitcnt vmcnt(2)
	v_pk_fma_f32 v[74:75], v[74:75], v[92:93], v[42:43]
	v_pk_fma_f32 v[72:73], v[72:73], v[80:81], v[44:45]
	v_cvt_pk_bf16_f32 v68, v68, v69
	v_cvt_pk_bf16_f32 v69, v70, v71
	s_waitcnt vmcnt(1)
	v_pk_fma_f32 v[88:89], v[120:121], v[94:95], v[38:39]
	v_cvt_pk_bf16_f32 v70, v72, v73
	v_cvt_pk_bf16_f32 v71, v74, v75
	v_pk_fma_f32 v[118:119], v[118:119], v[82:83], v[40:41]
	s_waitcnt vmcnt(0)
	v_pk_fma_f32 v[120:121], v[124:125], v[96:97], v[34:35]
	v_pk_fma_f32 v[122:123], v[122:123], v[84:85], v[36:37]
	global_store_dwordx4 v[86:87], v[68:71], off
	s_nop 1
	v_cvt_pk_bf16_f32 v68, v118, v119
	v_cvt_pk_bf16_f32 v69, v88, v89
	v_cvt_pk_bf16_f32 v70, v122, v123
	v_cvt_pk_bf16_f32 v71, v120, v121
	global_store_dwordx4 v[86:87], v[68:71], off offset:1024
	global_load_dwordx4 v[68:71], v[112:113], off
	s_nop 0
	global_load_dwordx4 v[72:75], v[112:113], off offset:16
	global_load_dwordx4 v[86:89], v[114:115], off
	global_load_dwordx4 v[118:121], v[114:115], off offset:16
	s_waitcnt vmcnt(3)
	v_pk_fma_f32 v[70:71], v[70:71], v[90:91], v[46:47]
	v_pk_fma_f32 v[68:69], v[68:69], v[78:79], v[48:49]
	s_waitcnt vmcnt(2)
	v_pk_fma_f32 v[74:75], v[74:75], v[92:93], v[42:43]
	v_pk_fma_f32 v[72:73], v[72:73], v[80:81], v[44:45]
	v_cvt_pk_bf16_f32 v68, v68, v69
	v_cvt_pk_bf16_f32 v69, v70, v71
	s_waitcnt vmcnt(1)
	v_pk_fma_f32 v[78:79], v[88:89], v[94:95], v[38:39]
	v_cvt_pk_bf16_f32 v70, v72, v73
	v_cvt_pk_bf16_f32 v71, v74, v75
	v_pk_fma_f32 v[80:81], v[86:87], v[82:83], v[40:41]
	s_waitcnt vmcnt(0)
	v_pk_fma_f32 v[82:83], v[120:121], v[96:97], v[34:35]
	v_pk_fma_f32 v[84:85], v[118:119], v[84:85], v[36:37]
	global_store_dwordx4 v[76:77], v[68:71], off
	v_pk_fma_f32 v[48:49], v[66:67], v[6:7], v[48:49] neg_lo:[1,0,0] neg_hi:[1,0,0]
	v_pk_fma_f32 v[46:47], v[64:65], v[8:9], v[46:47] neg_lo:[1,0,0] neg_hi:[1,0,0]
	v_cvt_pk_bf16_f32 v68, v80, v81
	v_cvt_pk_bf16_f32 v69, v78, v79
	v_cvt_pk_bf16_f32 v70, v84, v85
	v_cvt_pk_bf16_f32 v71, v82, v83
	global_store_dwordx4 v[76:77], v[68:71], off offset:1024
	v_pk_fma_f32 v[44:45], v[62:63], v[2:3], v[44:45] neg_lo:[1,0,0] neg_hi:[1,0,0]
	v_pk_fma_f32 v[42:43], v[60:61], v[4:5], v[42:43] neg_lo:[1,0,0] neg_hi:[1,0,0]
	v_cvt_pk_bf16_f32 v68, v30, v31
	v_cvt_pk_bf16_f32 v69, v32, v33
	v_cvt_pk_bf16_f32 v70, v26, v27
	v_cvt_pk_bf16_f32 v71, v28, v29
	global_store_dwordx4 v[56:57], v[68:71], off
	v_pk_fma_f32 v[38:39], v[54:55], v[16:17], v[38:39] neg_lo:[1,0,0] neg_hi:[1,0,0]
	v_pk_fma_f32 v[54:55], v[52:53], v[10:11], v[36:37] neg_lo:[1,0,0] neg_hi:[1,0,0]
	v_cvt_pk_bf16_f32 v68, v22, v23
	v_cvt_pk_bf16_f32 v69, v24, v25
	v_cvt_pk_bf16_f32 v70, v18, v19
	v_cvt_pk_bf16_f32 v71, v20, v21
	global_store_dwordx4 v[56:57], v[68:71], off offset:1024
	s_nop 0
	v_pk_fma_f32 v[66:67], v[50:51], v[12:13], v[34:35] neg_lo:[1,0,0] neg_hi:[1,0,0]
	v_lshl_add_u64 v[56:57], v[100:101], 0, s[8:9]
	v_pk_fma_f32 v[40:41], v[58:59], v[14:15], v[40:41] neg_lo:[1,0,0] neg_hi:[1,0,0]
	v_pk_fma_f32 v[36:37], v[230:231], v[46:47], v[32:33]
	v_pk_fma_f32 v[34:35], v[228:229], v[48:49], v[30:31]
	v_pk_fma_f32 v[50:51], v[234:235], v[42:43], v[28:29]
	v_pk_fma_f32 v[52:53], v[232:233], v[44:45], v[26:27]
	v_cvt_pk_bf16_f32 v34, v34, v35
	v_cvt_pk_bf16_f32 v35, v36, v37
	v_pk_fma_f32 v[58:59], v[238:239], v[38:39], v[24:25]
	v_cvt_pk_bf16_f32 v36, v52, v53
	v_cvt_pk_bf16_f32 v37, v50, v51
	v_pk_fma_f32 v[60:61], v[236:237], v[40:41], v[22:23]
	v_pk_fma_f32 v[62:63], v[242:243], v[66:67], v[20:21]
	v_pk_fma_f32 v[64:65], v[240:241], v[54:55], v[18:19]
	global_store_dwordx4 v[56:57], v[34:37], off
	v_add_co_u32_e32 v68, vcc, s14, v56
	s_nop 0
	v_cvt_pk_bf16_f32 v34, v60, v61
	v_cvt_pk_bf16_f32 v35, v58, v59
	v_cvt_pk_bf16_f32 v36, v64, v65
	v_cvt_pk_bf16_f32 v37, v62, v63
	global_store_dwordx4 v[56:57], v[34:37], off offset:1024
	s_nop 0
	global_load_dwordx4 v[58:61], v[106:107], off
	global_load_dwordx4 v[62:65], v[106:107], off offset:16
	v_addc_co_u32_e32 v69, vcc, 0, v57, vcc
	v_pk_fma_f32 v[36:37], v[246:247], v[46:47], v[32:33]
	v_pk_fma_f32 v[34:35], v[244:245], v[48:49], v[30:31]
	v_pk_fma_f32 v[52:53], v[250:251], v[42:43], v[28:29]
	v_pk_fma_f32 v[50:51], v[248:249], v[44:45], v[26:27]
	v_cvt_pk_bf16_f32 v34, v34, v35
	v_cvt_pk_bf16_f32 v35, v36, v37
	s_waitcnt vmcnt(1)
	v_pk_fma_f32 v[60:61], v[60:61], v[38:39], v[24:25]
	v_cvt_pk_bf16_f32 v36, v50, v51
	v_cvt_pk_bf16_f32 v37, v52, v53
	v_pk_fma_f32 v[58:59], v[58:59], v[40:41], v[22:23]
	s_waitcnt vmcnt(0)
	v_pk_fma_f32 v[64:65], v[64:65], v[66:67], v[20:21]
	v_pk_fma_f32 v[62:63], v[62:63], v[54:55], v[18:19]
	global_store_dwordx4 v[68:69], v[34:37], off
	s_nop 1
	v_cvt_pk_bf16_f32 v34, v58, v59
	v_cvt_pk_bf16_f32 v35, v60, v61
	v_cvt_pk_bf16_f32 v36, v62, v63
	v_cvt_pk_bf16_f32 v37, v64, v65
	global_store_dwordx4 v[68:69], v[34:37], off offset:1024
	global_load_dwordx4 v[34:37], v[108:109], off
	s_nop 0
	global_load_dwordx4 v[50:53], v[108:109], off offset:16
	global_load_dwordx4 v[58:61], v[110:111], off
	global_load_dwordx4 v[62:65], v[110:111], off offset:16
	v_add_co_u32_e32 v68, vcc, s15, v56
	s_waitcnt vmcnt(3)
	v_pk_fma_f32 v[36:37], v[36:37], v[46:47], v[32:33]
	v_pk_fma_f32 v[34:35], v[34:35], v[48:49], v[30:31]
	v_addc_co_u32_e32 v69, vcc, 0, v57, vcc
	s_waitcnt vmcnt(2)
	v_pk_fma_f32 v[52:53], v[52:53], v[42:43], v[28:29]
	v_pk_fma_f32 v[50:51], v[50:51], v[44:45], v[26:27]
	v_cvt_pk_bf16_f32 v34, v34, v35
	v_cvt_pk_bf16_f32 v35, v36, v37
	s_waitcnt vmcnt(1)
	v_pk_fma_f32 v[60:61], v[60:61], v[38:39], v[24:25]
	v_cvt_pk_bf16_f32 v36, v50, v51
	v_cvt_pk_bf16_f32 v37, v52, v53
	v_pk_fma_f32 v[58:59], v[58:59], v[40:41], v[22:23]
	s_waitcnt vmcnt(0)
	v_pk_fma_f32 v[64:65], v[64:65], v[66:67], v[20:21]
	v_pk_fma_f32 v[62:63], v[62:63], v[54:55], v[18:19]
	global_store_dwordx4 v[68:69], v[34:37], off
	v_add_co_u32_e32 v56, vcc, s16, v56
	s_nop 0
	v_cvt_pk_bf16_f32 v34, v58, v59
	v_cvt_pk_bf16_f32 v35, v60, v61
	v_cvt_pk_bf16_f32 v36, v62, v63
	v_cvt_pk_bf16_f32 v37, v64, v65
	global_store_dwordx4 v[68:69], v[34:37], off offset:1024
	global_load_dwordx4 v[34:37], v[112:113], off
	s_nop 0
	global_load_dwordx4 v[50:53], v[112:113], off offset:16
	global_load_dwordx4 v[58:61], v[114:115], off
	global_load_dwordx4 v[62:65], v[114:115], off offset:16
	v_addc_co_u32_e32 v57, vcc, 0, v57, vcc
	s_waitcnt vmcnt(3)
	v_pk_fma_f32 v[32:33], v[36:37], v[46:47], v[32:33]
	v_pk_fma_f32 v[30:31], v[34:35], v[48:49], v[30:31]
	s_waitcnt vmcnt(2)
	v_pk_fma_f32 v[28:29], v[52:53], v[42:43], v[28:29]
	v_pk_fma_f32 v[26:27], v[50:51], v[44:45], v[26:27]
	s_waitcnt vmcnt(0)
	v_pk_fma_f32 v[34:35], v[64:65], v[66:67], v[20:21]
	v_pk_fma_f32 v[36:37], v[62:63], v[54:55], v[18:19]
	v_cvt_pk_bf16_f32 v18, v30, v31
	v_cvt_pk_bf16_f32 v19, v32, v33
	v_cvt_pk_bf16_f32 v20, v26, v27
	v_cvt_pk_bf16_f32 v21, v28, v29
	v_pk_fma_f32 v[24:25], v[60:61], v[38:39], v[24:25]
	v_pk_fma_f32 v[22:23], v[58:59], v[40:41], v[22:23]
	global_store_dwordx4 v[56:57], v[18:21], off
	s_nop 1
	v_cvt_pk_bf16_f32 v18, v22, v23
	v_cvt_pk_bf16_f32 v19, v24, v25
	v_cvt_pk_bf16_f32 v20, v36, v37
	v_cvt_pk_bf16_f32 v21, v34, v35
	global_store_dwordx4 v[56:57], v[18:21], off offset:1024
	s_cbranch_scc0 .LBB0_57

.LBB0_902:
	s_or_b64 exec, exec, s[0:1]
	s_lshl_b32 s48, s84, 8
	s_waitcnt lgkmcnt(0)
	v_mov_b32_e32 v0, v226
	s_and_b32 s73, s48, 0xffffe000
	s_barrier
	s_or_b32 s1, s73, s85
	v_readfirstlane_b32 s0, v0
	s_ashr_i32 s0, s0, 6
	s_or_b32 s85, s1, 0x1c00
	s_add_i32 s0, s85, s0
	s_cmp_lt_i32 s0, s73
	s_cbranch_scc1 .LBB0_905
	v_and_b32_e32 v1, 63, v0
	v_readlane_b32 s4, v254, 14
	v_lshlrev_b32_e32 v92, 5, v1
	v_mov_b32_e32 v93, 0
	v_readlane_b32 s5, v254, 15
	v_readlane_b32 s6, v254, 16
	v_readlane_b32 s7, v254, 17
	v_readlane_b32 s8, v254, 18
	v_readlane_b32 s9, v254, 19
	v_readlane_b32 s10, v254, 20
	v_readlane_b32 s11, v254, 21
	v_readlane_b32 s12, v254, 22
	v_readlane_b32 s13, v254, 23
	v_readlane_b32 s14, v254, 24
	v_readlane_b32 s15, v254, 25
	v_readlane_b32 s16, v254, 26
	v_readlane_b32 s17, v254, 27
	v_readlane_b32 s18, v254, 28
	v_readlane_b32 s19, v254, 29
	s_ashr_i32 s1, s0, 31
	v_lshrrev_b32_e32 v0, 1, v0
	v_lshl_add_u64 v[94:95], s[18:19], 0, v[92:93]
	v_readlane_b32 s4, v254, 30
	v_readlane_b32 s8, v254, 34
	v_readlane_b32 s9, v254, 35
	v_readlane_b32 s10, v254, 36
	v_readlane_b32 s11, v254, 37
	v_readlane_b32 s12, v254, 38
	v_readlane_b32 s13, v254, 39
	v_readlane_b32 s14, v254, 40
	v_readlane_b32 s15, v254, 41
	v_readlane_b32 s5, v254, 31
	v_readlane_b32 s8, v254, 0
	v_readlane_b32 s6, v254, 32
	v_lshl_add_u64 v[96:97], s[4:5], 0, v[92:93]
	s_lshl_b64 s[4:5], s[0:1], 11
	v_readlane_b32 s9, v254, 1
	v_readlane_b32 s10, v254, 2
	v_readlane_b32 s11, v254, 3
	v_readlane_b32 s12, v254, 4
	v_readlane_b32 s13, v254, 5
	v_readlane_b32 s7, v254, 33
	s_add_u32 s6, s92, s4
	v_readlane_b32 s14, v254, 6
	v_readlane_b32 s15, v254, 7
	s_mov_b64 s[8:9], s[12:13]
	s_addc_u32 s7, s93, s5
	s_mov_b64 s[10:11], s[14:15]
	s_add_u32 s8, s10, s4
	s_addc_u32 s9, s11, s5
	s_lshl_b64 s[4:5], s[0:1], 6
	s_add_u32 s4, s92, s4
	v_lshlrev_b32_e32 v92, 4, v1
	v_and_b32_e32 v0, 28, v0
	v_mov_b32_e32 v1, v93
	s_addc_u32 s5, s93, s5
	v_lshl_add_u64 v[0:1], s[4:5], 0, v[0:1]
	s_mov_b64 s[4:5], 0x1e00000
	s_mov_b32 s10, 0xffff0000
	v_lshl_add_u64 v[98:99], v[0:1], 0, s[4:5]
	v_mov_b32_e32 v103, 0x3a27c5ac
	s_mov_b32 s1, 0x1fc00000
	s_mov_b32 s4, 0x1fc80000
	s_mov_b32 s5, 0x1fd00000
	s_mov_b32 s12, 0x1fd80000
	s_mov_b32 s11, -1
	v_readlane_b32 s16, v254, 42
	v_readlane_b32 s17, v254, 43
	v_readlane_b32 s18, v254, 44
	v_readlane_b32 s19, v254, 45
	global_load_dwordx4 v[150:153], v[94:95], off offset:16
	global_load_dwordx4 v[154:157], v[94:95], off
	global_load_dwordx4 v[158:161], v[96:97], off offset:16
	global_load_dwordx4 v[162:165], v[96:97], off
	global_load_dwordx4 v[170:173], v[94:95], off offset:2064
	global_load_dwordx4 v[174:177], v[94:95], off offset:2048
	global_load_dwordx4 v[178:181], v[96:97], off offset:2064
	global_load_dwordx4 v[182:185], v[96:97], off offset:2048
	s_waitcnt vmcnt(0)
.LBB0_904:
	v_lshl_add_u64 v[100:101], s[6:7], 0, v[92:93]
	v_add_co_u32_e32 v0, vcc, 0x27d00000, v100
	s_addk_i32 s0, 0xfc00
	s_nop 0
	v_addc_co_u32_e32 v1, vcc, 0, v101, vcc
	global_load_dwordx4 v[118:121], v[0:1], off nt
	global_load_dwordx4 v[80:83], v[0:1], off offset:1024 nt
	v_lshl_add_u64 v[0:1], s[8:9], 0, v[92:93]
	v_add_co_u32_e32 v2, vcc, 0x8000000, v0
	s_add_u32 s6, s6, 0xffe00000
	s_nop 0
	v_addc_co_u32_e32 v3, vcc, 0, v1, vcc
	global_load_dwordx4 v[88:91], v[2:3], off nt
	global_load_dwordx4 v[76:79], v[2:3], off offset:1024 nt
	v_add_co_u32_e32 v2, vcc, 0x7900000, v100
	s_addc_u32 s7, s7, -1
	s_nop 0
	v_addc_co_u32_e32 v3, vcc, 0, v101, vcc
	global_load_dwordx4 v[84:87], v[2:3], off nt
	global_load_dwordx4 v[72:75], v[2:3], off offset:1024 nt
	global_load_dword v116, v[98:99], off
	global_load_dword v114, v[98:99], off offset:32
	v_add_co_u32_e32 v2, vcc, 0x27d80000, v100
	s_add_u32 s8, s8, 0xffe00000
	s_nop 0
	v_addc_co_u32_e32 v3, vcc, 0, v101, vcc
	global_load_dwordx4 v[68:71], v[2:3], off nt
	global_load_dwordx4 v[56:59], v[2:3], off offset:1024 nt
	v_add_co_u32_e32 v2, vcc, 0x8080000, v0
	s_addc_u32 s9, s9, -1
	s_nop 0
	v_addc_co_u32_e32 v3, vcc, 0, v1, vcc
	global_load_dwordx4 v[64:67], v[2:3], off nt
	global_load_dwordx4 v[52:55], v[2:3], off offset:1024 nt
	v_add_co_u32_e32 v2, vcc, 0x7980000, v100
	s_cmp_lt_i32 s0, s73
	s_nop 0
	v_addc_co_u32_e32 v3, vcc, 0, v101, vcc
	global_load_dwordx4 v[60:63], v[2:3], off nt
	global_load_dwordx4 v[48:51], v[2:3], off offset:1024 nt
	v_add_co_u32_e32 v2, vcc, 0x4000, v98
	s_waitcnt vmcnt(13)
	v_and_b32_e32 v127, 0xffff0000, v120
	v_addc_co_u32_e32 v3, vcc, 0, v99, vcc
	global_load_dword v112, v[2:3], off
	global_load_dword v110, v[2:3], off offset:32
	v_add_co_u32_e32 v2, vcc, 0x27e00000, v100
	v_and_b32_e32 v126, 0xffff0000, v118
	s_nop 0
	v_addc_co_u32_e32 v3, vcc, 0, v101, vcc
	global_load_dwordx4 v[44:47], v[2:3], off nt
	global_load_dwordx4 v[32:35], v[2:3], off offset:1024 nt
	v_add_co_u32_e32 v2, vcc, 0x8100000, v0
	v_lshlrev_b32_e32 v129, 16, v121
	s_nop 0
	v_addc_co_u32_e32 v3, vcc, 0, v1, vcc
	global_load_dwordx4 v[40:43], v[2:3], off nt
	global_load_dwordx4 v[28:31], v[2:3], off offset:1024 nt
	v_add_co_u32_e32 v2, vcc, 0x7a00000, v100
	v_lshlrev_b32_e32 v128, 16, v119
	s_nop 0
	v_addc_co_u32_e32 v3, vcc, 0, v101, vcc
	global_load_dwordx4 v[36:39], v[2:3], off nt
	global_load_dwordx4 v[24:27], v[2:3], off offset:1024 nt
	v_add_co_u32_e32 v2, vcc, 0x8000, v98
	v_and_b32_e32 v131, 0xffff0000, v121
	s_nop 0
	v_addc_co_u32_e32 v3, vcc, 0, v99, vcc
	global_load_dword v108, v[2:3], off
	global_load_dword v106, v[2:3], off offset:32
	v_add_co_u32_e32 v2, vcc, 0x27e80000, v100
	v_and_b32_e32 v130, 0xffff0000, v119
	s_nop 0
	v_addc_co_u32_e32 v3, vcc, 0, v101, vcc
	v_add_co_u32_e32 v0, vcc, 0x8180000, v0
	global_load_dwordx4 v[20:23], v[2:3], off nt
	global_load_dwordx4 v[8:11], v[2:3], off offset:1024 nt
	v_addc_co_u32_e32 v1, vcc, 0, v1, vcc
	global_load_dwordx4 v[16:19], v[0:1], off nt
	global_load_dwordx4 v[4:7], v[0:1], off offset:1024 nt
	v_add_co_u32_e32 v0, vcc, 0x7a80000, v100
	s_waitcnt vmcnt(25)
	v_lshlrev_b32_e32 v144, 16, v88
	v_addc_co_u32_e32 v1, vcc, 0, v101, vcc
	v_add_co_u32_e32 v122, vcc, 0xc000, v98
	global_load_dwordx4 v[12:15], v[0:1], off nt
	s_nop 0
	global_load_dwordx4 v[0:3], v[0:1], off offset:1024 nt
	v_addc_co_u32_e32 v123, vcc, 0, v99, vcc
	global_load_dword v104, v[122:123], off
	global_load_dword v102, v[122:123], off offset:32
	v_lshlrev_b32_e32 v123, 16, v120
	v_lshlrev_b32_e32 v122, 16, v118
	v_pk_add_f32 v[118:119], v[122:123], v[126:127]
	v_pk_add_f32 v[120:121], v[128:129], v[130:131]
	v_and_b32_e32 v145, 0xffff0000, v88
	v_pk_add_f32 v[118:119], v[118:119], v[120:121]
	v_lshlrev_b32_e32 v88, 16, v89
	v_add_f32_e32 v105, v118, v119
	v_and_b32_e32 v89, 0xffff0000, v89
	s_waitcnt vmcnt(27)
	v_and_b32_e32 v107, 0xffff0000, v84
	v_add_f32_dpp v105, v105, v105 quad_perm:[1,0,3,2] row_mask:0xf bank_mask:0xf bound_ctrl:1
	v_lshlrev_b32_e32 v109, 16, v85
	v_and_b32_e32 v111, 0xffff0000, v85
	v_add_f32_dpp v105, v105, v105 quad_perm:[2,3,0,1] row_mask:0xf bank_mask:0xf bound_ctrl:1
	v_mul_f32_e32 v85, 0xbfb8aa3b, v111
	v_exp_f32_e32 v85, v85
	v_add_f32_dpp v105, v105, v105 row_half_mirror row_mask:0xf bank_mask:0xf bound_ctrl:1
	v_fmac_f32_e32 v126, 0xbc800000, v105
	v_fmac_f32_e32 v127, 0xbc800000, v105
	v_fmac_f32_e32 v130, 0xbc800000, v105
	v_fmac_f32_e32 v122, 0xbc800000, v105
	v_fmac_f32_e32 v131, 0xbc800000, v105
	v_fmac_f32_e32 v123, 0xbc800000, v105
	v_pk_mul_f32 v[120:121], v[126:127], v[126:127]
	v_fmac_f32_e32 v128, 0xbc800000, v105
	v_fmac_f32_e32 v129, 0xbc800000, v105
	v_mov_b32_e32 v118, v123
	v_mov_b32_e32 v119, v127
	v_mov_b32_e32 v124, v122
	v_pk_fma_f32 v[122:123], v[122:123], v[122:123], v[120:121]
	v_mov_b32_e32 v121, v131
	v_mov_b32_e32 v127, v130
	v_pk_mul_f32 v[130:131], v[130:131], v[130:131]
	v_mov_b32_e32 v125, v126
	v_mov_b32_e32 v120, v129
	v_mov_b32_e32 v126, v128
	v_pk_fma_f32 v[128:129], v[128:129], v[128:129], v[130:131]
	v_lshl_add_u64 v[98:99], v[98:99], 0, s[10:11]
	v_pk_add_f32 v[122:123], v[122:123], v[128:129]
	s_nop 0
	v_add_f32_e32 v105, v122, v123
	s_nop 1
	v_add_f32_dpp v105, v105, v105 quad_perm:[1,0,3,2] row_mask:0xf bank_mask:0xf bound_ctrl:1
	s_nop 1
	v_add_f32_dpp v105, v105, v105 quad_perm:[2,3,0,1] row_mask:0xf bank_mask:0xf bound_ctrl:1
	s_nop 1
	v_add_f32_dpp v105, v105, v105 row_half_mirror row_mask:0xf bank_mask:0xf bound_ctrl:1
	v_fmamk_f32 v105, v105, 0x3c800000, v103
	v_rsq_f32_e32 v122, v105
	v_lshlrev_b32_e32 v105, 16, v84
	v_mul_f32_e32 v84, 0xbfb8aa3b, v105
	v_pk_mul_f32 v[126:127], v[122:123], v[126:127] op_sel_hi:[0,1]
	v_pk_mul_f32 v[124:125], v[122:123], v[124:125] op_sel_hi:[0,1]
	v_pk_fma_f32 v[126:127], v[126:127], v[156:157], v[164:165]
	s_nop 0
	s_waitcnt vmcnt(25)
	v_pk_fma_f32 v[88:89], v[116:117], v[88:89], v[126:127] op_sel_hi:[0,1,1]
	v_exp_f32_e32 v126, v84
	v_mul_f32_e32 v84, 0xbfb8aa3b, v107
	v_exp_f32_e32 v127, v84
	v_mul_f32_e32 v84, 0xbfb8aa3b, v109
	v_exp_f32_e32 v84, v84
	v_pk_fma_f32 v[124:125], v[124:125], v[154:155], v[162:163]
	v_pk_add_f32 v[126:127], v[126:127], 1.0 op_sel_hi:[1,0]
	v_pk_fma_f32 v[124:125], v[116:117], v[144:145], v[124:125] op_sel_hi:[0,1,1]
	v_pk_add_f32 v[84:85], v[84:85], 1.0 op_sel_hi:[1,0]
	s_nop 0
	v_rcp_f32_e32 v113, v85
	s_nop 0
	v_mul_f32_e32 v85, v111, v113
	v_rcp_f32_e32 v111, v84
	s_nop 0
	v_mul_f32_e32 v84, v109, v111
	v_pk_mul_f32 v[118:119], v[122:123], v[118:119] op_sel_hi:[0,1]
	v_pk_mul_f32 v[120:121], v[122:123], v[120:121] op_sel_hi:[0,1]
	v_pk_mul_f32 v[84:85], v[88:89], v[84:85]
	v_rcp_f32_e32 v109, v127
	s_nop 0
	v_mul_f32_e32 v127, v107, v109
	v_pk_fma_f32 v[120:121], v[120:121], v[152:153], v[160:161]
	v_pk_fma_f32 v[118:119], v[118:119], v[150:151], v[158:159]
	v_lshlrev_b32_e32 v123, 16, v83
	v_rcp_f32_e32 v107, v126
	s_nop 0
	v_mul_f32_e32 v126, v105, v107
	v_lshlrev_b32_e32 v105, 16, v86
	v_pk_mul_f32 v[88:89], v[124:125], v[126:127]
	v_lshlrev_b32_e32 v124, 16, v90
	v_and_b32_e32 v125, 0xffff0000, v90
	v_lshlrev_b32_e32 v90, 16, v91
	v_and_b32_e32 v91, 0xffff0000, v91
	v_and_b32_e32 v107, 0xffff0000, v86
	v_mul_f32_e32 v86, 0xbfb8aa3b, v105
	v_pk_fma_f32 v[118:119], v[116:117], v[124:125], v[118:119] op_sel_hi:[0,1,1]
	v_pk_fma_f32 v[90:91], v[116:117], v[90:91], v[120:121] op_sel_hi:[0,1,1]
	v_exp_f32_e32 v116, v86
	v_mul_f32_e32 v86, 0xbfb8aa3b, v107
	v_lshlrev_b32_e32 v109, 16, v87
	v_and_b32_e32 v111, 0xffff0000, v87
	v_exp_f32_e32 v117, v86
	v_mul_f32_e32 v86, 0xbfb8aa3b, v109
	v_mul_f32_e32 v87, 0xbfb8aa3b, v111
	v_exp_f32_e32 v86, v86
	v_exp_f32_e32 v87, v87
	v_pk_add_f32 v[116:117], v[116:117], 1.0 op_sel_hi:[1,0]
	v_and_b32_e32 v125, 0xffff0000, v83
	v_and_b32_e32 v124, 0xffff0000, v81
	v_pk_add_f32 v[86:87], v[86:87], 1.0 op_sel_hi:[1,0]
	v_lshlrev_b32_e32 v138, 16, v76
	v_and_b32_e32 v139, 0xffff0000, v76
	v_lshlrev_b32_e32 v76, 16, v77
	v_and_b32_e32 v77, 0xffff0000, v77
	v_rcp_f32_e32 v113, v87
	s_nop 0
	v_mul_f32_e32 v87, v111, v113
	v_lshlrev_b32_e32 v122, 16, v81
	v_rcp_f32_e32 v111, v86
	s_nop 0
	v_mul_f32_e32 v86, v109, v111
	v_pk_mul_f32 v[86:87], v[90:91], v[86:87]
	v_and_b32_e32 v121, 0xffff0000, v82
	v_rcp_f32_e32 v109, v117
	s_nop 0
	v_mul_f32_e32 v117, v107, v109
	v_and_b32_e32 v120, 0xffff0000, v80
	v_rcp_f32_e32 v107, v116
	s_nop 0
	v_mul_f32_e32 v116, v105, v107
	v_pk_mul_f32 v[90:91], v[118:119], v[116:117]
	v_lshlrev_b32_e32 v117, 16, v82
	v_lshlrev_b32_e32 v116, 16, v80
	v_pk_add_f32 v[80:81], v[116:117], v[120:121]
	v_pk_add_f32 v[82:83], v[122:123], v[124:125]
	v_and_b32_e32 v107, 0xffff0000, v72
	v_pk_add_f32 v[80:81], v[80:81], v[82:83]
	v_lshlrev_b32_e32 v109, 16, v73
	v_add_f32_e32 v80, v80, v81
	v_and_b32_e32 v111, 0xffff0000, v73
	v_mul_f32_e32 v73, 0xbfb8aa3b, v111
	v_add_f32_dpp v80, v80, v80 quad_perm:[1,0,3,2] row_mask:0xf bank_mask:0xf bound_ctrl:1
	v_exp_f32_e32 v73, v73
	s_nop 0
	v_add_f32_dpp v80, v80, v80 quad_perm:[2,3,0,1] row_mask:0xf bank_mask:0xf bound_ctrl:1
	s_nop 1
	v_add_f32_dpp v80, v80, v80 row_half_mirror row_mask:0xf bank_mask:0xf bound_ctrl:1
	v_fmac_f32_e32 v120, 0xbc800000, v80
	v_fmac_f32_e32 v121, 0xbc800000, v80
	v_fmac_f32_e32 v124, 0xbc800000, v80
	v_fmac_f32_e32 v116, 0xbc800000, v80
	v_fmac_f32_e32 v125, 0xbc800000, v80
	v_fmac_f32_e32 v117, 0xbc800000, v80
	v_pk_mul_f32 v[82:83], v[120:121], v[120:121]
	v_fmac_f32_e32 v122, 0xbc800000, v80
	v_fmac_f32_e32 v123, 0xbc800000, v80
	v_mov_b32_e32 v80, v117
	v_mov_b32_e32 v81, v121
	v_mov_b32_e32 v118, v116
	v_pk_fma_f32 v[116:117], v[116:117], v[116:117], v[82:83]
	v_mov_b32_e32 v83, v125
	v_mov_b32_e32 v121, v124
	v_pk_mul_f32 v[124:125], v[124:125], v[124:125]
	v_mov_b32_e32 v119, v120
	v_mov_b32_e32 v82, v123
	v_mov_b32_e32 v120, v122
	v_pk_fma_f32 v[122:123], v[122:123], v[122:123], v[124:125]
	s_nop 0
	v_pk_add_f32 v[116:117], v[116:117], v[122:123]
	s_nop 0
	v_add_f32_e32 v105, v116, v117
	s_nop 1
	v_add_f32_dpp v105, v105, v105 quad_perm:[1,0,3,2] row_mask:0xf bank_mask:0xf bound_ctrl:1
	s_nop 1
	v_add_f32_dpp v105, v105, v105 quad_perm:[2,3,0,1] row_mask:0xf bank_mask:0xf bound_ctrl:1
	s_nop 1
	v_add_f32_dpp v105, v105, v105 row_half_mirror row_mask:0xf bank_mask:0xf bound_ctrl:1
	v_fmamk_f32 v105, v105, 0x3c800000, v103
	v_rsq_f32_e32 v116, v105
	v_lshlrev_b32_e32 v105, 16, v72
	v_mul_f32_e32 v72, 0xbfb8aa3b, v105
	v_pk_mul_f32 v[120:121], v[116:117], v[120:121] op_sel_hi:[0,1]
	v_pk_mul_f32 v[118:119], v[116:117], v[118:119] op_sel_hi:[0,1]
	v_pk_fma_f32 v[120:121], v[120:121], v[176:177], v[184:185]
	s_nop 0
	s_waitcnt vmcnt(24)
	v_pk_fma_f32 v[76:77], v[114:115], v[76:77], v[120:121] op_sel_hi:[0,1,1]
	v_exp_f32_e32 v120, v72
	v_mul_f32_e32 v72, 0xbfb8aa3b, v107
	v_exp_f32_e32 v121, v72
	v_mul_f32_e32 v72, 0xbfb8aa3b, v109
	v_exp_f32_e32 v72, v72
	v_pk_fma_f32 v[118:119], v[118:119], v[174:175], v[182:183]
	v_pk_add_f32 v[120:121], v[120:121], 1.0 op_sel_hi:[1,0]
	v_pk_fma_f32 v[118:119], v[114:115], v[138:139], v[118:119] op_sel_hi:[0,1,1]
	v_pk_add_f32 v[72:73], v[72:73], 1.0 op_sel_hi:[1,0]
	s_nop 0
	v_rcp_f32_e32 v113, v73
	s_nop 0
	v_mul_f32_e32 v73, v111, v113
	v_rcp_f32_e32 v111, v72
	s_nop 0
	v_mul_f32_e32 v72, v109, v111
	v_pk_mul_f32 v[76:77], v[76:77], v[72:73]
	v_lshlrev_b32_e32 v72, 16, v78
	v_and_b32_e32 v73, 0xffff0000, v78
	v_rcp_f32_e32 v109, v121
	s_nop 0
	v_mul_f32_e32 v121, v107, v109
	v_pk_mul_f32 v[82:83], v[116:117], v[82:83] op_sel_hi:[0,1]
	v_lshlrev_b32_e32 v78, 16, v79
	v_and_b32_e32 v79, 0xffff0000, v79
	v_pk_fma_f32 v[82:83], v[82:83], v[172:173], v[180:181]
	v_pk_mul_f32 v[80:81], v[116:117], v[80:81] op_sel_hi:[0,1]
	v_pk_fma_f32 v[78:79], v[114:115], v[78:79], v[82:83] op_sel_hi:[0,1,1]
	v_lshlrev_b32_e32 v82, 16, v74
	v_pk_fma_f32 v[80:81], v[80:81], v[170:171], v[178:179]
	v_and_b32_e32 v83, 0xffff0000, v74
	v_mul_f32_e32 v74, 0xbfb8aa3b, v82
	v_rcp_f32_e32 v107, v120
	s_nop 0
	v_mul_f32_e32 v120, v105, v107
	v_pk_fma_f32 v[72:73], v[114:115], v[72:73], v[80:81] op_sel_hi:[0,1,1]
	v_exp_f32_e32 v80, v74
	v_mul_f32_e32 v74, 0xbfb8aa3b, v83
	v_lshlrev_b32_e32 v105, 16, v75
	v_and_b32_e32 v107, 0xffff0000, v75
	v_exp_f32_e32 v81, v74
	v_mul_f32_e32 v74, 0xbfb8aa3b, v105
	v_mul_f32_e32 v75, 0xbfb8aa3b, v107
	v_exp_f32_e32 v74, v74
	v_exp_f32_e32 v75, v75
	v_pk_add_f32 v[80:81], v[80:81], 1.0 op_sel_hi:[1,0]
	v_pk_mul_f32 v[118:119], v[118:119], v[120:121]
	s_waitcnt vmcnt(21)
	v_lshlrev_b32_e32 v116, 16, v64
	v_pk_add_f32 v[74:75], v[74:75], 1.0 op_sel_hi:[1,0]
	v_and_b32_e32 v117, 0xffff0000, v64
	v_lshlrev_b32_e32 v64, 16, v65
	v_and_b32_e32 v65, 0xffff0000, v65
	v_rcp_f32_e32 v109, v75
	s_nop 0
	v_mul_f32_e32 v75, v107, v109
	v_rcp_f32_e32 v107, v74
	s_nop 0
	v_mul_f32_e32 v74, v105, v107
	v_pk_mul_f32 v[78:79], v[78:79], v[74:75]
	v_rcp_f32_e32 v105, v81
	s_nop 0
	v_mul_f32_e32 v81, v83, v105
	v_rcp_f32_e32 v83, v80
	s_nop 0
	v_mul_f32_e32 v80, v82, v83
	v_add_co_u32_e32 v82, vcc, s1, v100
	v_pk_mul_f32 v[80:81], v[72:73], v[80:81]
	v_cvt_pk_bf16_f32 v72, v88, v89
	v_cvt_pk_bf16_f32 v73, v84, v85
	v_cvt_pk_bf16_f32 v74, v90, v91
	v_cvt_pk_bf16_f32 v75, v86, v87
	s_nop 0
	v_addc_co_u32_e32 v83, vcc, 0, v101, vcc
	global_store_dwordx4 v[82:83], v[72:75], off
	s_nop 1
	v_cvt_pk_bf16_f32 v72, v118, v119
	v_cvt_pk_bf16_f32 v73, v76, v77
	v_cvt_pk_bf16_f32 v74, v80, v81
	v_cvt_pk_bf16_f32 v75, v78, v79
	global_store_dwordx4 v[82:83], v[72:75], off offset:1024
	v_lshlrev_b32_e32 v77, 16, v71
	v_lshlrev_b32_e32 v76, 16, v69
	v_lshlrev_b32_e32 v73, 16, v70
	v_lshlrev_b32_e32 v72, 16, v68
	v_and_b32_e32 v75, 0xffff0000, v70
	v_and_b32_e32 v74, 0xffff0000, v68
	v_and_b32_e32 v71, 0xffff0000, v71
	v_and_b32_e32 v70, 0xffff0000, v69
	v_pk_add_f32 v[68:69], v[72:73], v[74:75]
	v_pk_add_f32 v[78:79], v[76:77], v[70:71]
	s_nop 0
	v_pk_add_f32 v[68:69], v[68:69], v[78:79]
	s_nop 0
	v_add_f32_e32 v68, v68, v69
	s_nop 1
	v_add_f32_dpp v68, v68, v68 quad_perm:[1,0,3,2] row_mask:0xf bank_mask:0xf bound_ctrl:1
	s_nop 1
	v_add_f32_dpp v68, v68, v68 quad_perm:[2,3,0,1] row_mask:0xf bank_mask:0xf bound_ctrl:1
	s_nop 1
	v_add_f32_dpp v68, v68, v68 row_half_mirror row_mask:0xf bank_mask:0xf bound_ctrl:1
	v_fmac_f32_e32 v70, 0xbc800000, v68
	v_fmac_f32_e32 v74, 0xbc800000, v68
	v_fmac_f32_e32 v71, 0xbc800000, v68
	v_fmac_f32_e32 v75, 0xbc800000, v68
	v_fmac_f32_e32 v76, 0xbc800000, v68
	v_fmac_f32_e32 v72, 0xbc800000, v68
	v_fmac_f32_e32 v77, 0xbc800000, v68
	v_fmac_f32_e32 v73, 0xbc800000, v68
	v_pk_mul_f32 v[68:69], v[74:75], v[74:75]
	v_mov_b32_e32 v89, v71
	v_mov_b32_e32 v91, v70
	v_pk_mul_f32 v[70:71], v[70:71], v[70:71]
	v_pk_fma_f32 v[68:69], v[72:73], v[72:73], v[68:69]
	v_pk_fma_f32 v[70:71], v[76:77], v[76:77], v[70:71]
	v_mov_b32_e32 v84, v73
	v_pk_add_f32 v[68:69], v[68:69], v[70:71]
	v_mov_b32_e32 v85, v75
	v_add_f32_e32 v68, v68, v69
	v_mov_b32_e32 v86, v72
	v_mov_b32_e32 v87, v74
	v_add_f32_dpp v68, v68, v68 quad_perm:[1,0,3,2] row_mask:0xf bank_mask:0xf bound_ctrl:1
	v_mov_b32_e32 v88, v77
	v_mov_b32_e32 v90, v76
	v_add_f32_dpp v68, v68, v68 quad_perm:[2,3,0,1] row_mask:0xf bank_mask:0xf bound_ctrl:1
	s_nop 1
	v_add_f32_dpp v68, v68, v68 row_half_mirror row_mask:0xf bank_mask:0xf bound_ctrl:1
	v_fmamk_f32 v68, v68, 0x3c800000, v103
	v_rsq_f32_e32 v114, v68
	s_nop 0
	v_pk_mul_f32 v[86:87], v[114:115], v[86:87] op_sel_hi:[0,1]
	v_pk_mul_f32 v[90:91], v[114:115], v[90:91] op_sel_hi:[0,1]
	v_pk_fma_f32 v[72:73], v[86:87], v[154:155], v[162:163]
	s_waitcnt vmcnt(21)
	v_lshlrev_b32_e32 v80, 16, v60
	v_pk_fma_f32 v[74:75], v[90:91], v[156:157], v[164:165]
	v_and_b32_e32 v81, 0xffff0000, v60
	v_mul_f32_e32 v60, 0xbfb8aa3b, v80
	s_waitcnt vmcnt(19)
	v_pk_fma_f32 v[64:65], v[112:113], v[64:65], v[74:75] op_sel_hi:[0,1,1]
	v_exp_f32_e32 v74, v60
	v_mul_f32_e32 v60, 0xbfb8aa3b, v81
	v_lshlrev_b32_e32 v82, 16, v61
	v_and_b32_e32 v83, 0xffff0000, v61
	v_exp_f32_e32 v75, v60
	v_mul_f32_e32 v60, 0xbfb8aa3b, v82
	v_mul_f32_e32 v61, 0xbfb8aa3b, v83
	v_exp_f32_e32 v60, v60
	v_exp_f32_e32 v61, v61
	v_pk_add_f32 v[74:75], v[74:75], 1.0 op_sel_hi:[1,0]
	v_pk_fma_f32 v[72:73], v[112:113], v[116:117], v[72:73] op_sel_hi:[0,1,1]
	v_pk_add_f32 v[60:61], v[60:61], 1.0 op_sel_hi:[1,0]
	s_nop 0
	v_rcp_f32_e32 v86, v61
	s_nop 0
	v_mul_f32_e32 v61, v83, v86
	v_rcp_f32_e32 v83, v60
	s_nop 0
	v_mul_f32_e32 v60, v82, v83
	v_pk_mul_f32 v[60:61], v[64:65], v[60:61]
	v_and_b32_e32 v91, 0xffff0000, v52
	v_rcp_f32_e32 v82, v75
	s_nop 0
	v_mul_f32_e32 v75, v81, v82
	v_lshlrev_b32_e32 v90, 16, v52
	v_lshlrev_b32_e32 v52, 16, v53
	v_and_b32_e32 v53, 0xffff0000, v53
	v_rcp_f32_e32 v81, v74
	s_nop 0
	v_mul_f32_e32 v74, v80, v81
	v_pk_mul_f32 v[64:65], v[72:73], v[74:75]
	v_pk_mul_f32 v[74:75], v[114:115], v[84:85] op_sel_hi:[0,1]
	v_lshlrev_b32_e32 v72, 16, v66
	v_and_b32_e32 v73, 0xffff0000, v66
	v_pk_fma_f32 v[68:69], v[74:75], v[150:151], v[158:159]
	v_pk_mul_f32 v[80:81], v[114:115], v[88:89] op_sel_hi:[0,1]
	v_pk_fma_f32 v[68:69], v[112:113], v[72:73], v[68:69] op_sel_hi:[0,1,1]
	v_lshlrev_b32_e32 v72, 16, v62
	v_lshlrev_b32_e32 v66, 16, v67
	v_and_b32_e32 v67, 0xffff0000, v67
	v_pk_fma_f32 v[70:71], v[80:81], v[152:153], v[160:161]
	v_and_b32_e32 v73, 0xffff0000, v62
	v_mul_f32_e32 v62, 0xbfb8aa3b, v72
	v_pk_fma_f32 v[66:67], v[112:113], v[66:67], v[70:71] op_sel_hi:[0,1,1]
	v_exp_f32_e32 v70, v62
	v_mul_f32_e32 v62, 0xbfb8aa3b, v73
	v_lshlrev_b32_e32 v74, 16, v63
	v_and_b32_e32 v75, 0xffff0000, v63
	v_exp_f32_e32 v71, v62
	v_mul_f32_e32 v62, 0xbfb8aa3b, v74
	v_mul_f32_e32 v63, 0xbfb8aa3b, v75
	v_exp_f32_e32 v62, v62
	v_exp_f32_e32 v63, v63
	v_pk_add_f32 v[70:71], v[70:71], 1.0 op_sel_hi:[1,0]
	v_pk_add_f32 v[62:63], v[62:63], 1.0 op_sel_hi:[1,0]
	s_nop 0
	v_rcp_f32_e32 v76, v63
	s_nop 0
	v_mul_f32_e32 v63, v75, v76
	v_rcp_f32_e32 v75, v62
	s_nop 0
	v_mul_f32_e32 v62, v74, v75
	v_pk_mul_f32 v[62:63], v[66:67], v[62:63]
	v_lshlrev_b32_e32 v67, 16, v58
	v_lshlrev_b32_e32 v66, 16, v56
	v_rcp_f32_e32 v74, v71
	s_nop 0
	v_mul_f32_e32 v71, v73, v74
	v_rcp_f32_e32 v73, v70
	s_nop 0
	v_mul_f32_e32 v70, v72, v73
	v_pk_mul_f32 v[78:79], v[68:69], v[70:71]
	v_and_b32_e32 v69, 0xffff0000, v58
	v_and_b32_e32 v68, 0xffff0000, v56
	v_lshlrev_b32_e32 v71, 16, v59
	v_lshlrev_b32_e32 v70, 16, v57
	v_and_b32_e32 v59, 0xffff0000, v59
	v_and_b32_e32 v58, 0xffff0000, v57
	v_pk_add_f32 v[56:57], v[66:67], v[68:69]
	v_pk_add_f32 v[72:73], v[70:71], v[58:59]
	s_nop 0
	v_pk_add_f32 v[56:57], v[56:57], v[72:73]
	s_nop 0
	v_add_f32_e32 v56, v56, v57
	s_nop 1
	v_add_f32_dpp v56, v56, v56 quad_perm:[1,0,3,2] row_mask:0xf bank_mask:0xf bound_ctrl:1
	s_nop 1
	v_add_f32_dpp v56, v56, v56 quad_perm:[2,3,0,1] row_mask:0xf bank_mask:0xf bound_ctrl:1
	s_nop 1
	v_add_f32_dpp v56, v56, v56 row_half_mirror row_mask:0xf bank_mask:0xf bound_ctrl:1
	v_fmac_f32_e32 v58, 0xbc800000, v56
	v_fmac_f32_e32 v68, 0xbc800000, v56
	v_fmac_f32_e32 v59, 0xbc800000, v56
	v_fmac_f32_e32 v69, 0xbc800000, v56
	v_fmac_f32_e32 v70, 0xbc800000, v56
	v_fmac_f32_e32 v66, 0xbc800000, v56
	v_fmac_f32_e32 v71, 0xbc800000, v56
	v_fmac_f32_e32 v67, 0xbc800000, v56
	v_pk_mul_f32 v[56:57], v[68:69], v[68:69]
	v_mov_b32_e32 v85, v59
	v_mov_b32_e32 v87, v58
	v_pk_mul_f32 v[58:59], v[58:59], v[58:59]
	v_pk_fma_f32 v[56:57], v[66:67], v[66:67], v[56:57]
	v_pk_fma_f32 v[58:59], v[70:71], v[70:71], v[58:59]
	v_mov_b32_e32 v80, v67
	v_pk_add_f32 v[56:57], v[56:57], v[58:59]
	v_mov_b32_e32 v81, v69
	v_add_f32_e32 v56, v56, v57
	v_mov_b32_e32 v82, v66
	v_mov_b32_e32 v83, v68
	v_add_f32_dpp v56, v56, v56 quad_perm:[1,0,3,2] row_mask:0xf bank_mask:0xf bound_ctrl:1
	v_mov_b32_e32 v84, v71
	v_mov_b32_e32 v86, v70
	v_add_f32_dpp v56, v56, v56 quad_perm:[2,3,0,1] row_mask:0xf bank_mask:0xf bound_ctrl:1
	s_nop 1
	v_add_f32_dpp v56, v56, v56 row_half_mirror row_mask:0xf bank_mask:0xf bound_ctrl:1
	v_fmamk_f32 v56, v56, 0x3c800000, v103
	v_rsq_f32_e32 v88, v56
	s_nop 0
	v_pk_mul_f32 v[82:83], v[88:89], v[82:83] op_sel_hi:[0,1]
	v_pk_mul_f32 v[86:87], v[88:89], v[86:87] op_sel_hi:[0,1]
	v_pk_fma_f32 v[56:57], v[82:83], v[174:175], v[182:183]
	v_lshlrev_b32_e32 v74, 16, v48
	v_pk_fma_f32 v[58:59], v[86:87], v[176:177], v[184:185]
	v_and_b32_e32 v75, 0xffff0000, v48
	v_mul_f32_e32 v48, 0xbfb8aa3b, v74
	s_waitcnt vmcnt(18)
	v_pk_fma_f32 v[52:53], v[110:111], v[52:53], v[58:59] op_sel_hi:[0,1,1]
	v_exp_f32_e32 v58, v48
	v_mul_f32_e32 v48, 0xbfb8aa3b, v75
	v_lshlrev_b32_e32 v76, 16, v49
	v_and_b32_e32 v77, 0xffff0000, v49
	v_exp_f32_e32 v59, v48
	v_mul_f32_e32 v48, 0xbfb8aa3b, v76
	v_mul_f32_e32 v49, 0xbfb8aa3b, v77
	v_exp_f32_e32 v48, v48
	v_exp_f32_e32 v49, v49
	v_pk_add_f32 v[58:59], v[58:59], 1.0 op_sel_hi:[1,0]
	v_pk_fma_f32 v[56:57], v[110:111], v[90:91], v[56:57] op_sel_hi:[0,1,1]
	v_pk_add_f32 v[48:49], v[48:49], 1.0 op_sel_hi:[1,0]
	s_nop 0
	v_rcp_f32_e32 v82, v49
	s_nop 0
	v_mul_f32_e32 v49, v77, v82
	v_rcp_f32_e32 v77, v48
	s_nop 0
	v_mul_f32_e32 v48, v76, v77
	v_pk_mul_f32 v[52:53], v[52:53], v[48:49]
	v_lshlrev_b32_e32 v48, 16, v54
	v_and_b32_e32 v49, 0xffff0000, v54
	v_rcp_f32_e32 v76, v59
	s_nop 0
	v_mul_f32_e32 v59, v75, v76
	v_lshlrev_b32_e32 v54, 16, v55
	v_and_b32_e32 v55, 0xffff0000, v55
	v_rcp_f32_e32 v75, v58
	s_nop 0
	v_mul_f32_e32 v58, v74, v75
	v_pk_mul_f32 v[56:57], v[56:57], v[58:59]
	v_pk_mul_f32 v[58:59], v[88:89], v[80:81] op_sel_hi:[0,1]
	v_pk_mul_f32 v[74:75], v[88:89], v[84:85] op_sel_hi:[0,1]
	v_pk_fma_f32 v[58:59], v[58:59], v[170:171], v[178:179]
	v_lshlrev_b32_e32 v66, 16, v50
	v_pk_fma_f32 v[68:69], v[74:75], v[172:173], v[180:181]
	v_and_b32_e32 v67, 0xffff0000, v50
	v_mul_f32_e32 v50, 0xbfb8aa3b, v66
	v_pk_fma_f32 v[48:49], v[110:111], v[48:49], v[58:59] op_sel_hi:[0,1,1]
	v_pk_fma_f32 v[54:55], v[110:111], v[54:55], v[68:69] op_sel_hi:[0,1,1]
	v_exp_f32_e32 v58, v50
	v_mul_f32_e32 v50, 0xbfb8aa3b, v67
	v_lshlrev_b32_e32 v68, 16, v51
	v_and_b32_e32 v69, 0xffff0000, v51
	v_exp_f32_e32 v59, v50
	v_mul_f32_e32 v50, 0xbfb8aa3b, v68
	v_mul_f32_e32 v51, 0xbfb8aa3b, v69
	v_exp_f32_e32 v50, v50
	v_exp_f32_e32 v51, v51
	v_pk_add_f32 v[58:59], v[58:59], 1.0 op_sel_hi:[1,0]
	v_pk_add_f32 v[50:51], v[50:51], 1.0 op_sel_hi:[1,0]
	s_nop 0
	v_rcp_f32_e32 v70, v51
	s_nop 0
	v_mul_f32_e32 v51, v69, v70
	v_rcp_f32_e32 v69, v50
	s_nop 0
	v_mul_f32_e32 v50, v68, v69
	v_pk_mul_f32 v[54:55], v[54:55], v[50:51]
	v_rcp_f32_e32 v68, v59
	s_nop 0
	v_mul_f32_e32 v59, v67, v68
	v_rcp_f32_e32 v67, v58
	s_nop 0
	v_mul_f32_e32 v58, v66, v67
	v_pk_mul_f32 v[58:59], v[48:49], v[58:59]
	v_cvt_pk_bf16_f32 v48, v64, v65
	v_cvt_pk_bf16_f32 v49, v60, v61
	v_add_co_u32_e32 v60, vcc, s4, v100
	v_cvt_pk_bf16_f32 v50, v78, v79
	v_cvt_pk_bf16_f32 v51, v62, v63
	s_waitcnt vmcnt(15)
	v_lshlrev_b32_e32 v70, 16, v40
	s_nop 0
	v_addc_co_u32_e32 v61, vcc, 0, v101, vcc
	global_store_dwordx4 v[60:61], v[48:51], off
	v_and_b32_e32 v71, 0xffff0000, v40
	v_lshlrev_b32_e32 v40, 16, v41
	v_cvt_pk_bf16_f32 v48, v56, v57
	v_cvt_pk_bf16_f32 v49, v52, v53
	v_cvt_pk_bf16_f32 v50, v58, v59
	v_cvt_pk_bf16_f32 v51, v54, v55
	global_store_dwordx4 v[60:61], v[48:51], off offset:1024
	v_lshlrev_b32_e32 v53, 16, v47
	v_lshlrev_b32_e32 v52, 16, v45
	v_lshlrev_b32_e32 v49, 16, v46
	v_lshlrev_b32_e32 v48, 16, v44
	v_and_b32_e32 v51, 0xffff0000, v46
	v_and_b32_e32 v50, 0xffff0000, v44
	v_and_b32_e32 v47, 0xffff0000, v47
	v_and_b32_e32 v46, 0xffff0000, v45
	v_pk_add_f32 v[44:45], v[48:49], v[50:51]
	v_pk_add_f32 v[54:55], v[52:53], v[46:47]
	v_and_b32_e32 v41, 0xffff0000, v41
	v_pk_add_f32 v[44:45], v[44:45], v[54:55]
	s_nop 0
	v_add_f32_e32 v44, v44, v45
	s_nop 1
	v_add_f32_dpp v44, v44, v44 quad_perm:[1,0,3,2] row_mask:0xf bank_mask:0xf bound_ctrl:1
	s_nop 1
	v_add_f32_dpp v44, v44, v44 quad_perm:[2,3,0,1] row_mask:0xf bank_mask:0xf bound_ctrl:1
	s_nop 1
	v_add_f32_dpp v44, v44, v44 row_half_mirror row_mask:0xf bank_mask:0xf bound_ctrl:1
	v_fmac_f32_e32 v46, 0xbc800000, v44
	v_fmac_f32_e32 v50, 0xbc800000, v44
	v_fmac_f32_e32 v47, 0xbc800000, v44
	v_fmac_f32_e32 v51, 0xbc800000, v44
	v_fmac_f32_e32 v52, 0xbc800000, v44
	v_fmac_f32_e32 v48, 0xbc800000, v44
	v_fmac_f32_e32 v53, 0xbc800000, v44
	v_fmac_f32_e32 v49, 0xbc800000, v44
	v_pk_mul_f32 v[44:45], v[50:51], v[50:51]
	v_mov_b32_e32 v65, v47
	v_mov_b32_e32 v67, v46
	v_pk_mul_f32 v[46:47], v[46:47], v[46:47]
	v_pk_fma_f32 v[44:45], v[48:49], v[48:49], v[44:45]
	v_pk_fma_f32 v[46:47], v[52:53], v[52:53], v[46:47]
	v_mov_b32_e32 v60, v49
	v_pk_add_f32 v[44:45], v[44:45], v[46:47]
	v_mov_b32_e32 v61, v51
	v_add_f32_e32 v44, v44, v45
	v_mov_b32_e32 v62, v48
	v_mov_b32_e32 v63, v50
	v_add_f32_dpp v44, v44, v44 quad_perm:[1,0,3,2] row_mask:0xf bank_mask:0xf bound_ctrl:1
	v_mov_b32_e32 v64, v53
	v_mov_b32_e32 v66, v52
	v_add_f32_dpp v44, v44, v44 quad_perm:[2,3,0,1] row_mask:0xf bank_mask:0xf bound_ctrl:1
	s_nop 1
	v_add_f32_dpp v44, v44, v44 row_half_mirror row_mask:0xf bank_mask:0xf bound_ctrl:1
	v_fmamk_f32 v44, v44, 0x3c800000, v103
	v_rsq_f32_e32 v68, v44
	s_nop 0
	v_pk_mul_f32 v[62:63], v[68:69], v[62:63] op_sel_hi:[0,1]
	v_pk_mul_f32 v[66:67], v[68:69], v[66:67] op_sel_hi:[0,1]
	v_pk_fma_f32 v[48:49], v[62:63], v[154:155], v[162:163]
	s_waitcnt vmcnt(15)
	v_lshlrev_b32_e32 v56, 16, v36
	v_pk_fma_f32 v[50:51], v[66:67], v[156:157], v[164:165]
	v_and_b32_e32 v57, 0xffff0000, v36
	v_mul_f32_e32 v36, 0xbfb8aa3b, v56
	s_waitcnt vmcnt(13)
	v_pk_fma_f32 v[40:41], v[108:109], v[40:41], v[50:51] op_sel_hi:[0,1,1]
	v_exp_f32_e32 v50, v36
	v_mul_f32_e32 v36, 0xbfb8aa3b, v57
	v_lshlrev_b32_e32 v58, 16, v37
	v_and_b32_e32 v59, 0xffff0000, v37
	v_exp_f32_e32 v51, v36
	v_mul_f32_e32 v36, 0xbfb8aa3b, v58
	v_mul_f32_e32 v37, 0xbfb8aa3b, v59
	v_exp_f32_e32 v36, v36
	v_exp_f32_e32 v37, v37
	v_pk_add_f32 v[50:51], v[50:51], 1.0 op_sel_hi:[1,0]
	v_pk_fma_f32 v[48:49], v[108:109], v[70:71], v[48:49] op_sel_hi:[0,1,1]
	v_pk_add_f32 v[36:37], v[36:37], 1.0 op_sel_hi:[1,0]
	s_nop 0
	v_rcp_f32_e32 v62, v37
	s_nop 0
	v_mul_f32_e32 v37, v59, v62
	v_rcp_f32_e32 v59, v36
	s_nop 0
	v_mul_f32_e32 v36, v58, v59
	v_pk_mul_f32 v[36:37], v[40:41], v[36:37]
	v_and_b32_e32 v67, 0xffff0000, v28
	v_rcp_f32_e32 v58, v51
	s_nop 0
	v_mul_f32_e32 v51, v57, v58
	v_lshlrev_b32_e32 v66, 16, v28
	v_lshlrev_b32_e32 v28, 16, v29
	v_and_b32_e32 v29, 0xffff0000, v29
	v_rcp_f32_e32 v57, v50
	s_nop 0
	v_mul_f32_e32 v50, v56, v57
	v_pk_mul_f32 v[40:41], v[48:49], v[50:51]
	v_pk_mul_f32 v[50:51], v[68:69], v[60:61] op_sel_hi:[0,1]
	v_lshlrev_b32_e32 v48, 16, v42
	v_and_b32_e32 v49, 0xffff0000, v42
	v_pk_fma_f32 v[44:45], v[50:51], v[150:151], v[158:159]
	v_pk_mul_f32 v[56:57], v[68:69], v[64:65] op_sel_hi:[0,1]
	v_pk_fma_f32 v[44:45], v[108:109], v[48:49], v[44:45] op_sel_hi:[0,1,1]
	v_lshlrev_b32_e32 v48, 16, v38
	v_lshlrev_b32_e32 v42, 16, v43
	v_and_b32_e32 v43, 0xffff0000, v43
	v_pk_fma_f32 v[46:47], v[56:57], v[152:153], v[160:161]
	v_and_b32_e32 v49, 0xffff0000, v38
	v_mul_f32_e32 v38, 0xbfb8aa3b, v48
	v_pk_fma_f32 v[42:43], v[108:109], v[42:43], v[46:47] op_sel_hi:[0,1,1]
	v_exp_f32_e32 v46, v38
	v_mul_f32_e32 v38, 0xbfb8aa3b, v49
	v_lshlrev_b32_e32 v50, 16, v39
	v_and_b32_e32 v51, 0xffff0000, v39
	v_exp_f32_e32 v47, v38
	v_mul_f32_e32 v38, 0xbfb8aa3b, v50
	v_mul_f32_e32 v39, 0xbfb8aa3b, v51
	v_exp_f32_e32 v38, v38
	v_exp_f32_e32 v39, v39
	v_pk_add_f32 v[46:47], v[46:47], 1.0 op_sel_hi:[1,0]
	v_pk_add_f32 v[38:39], v[38:39], 1.0 op_sel_hi:[1,0]
	s_nop 0
	v_rcp_f32_e32 v52, v39
	s_nop 0
	v_mul_f32_e32 v39, v51, v52
	v_rcp_f32_e32 v51, v38
	s_nop 0
	v_mul_f32_e32 v38, v50, v51
	v_pk_mul_f32 v[38:39], v[42:43], v[38:39]
	v_lshlrev_b32_e32 v43, 16, v34
	v_lshlrev_b32_e32 v42, 16, v32
	v_rcp_f32_e32 v50, v47
	s_nop 0
	v_mul_f32_e32 v47, v49, v50
	v_rcp_f32_e32 v49, v46
	s_nop 0
	v_mul_f32_e32 v46, v48, v49
	v_pk_mul_f32 v[54:55], v[44:45], v[46:47]
	v_and_b32_e32 v45, 0xffff0000, v34
	v_and_b32_e32 v44, 0xffff0000, v32
	v_lshlrev_b32_e32 v47, 16, v35
	v_lshlrev_b32_e32 v46, 16, v33
	v_and_b32_e32 v35, 0xffff0000, v35
	v_and_b32_e32 v34, 0xffff0000, v33
	v_pk_add_f32 v[32:33], v[42:43], v[44:45]
	v_pk_add_f32 v[48:49], v[46:47], v[34:35]
	s_nop 0
	v_pk_add_f32 v[32:33], v[32:33], v[48:49]
	s_nop 0
	v_add_f32_e32 v32, v32, v33
	s_nop 1
	v_add_f32_dpp v32, v32, v32 quad_perm:[1,0,3,2] row_mask:0xf bank_mask:0xf bound_ctrl:1
	s_nop 1
	v_add_f32_dpp v32, v32, v32 quad_perm:[2,3,0,1] row_mask:0xf bank_mask:0xf bound_ctrl:1
	s_nop 1
	v_add_f32_dpp v32, v32, v32 row_half_mirror row_mask:0xf bank_mask:0xf bound_ctrl:1
	v_fmac_f32_e32 v34, 0xbc800000, v32
	v_fmac_f32_e32 v44, 0xbc800000, v32
	v_fmac_f32_e32 v35, 0xbc800000, v32
	v_fmac_f32_e32 v45, 0xbc800000, v32
	v_fmac_f32_e32 v46, 0xbc800000, v32
	v_fmac_f32_e32 v42, 0xbc800000, v32
	v_fmac_f32_e32 v47, 0xbc800000, v32
	v_fmac_f32_e32 v43, 0xbc800000, v32
	v_pk_mul_f32 v[32:33], v[44:45], v[44:45]
	v_mov_b32_e32 v61, v35
	v_mov_b32_e32 v63, v34
	v_pk_mul_f32 v[34:35], v[34:35], v[34:35]
	v_pk_fma_f32 v[32:33], v[42:43], v[42:43], v[32:33]
	v_pk_fma_f32 v[34:35], v[46:47], v[46:47], v[34:35]
	v_mov_b32_e32 v56, v43
	v_pk_add_f32 v[32:33], v[32:33], v[34:35]
	v_mov_b32_e32 v57, v45
	v_add_f32_e32 v32, v32, v33
	v_mov_b32_e32 v58, v42
	v_mov_b32_e32 v59, v44
	v_add_f32_dpp v32, v32, v32 quad_perm:[1,0,3,2] row_mask:0xf bank_mask:0xf bound_ctrl:1
	v_mov_b32_e32 v60, v47
	v_mov_b32_e32 v62, v46
	v_add_f32_dpp v32, v32, v32 quad_perm:[2,3,0,1] row_mask:0xf bank_mask:0xf bound_ctrl:1
	s_nop 1
	v_add_f32_dpp v32, v32, v32 row_half_mirror row_mask:0xf bank_mask:0xf bound_ctrl:1
	v_fmamk_f32 v32, v32, 0x3c800000, v103
	v_rsq_f32_e32 v64, v32
	s_nop 0
	v_pk_mul_f32 v[58:59], v[64:65], v[58:59] op_sel_hi:[0,1]
	v_pk_mul_f32 v[62:63], v[64:65], v[62:63] op_sel_hi:[0,1]
	v_pk_fma_f32 v[32:33], v[58:59], v[174:175], v[182:183]
	v_lshlrev_b32_e32 v50, 16, v24
	v_pk_fma_f32 v[34:35], v[62:63], v[176:177], v[184:185]
	v_and_b32_e32 v51, 0xffff0000, v24
	v_mul_f32_e32 v24, 0xbfb8aa3b, v50
	s_waitcnt vmcnt(12)
	v_pk_fma_f32 v[28:29], v[106:107], v[28:29], v[34:35] op_sel_hi:[0,1,1]
	v_exp_f32_e32 v34, v24
	v_mul_f32_e32 v24, 0xbfb8aa3b, v51
	v_lshlrev_b32_e32 v52, 16, v25
	v_and_b32_e32 v53, 0xffff0000, v25
	v_exp_f32_e32 v35, v24
	v_mul_f32_e32 v24, 0xbfb8aa3b, v52
	v_mul_f32_e32 v25, 0xbfb8aa3b, v53
	v_exp_f32_e32 v24, v24
	v_exp_f32_e32 v25, v25
	v_pk_add_f32 v[34:35], v[34:35], 1.0 op_sel_hi:[1,0]
	v_pk_fma_f32 v[32:33], v[106:107], v[66:67], v[32:33] op_sel_hi:[0,1,1]
	v_pk_add_f32 v[24:25], v[24:25], 1.0 op_sel_hi:[1,0]
	s_nop 0
	v_rcp_f32_e32 v58, v25
	s_nop 0
	v_mul_f32_e32 v25, v53, v58
	v_rcp_f32_e32 v53, v24
	s_nop 0
	v_mul_f32_e32 v24, v52, v53
	v_pk_mul_f32 v[28:29], v[28:29], v[24:25]
	v_lshlrev_b32_e32 v24, 16, v30
	v_and_b32_e32 v25, 0xffff0000, v30
	v_rcp_f32_e32 v52, v35
	s_nop 0
	v_mul_f32_e32 v35, v51, v52
	v_lshlrev_b32_e32 v30, 16, v31
	v_and_b32_e32 v31, 0xffff0000, v31
	v_rcp_f32_e32 v51, v34
	s_nop 0
	v_mul_f32_e32 v34, v50, v51
	v_pk_mul_f32 v[32:33], v[32:33], v[34:35]
	v_pk_mul_f32 v[34:35], v[64:65], v[56:57] op_sel_hi:[0,1]
	v_pk_mul_f32 v[50:51], v[64:65], v[60:61] op_sel_hi:[0,1]
	v_pk_fma_f32 v[34:35], v[34:35], v[170:171], v[178:179]
	v_lshlrev_b32_e32 v42, 16, v26
	v_pk_fma_f32 v[44:45], v[50:51], v[172:173], v[180:181]
	v_and_b32_e32 v43, 0xffff0000, v26
	v_mul_f32_e32 v26, 0xbfb8aa3b, v42
	v_pk_fma_f32 v[24:25], v[106:107], v[24:25], v[34:35] op_sel_hi:[0,1,1]
	v_pk_fma_f32 v[30:31], v[106:107], v[30:31], v[44:45] op_sel_hi:[0,1,1]
	v_exp_f32_e32 v34, v26
	v_mul_f32_e32 v26, 0xbfb8aa3b, v43
	v_lshlrev_b32_e32 v44, 16, v27
	v_and_b32_e32 v45, 0xffff0000, v27
	v_exp_f32_e32 v35, v26
	v_mul_f32_e32 v26, 0xbfb8aa3b, v44
	v_mul_f32_e32 v27, 0xbfb8aa3b, v45
	v_exp_f32_e32 v26, v26
	v_exp_f32_e32 v27, v27
	v_pk_add_f32 v[34:35], v[34:35], 1.0 op_sel_hi:[1,0]
	v_pk_add_f32 v[26:27], v[26:27], 1.0 op_sel_hi:[1,0]
	s_nop 0
	v_rcp_f32_e32 v46, v27
	s_nop 0
	v_mul_f32_e32 v27, v45, v46
	v_rcp_f32_e32 v45, v26
	s_nop 0
	v_mul_f32_e32 v26, v44, v45
	v_pk_mul_f32 v[30:31], v[30:31], v[26:27]
	v_rcp_f32_e32 v44, v35
	s_nop 0
	v_mul_f32_e32 v35, v43, v44
	v_rcp_f32_e32 v43, v34
	s_nop 0
	v_mul_f32_e32 v34, v42, v43
	v_pk_mul_f32 v[34:35], v[24:25], v[34:35]
	v_cvt_pk_bf16_f32 v24, v40, v41
	v_cvt_pk_bf16_f32 v25, v36, v37
	v_add_co_u32_e32 v36, vcc, s5, v100
	v_cvt_pk_bf16_f32 v26, v54, v55
	v_cvt_pk_bf16_f32 v27, v38, v39
	s_waitcnt vmcnt(9)
	v_lshlrev_b32_e32 v46, 16, v16
	s_nop 0
	v_addc_co_u32_e32 v37, vcc, 0, v101, vcc
	global_store_dwordx4 v[36:37], v[24:27], off
	v_and_b32_e32 v47, 0xffff0000, v16
	v_lshlrev_b32_e32 v16, 16, v17
	v_cvt_pk_bf16_f32 v24, v32, v33
	v_cvt_pk_bf16_f32 v25, v28, v29
	v_cvt_pk_bf16_f32 v26, v34, v35
	v_cvt_pk_bf16_f32 v27, v30, v31
	global_store_dwordx4 v[36:37], v[24:27], off offset:1024
	v_lshlrev_b32_e32 v29, 16, v23
	v_lshlrev_b32_e32 v28, 16, v21
	v_lshlrev_b32_e32 v25, 16, v22
	v_lshlrev_b32_e32 v24, 16, v20
	v_and_b32_e32 v27, 0xffff0000, v22
	v_and_b32_e32 v26, 0xffff0000, v20
	v_and_b32_e32 v23, 0xffff0000, v23
	v_and_b32_e32 v22, 0xffff0000, v21
	v_pk_add_f32 v[20:21], v[24:25], v[26:27]
	v_pk_add_f32 v[30:31], v[28:29], v[22:23]
	v_and_b32_e32 v17, 0xffff0000, v17
	v_pk_add_f32 v[20:21], v[20:21], v[30:31]
	s_nop 0
	v_add_f32_e32 v20, v20, v21
	s_nop 1
	v_add_f32_dpp v20, v20, v20 quad_perm:[1,0,3,2] row_mask:0xf bank_mask:0xf bound_ctrl:1
	s_nop 1
	v_add_f32_dpp v20, v20, v20 quad_perm:[2,3,0,1] row_mask:0xf bank_mask:0xf bound_ctrl:1
	s_nop 1
	v_add_f32_dpp v20, v20, v20 row_half_mirror row_mask:0xf bank_mask:0xf bound_ctrl:1
	v_fmac_f32_e32 v22, 0xbc800000, v20
	v_fmac_f32_e32 v26, 0xbc800000, v20
	v_fmac_f32_e32 v23, 0xbc800000, v20
	v_fmac_f32_e32 v27, 0xbc800000, v20
	v_fmac_f32_e32 v28, 0xbc800000, v20
	v_fmac_f32_e32 v24, 0xbc800000, v20
	v_fmac_f32_e32 v29, 0xbc800000, v20
	v_fmac_f32_e32 v25, 0xbc800000, v20
	v_pk_mul_f32 v[20:21], v[26:27], v[26:27]
	v_mov_b32_e32 v41, v23
	v_mov_b32_e32 v43, v22
	v_pk_mul_f32 v[22:23], v[22:23], v[22:23]
	v_pk_fma_f32 v[20:21], v[24:25], v[24:25], v[20:21]
	v_pk_fma_f32 v[22:23], v[28:29], v[28:29], v[22:23]
	v_mov_b32_e32 v36, v25
	v_pk_add_f32 v[20:21], v[20:21], v[22:23]
	v_mov_b32_e32 v37, v27
	v_add_f32_e32 v20, v20, v21
	v_mov_b32_e32 v38, v24
	v_mov_b32_e32 v39, v26
	v_add_f32_dpp v20, v20, v20 quad_perm:[1,0,3,2] row_mask:0xf bank_mask:0xf bound_ctrl:1
	v_mov_b32_e32 v40, v29
	v_mov_b32_e32 v42, v28
	v_add_f32_dpp v20, v20, v20 quad_perm:[2,3,0,1] row_mask:0xf bank_mask:0xf bound_ctrl:1
	s_nop 1
	v_add_f32_dpp v20, v20, v20 row_half_mirror row_mask:0xf bank_mask:0xf bound_ctrl:1
	v_fmamk_f32 v20, v20, 0x3c800000, v103
	v_rsq_f32_e32 v44, v20
	s_nop 0
	v_pk_mul_f32 v[38:39], v[44:45], v[38:39] op_sel_hi:[0,1]
	v_pk_mul_f32 v[42:43], v[44:45], v[42:43] op_sel_hi:[0,1]
	v_pk_fma_f32 v[24:25], v[38:39], v[154:155], v[162:163]
	s_waitcnt vmcnt(9)
	v_lshlrev_b32_e32 v32, 16, v12
	v_pk_fma_f32 v[26:27], v[42:43], v[156:157], v[164:165]
	v_and_b32_e32 v33, 0xffff0000, v12
	v_mul_f32_e32 v12, 0xbfb8aa3b, v32
	s_waitcnt vmcnt(7)
	v_pk_fma_f32 v[16:17], v[104:105], v[16:17], v[26:27] op_sel_hi:[0,1,1]
	v_exp_f32_e32 v26, v12
	v_mul_f32_e32 v12, 0xbfb8aa3b, v33
	v_lshlrev_b32_e32 v34, 16, v13
	v_and_b32_e32 v35, 0xffff0000, v13
	v_exp_f32_e32 v27, v12
	v_mul_f32_e32 v12, 0xbfb8aa3b, v34
	v_mul_f32_e32 v13, 0xbfb8aa3b, v35
	v_exp_f32_e32 v12, v12
	v_exp_f32_e32 v13, v13
	v_pk_add_f32 v[26:27], v[26:27], 1.0 op_sel_hi:[1,0]
	v_pk_fma_f32 v[24:25], v[104:105], v[46:47], v[24:25] op_sel_hi:[0,1,1]
	v_pk_add_f32 v[12:13], v[12:13], 1.0 op_sel_hi:[1,0]
	s_nop 0
	v_rcp_f32_e32 v38, v13
	s_nop 0
	v_mul_f32_e32 v13, v35, v38
	v_rcp_f32_e32 v35, v12
	s_nop 0
	v_mul_f32_e32 v12, v34, v35
	v_pk_mul_f32 v[12:13], v[16:17], v[12:13]
	v_and_b32_e32 v43, 0xffff0000, v4
	v_rcp_f32_e32 v34, v27
	s_nop 0
	v_mul_f32_e32 v27, v33, v34
	v_lshlrev_b32_e32 v42, 16, v4
	v_lshlrev_b32_e32 v4, 16, v5
	v_and_b32_e32 v5, 0xffff0000, v5
	v_rcp_f32_e32 v33, v26
	s_nop 0
	v_mul_f32_e32 v26, v32, v33
	v_pk_mul_f32 v[16:17], v[24:25], v[26:27]
	v_pk_mul_f32 v[26:27], v[44:45], v[36:37] op_sel_hi:[0,1]
	v_lshlrev_b32_e32 v24, 16, v18
	v_and_b32_e32 v25, 0xffff0000, v18
	v_pk_fma_f32 v[20:21], v[26:27], v[150:151], v[158:159]
	v_pk_mul_f32 v[32:33], v[44:45], v[40:41] op_sel_hi:[0,1]
	v_pk_fma_f32 v[20:21], v[104:105], v[24:25], v[20:21] op_sel_hi:[0,1,1]
	v_lshlrev_b32_e32 v24, 16, v14
	v_lshlrev_b32_e32 v18, 16, v19
	v_and_b32_e32 v19, 0xffff0000, v19
	v_pk_fma_f32 v[22:23], v[32:33], v[152:153], v[160:161]
	v_and_b32_e32 v25, 0xffff0000, v14
	v_mul_f32_e32 v14, 0xbfb8aa3b, v24
	v_pk_fma_f32 v[18:19], v[104:105], v[18:19], v[22:23] op_sel_hi:[0,1,1]
	v_exp_f32_e32 v22, v14
	v_mul_f32_e32 v14, 0xbfb8aa3b, v25
	v_lshlrev_b32_e32 v26, 16, v15
	v_and_b32_e32 v27, 0xffff0000, v15
	v_exp_f32_e32 v23, v14
	v_mul_f32_e32 v14, 0xbfb8aa3b, v26
	v_mul_f32_e32 v15, 0xbfb8aa3b, v27
	v_exp_f32_e32 v14, v14
	v_exp_f32_e32 v15, v15
	v_pk_add_f32 v[22:23], v[22:23], 1.0 op_sel_hi:[1,0]
	v_pk_add_f32 v[14:15], v[14:15], 1.0 op_sel_hi:[1,0]
	s_nop 0
	v_rcp_f32_e32 v28, v15
	s_nop 0
	v_mul_f32_e32 v15, v27, v28
	v_rcp_f32_e32 v27, v14
	s_nop 0
	v_mul_f32_e32 v14, v26, v27
	v_pk_mul_f32 v[14:15], v[18:19], v[14:15]
	v_lshlrev_b32_e32 v19, 16, v10
	v_lshlrev_b32_e32 v18, 16, v8
	v_rcp_f32_e32 v26, v23
	s_nop 0
	v_mul_f32_e32 v23, v25, v26
	v_rcp_f32_e32 v25, v22
	s_nop 0
	v_mul_f32_e32 v22, v24, v25
	v_pk_mul_f32 v[30:31], v[20:21], v[22:23]
	v_and_b32_e32 v21, 0xffff0000, v10
	v_and_b32_e32 v20, 0xffff0000, v8
	v_lshlrev_b32_e32 v23, 16, v11
	v_lshlrev_b32_e32 v22, 16, v9
	v_and_b32_e32 v11, 0xffff0000, v11
	v_and_b32_e32 v10, 0xffff0000, v9
	v_pk_add_f32 v[8:9], v[18:19], v[20:21]
	v_pk_add_f32 v[24:25], v[22:23], v[10:11]
	s_nop 0
	v_pk_add_f32 v[8:9], v[8:9], v[24:25]
	s_nop 0
	v_add_f32_e32 v8, v8, v9
	s_nop 1
	v_add_f32_dpp v8, v8, v8 quad_perm:[1,0,3,2] row_mask:0xf bank_mask:0xf bound_ctrl:1
	s_nop 1
	v_add_f32_dpp v8, v8, v8 quad_perm:[2,3,0,1] row_mask:0xf bank_mask:0xf bound_ctrl:1
	s_nop 1
	v_add_f32_dpp v8, v8, v8 row_half_mirror row_mask:0xf bank_mask:0xf bound_ctrl:1
	v_fmac_f32_e32 v10, 0xbc800000, v8
	v_fmac_f32_e32 v20, 0xbc800000, v8
	v_fmac_f32_e32 v11, 0xbc800000, v8
	v_fmac_f32_e32 v21, 0xbc800000, v8
	v_fmac_f32_e32 v22, 0xbc800000, v8
	v_fmac_f32_e32 v18, 0xbc800000, v8
	v_fmac_f32_e32 v23, 0xbc800000, v8
	v_fmac_f32_e32 v19, 0xbc800000, v8
	v_pk_mul_f32 v[8:9], v[20:21], v[20:21]
	v_mov_b32_e32 v37, v11
	v_mov_b32_e32 v39, v10
	v_pk_mul_f32 v[10:11], v[10:11], v[10:11]
	v_pk_fma_f32 v[8:9], v[18:19], v[18:19], v[8:9]
	v_pk_fma_f32 v[10:11], v[22:23], v[22:23], v[10:11]
	v_mov_b32_e32 v32, v19
	v_pk_add_f32 v[8:9], v[8:9], v[10:11]
	v_mov_b32_e32 v33, v21
	v_add_f32_e32 v8, v8, v9
	v_mov_b32_e32 v34, v18
	v_mov_b32_e32 v35, v20
	v_add_f32_dpp v8, v8, v8 quad_perm:[1,0,3,2] row_mask:0xf bank_mask:0xf bound_ctrl:1
	v_mov_b32_e32 v36, v23
	v_mov_b32_e32 v38, v22
	v_add_f32_dpp v8, v8, v8 quad_perm:[2,3,0,1] row_mask:0xf bank_mask:0xf bound_ctrl:1
	s_nop 1
	v_add_f32_dpp v8, v8, v8 row_half_mirror row_mask:0xf bank_mask:0xf bound_ctrl:1
	v_fmamk_f32 v8, v8, 0x3c800000, v103
	v_rsq_f32_e32 v40, v8
	s_nop 0
	v_pk_mul_f32 v[34:35], v[40:41], v[34:35] op_sel_hi:[0,1]
	v_pk_mul_f32 v[38:39], v[40:41], v[38:39] op_sel_hi:[0,1]
	v_pk_fma_f32 v[8:9], v[34:35], v[174:175], v[182:183]
	v_lshlrev_b32_e32 v26, 16, v0
	v_pk_fma_f32 v[10:11], v[38:39], v[176:177], v[184:185]
	v_and_b32_e32 v27, 0xffff0000, v0
	v_mul_f32_e32 v0, 0xbfb8aa3b, v26
	s_waitcnt vmcnt(6)
	v_pk_fma_f32 v[4:5], v[102:103], v[4:5], v[10:11] op_sel_hi:[0,1,1]
	v_exp_f32_e32 v10, v0
	v_mul_f32_e32 v0, 0xbfb8aa3b, v27
	v_lshlrev_b32_e32 v28, 16, v1
	v_and_b32_e32 v29, 0xffff0000, v1
	v_exp_f32_e32 v11, v0
	v_mul_f32_e32 v0, 0xbfb8aa3b, v28
	v_mul_f32_e32 v1, 0xbfb8aa3b, v29
	v_exp_f32_e32 v0, v0
	v_exp_f32_e32 v1, v1
	v_pk_add_f32 v[10:11], v[10:11], 1.0 op_sel_hi:[1,0]
	v_pk_fma_f32 v[8:9], v[102:103], v[42:43], v[8:9] op_sel_hi:[0,1,1]
	v_pk_add_f32 v[0:1], v[0:1], 1.0 op_sel_hi:[1,0]
	s_nop 0
	v_rcp_f32_e32 v34, v1
	s_nop 0
	v_mul_f32_e32 v1, v29, v34
	v_rcp_f32_e32 v29, v0
	s_nop 0
	v_mul_f32_e32 v0, v28, v29
	v_pk_mul_f32 v[4:5], v[4:5], v[0:1]
	v_lshlrev_b32_e32 v0, 16, v6
	v_and_b32_e32 v1, 0xffff0000, v6
	v_rcp_f32_e32 v28, v11
	s_nop 0
	v_mul_f32_e32 v11, v27, v28
	v_lshlrev_b32_e32 v6, 16, v7
	v_and_b32_e32 v7, 0xffff0000, v7
	v_rcp_f32_e32 v27, v10
	s_nop 0
	v_mul_f32_e32 v10, v26, v27
	v_pk_mul_f32 v[8:9], v[8:9], v[10:11]
	v_pk_mul_f32 v[10:11], v[40:41], v[32:33] op_sel_hi:[0,1]
	v_pk_mul_f32 v[26:27], v[40:41], v[36:37] op_sel_hi:[0,1]
	v_pk_fma_f32 v[10:11], v[10:11], v[170:171], v[178:179]
	v_lshlrev_b32_e32 v18, 16, v2
	v_pk_fma_f32 v[20:21], v[26:27], v[172:173], v[180:181]
	v_and_b32_e32 v19, 0xffff0000, v2
	v_mul_f32_e32 v2, 0xbfb8aa3b, v18
	v_pk_fma_f32 v[0:1], v[102:103], v[0:1], v[10:11] op_sel_hi:[0,1,1]
	v_pk_fma_f32 v[6:7], v[102:103], v[6:7], v[20:21] op_sel_hi:[0,1,1]
	v_exp_f32_e32 v10, v2
	v_mul_f32_e32 v2, 0xbfb8aa3b, v19
	v_lshlrev_b32_e32 v20, 16, v3
	v_and_b32_e32 v21, 0xffff0000, v3
	v_exp_f32_e32 v11, v2
	v_mul_f32_e32 v2, 0xbfb8aa3b, v20
	v_mul_f32_e32 v3, 0xbfb8aa3b, v21
	v_exp_f32_e32 v2, v2
	v_exp_f32_e32 v3, v3
	v_pk_add_f32 v[10:11], v[10:11], 1.0 op_sel_hi:[1,0]
	v_pk_add_f32 v[2:3], v[2:3], 1.0 op_sel_hi:[1,0]
	s_nop 0
	v_rcp_f32_e32 v22, v3
	s_nop 0
	v_mul_f32_e32 v3, v21, v22
	v_rcp_f32_e32 v21, v2
	s_nop 0
	v_mul_f32_e32 v2, v20, v21
	v_pk_mul_f32 v[6:7], v[6:7], v[2:3]
	v_rcp_f32_e32 v20, v11
	s_nop 0
	v_mul_f32_e32 v11, v19, v20
	v_rcp_f32_e32 v19, v10
	s_nop 0
	v_mul_f32_e32 v10, v18, v19
	v_pk_mul_f32 v[10:11], v[0:1], v[10:11]
	v_cvt_pk_bf16_f32 v0, v16, v17
	v_cvt_pk_bf16_f32 v1, v12, v13
	v_add_co_u32_e32 v12, vcc, s12, v100
	v_cvt_pk_bf16_f32 v2, v30, v31
	v_cvt_pk_bf16_f32 v3, v14, v15
	s_nop 1
	v_addc_co_u32_e32 v13, vcc, 0, v101, vcc
	global_store_dwordx4 v[12:13], v[0:3], off
	s_nop 1
	v_cvt_pk_bf16_f32 v0, v8, v9
	v_cvt_pk_bf16_f32 v1, v4, v5
	v_cvt_pk_bf16_f32 v2, v10, v11
	v_cvt_pk_bf16_f32 v3, v6, v7
	global_store_dwordx4 v[12:13], v[0:3], off offset:1024
	s_cbranch_scc0 .LBB0_904

.LBB0_1029:
	s_or_b64 exec, exec, s[0:1]
	s_waitcnt lgkmcnt(0)
	v_mov_b32_e32 v0, v226
	s_barrier
	s_nop 0
	v_readfirstlane_b32 s0, v0
	s_ashr_i32 s0, s0, 6
	s_add_i32 s6, s85, s0
	s_cmp_lt_i32 s6, s73
	s_cbranch_scc1 .LBB0_1032
	v_readlane_b32 s8, v254, 46
	s_ashr_i32 s7, s6, 31
	v_lshlrev_b32_e32 v1, 5, v0
	v_readlane_b32 s10, v254, 48
	v_readlane_b32 s11, v254, 49
	v_readlane_b32 s14, v254, 52
	v_readlane_b32 s15, v254, 53
	s_lshl_b64 s[0:1], s[6:7], 11
	v_and_b32_e32 v2, 0x7e0, v1
	v_mov_b32_e32 v3, 0
	s_mov_b64 s[10:11], s[14:15]
	v_and_b32_e32 v4, 63, v0
	s_add_u32 s0, s92, s0
	v_lshl_add_u64 v[56:57], s[10:11], 0, v[2:3]
	v_lshlrev_b32_e32 v2, 4, v4
	s_addc_u32 s1, s93, s1
	v_readlane_b32 s9, v254, 47
	v_lshl_add_u64 v[0:1], s[0:1], 0, v[2:3]
	s_mov_b64 s[0:1], 0x38080400
	s_mov_b64 s[4:5], s[8:9]
	v_lshl_add_u64 v[58:59], v[0:1], 0, s[0:1]
	s_lshl_b64 s[0:1], s[6:7], 12
	s_add_u32 s0, s4, s0
	v_readlane_b32 s12, v254, 50
	v_readlane_b32 s13, v254, 51
	v_readlane_b32 s16, v254, 54
	v_readlane_b32 s17, v254, 55
	v_readlane_b32 s18, v254, 56
	v_readlane_b32 s19, v254, 57
	v_readlane_b32 s20, v254, 58
	v_readlane_b32 s21, v254, 59
	v_readlane_b32 s22, v254, 60
	v_readlane_b32 s23, v254, 61
	v_lshlrev_b32_e32 v2, 5, v4
	s_addc_u32 s1, s5, s1
	v_lshl_add_u64 v[0:1], s[0:1], 0, v[2:3]
	s_mov_b64 s[0:1], 0x300810
	s_mov_b32 s8, 0xffcff7f0
	s_mov_b32 s10, 0xffcffff0
	s_mov_b32 s12, 0xffdff7f0
	s_mov_b32 s14, 0xffdffff0
	s_mov_b32 s16, 0xffeff7f0
	s_mov_b32 s18, 0xffeffff0
	s_mov_b32 s20, 0xffe00000
	s_mov_b32 s22, 0xffc00000
	v_lshl_add_u64 v[60:61], v[0:1], 0, s[0:1]
	s_mov_b32 s9, -1
	s_mov_b32 s11, -1
	s_mov_b32 s4, 0xfff00000
	s_mov_b32 s13, -1
	s_mov_b32 s15, -1
	s_mov_b32 s17, -1
	s_mov_b32 s19, -1
	v_mov_b32_e32 v82, 0x358637bd
	s_mov_b32 s5, 0xcf880000
	s_mov_b32 s7, 0xcf900000
	s_mov_b32 s24, 0xcf980000
	s_mov_b32 s25, 0xcfa00000
	s_mov_b32 s21, -1
	s_mov_b32 s23, -1
	global_load_dwordx4 v[182:185], v[56:57], off offset:16
	global_load_dwordx4 v[186:189], v[56:57], off
	global_load_dwordx4 v[190:193], v[56:57], off offset:2064
	global_load_dwordx4 v[194:197], v[56:57], off offset:2048
	s_waitcnt vmcnt(0)
.LBB0_1031:
	v_add_co_u32_e32 v62, vcc, 0xffe80000, v58
	v_add_co_u32_e64 v42, s[0:1], s4, v60
	v_lshl_add_u64 v[40:41], v[60:61], 0, s[16:17]
	s_nop 0
	v_addc_co_u32_e64 v43, s[0:1], -1, v61, s[0:1]
	v_addc_co_u32_e32 v63, vcc, -1, v59, vcc
	v_lshl_add_u64 v[74:75], v[60:61], 0, s[18:19]
	global_load_dwordx4 v[36:39], v[58:59], off offset:-1024 nt
	global_load_dwordx4 v[16:19], v[58:59], off nt
	global_load_dwordx4 v[4:7], v[60:61], off offset:-2048 nt
	global_load_dwordx4 v[12:15], v[60:61], off offset:-2064 nt
	global_load_dwordx4 v[0:3], v[60:61], off nt
	global_load_dwordx4 v[8:11], v[60:61], off offset:-16 nt
	global_load_dwordx4 v[52:55], v[42:43], off offset:-2064 nt
	global_load_dwordx4 v[48:51], v[40:41], off offset:16 nt
	global_load_dwordx4 v[44:47], v[42:43], off offset:-16 nt
	s_nop 0
	global_load_dwordx4 v[40:43], v[74:75], off offset:16 nt
	global_load_dwordx4 v[84:87], v[62:63], off offset:-1024 nt
	global_load_dwordx4 v[88:91], v[62:63], off nt
	v_add_co_u32_e32 v100, vcc, 0xffd00000, v60
	v_lshl_add_u64 v[64:65], v[60:61], 0, s[8:9]
	s_nop 0
	v_addc_co_u32_e32 v101, vcc, -1, v61, vcc
	v_lshl_add_u64 v[68:69], v[60:61], 0, s[10:11]
	global_load_dwordx4 v[92:95], v[100:101], off offset:-2064 nt
	global_load_dwordx4 v[96:99], v[64:65], off offset:16 nt
	s_nop 0
	global_load_dwordx4 v[100:103], v[100:101], off offset:-16 nt
	s_nop 0
	global_load_dwordx4 v[104:107], v[68:69], off offset:16 nt
	v_add_co_u32_e32 v62, vcc, 0xfff00000, v58
	v_lshl_add_u64 v[66:67], v[60:61], 0, s[12:13]
	s_nop 0
	v_addc_co_u32_e32 v63, vcc, -1, v59, vcc
	v_add_co_u32_e32 v64, vcc, 0xffe00000, v60
	v_lshl_add_u64 v[70:71], v[60:61], 0, s[14:15]
	s_nop 0
	v_addc_co_u32_e32 v65, vcc, -1, v61, vcc
	global_load_dwordx4 v[108:111], v[62:63], off offset:-1024 nt
	global_load_dwordx4 v[112:115], v[62:63], off nt
	global_load_dwordx4 v[116:119], v[64:65], off offset:-2064 nt
	s_nop 0
	global_load_dwordx4 v[66:69], v[66:67], off offset:16 nt
	s_nop 0
	global_load_dwordx4 v[120:123], v[64:65], off offset:-16 nt
	global_load_dwordx4 v[124:127], v[70:71], off offset:16 nt
	v_add_co_u32_e64 v72, s[0:1], s5, v58
	v_add_co_u32_e32 v62, vcc, 0xfff80000, v58
	s_nop 0
	v_addc_co_u32_e64 v73, s[0:1], -1, v59, s[0:1]
	v_add_co_u32_e64 v76, s[0:1], s7, v58
	v_addc_co_u32_e32 v63, vcc, -1, v59, vcc
	s_nop 0
	v_addc_co_u32_e64 v77, s[0:1], -1, v59, s[0:1]
	v_add_co_u32_e64 v78, s[0:1], s24, v58
	global_load_dwordx4 v[128:131], v[62:63], off offset:-1024 nt
	global_load_dwordx4 v[132:135], v[62:63], off nt
	v_addc_co_u32_e64 v79, s[0:1], -1, v59, s[0:1]
	v_add_co_u32_e64 v80, s[0:1], s25, v58
	s_addk_i32 s6, 0xfc00
	s_nop 0
	v_addc_co_u32_e64 v81, s[0:1], -1, v59, s[0:1]
	s_cmp_lt_i32 s6, s73
	v_lshl_add_u64 v[60:61], v[60:61], 0, s[22:23]
	v_lshl_add_u64 v[58:59], v[58:59], 0, s[20:21]
	s_waitcnt vmcnt(23)
	v_lshlrev_b32_e32 v62, 16, v36
	v_and_b32_e32 v63, 0xffff0000, v36
	v_lshlrev_b32_e32 v36, 16, v37
	v_and_b32_e32 v37, 0xffff0000, v37
	v_lshlrev_b32_e32 v65, 16, v39
	v_lshlrev_b32_e32 v64, 16, v38
	v_and_b32_e32 v39, 0xffff0000, v39
	v_and_b32_e32 v38, 0xffff0000, v38
	s_waitcnt vmcnt(13)
	v_lshlrev_b32_e32 v70, 16, v84
	v_and_b32_e32 v71, 0xffff0000, v84
	v_lshlrev_b32_e32 v74, 16, v85
	v_and_b32_e32 v75, 0xffff0000, v85
	v_lshlrev_b32_e32 v85, 16, v87
	v_lshlrev_b32_e32 v84, 16, v86
	v_and_b32_e32 v87, 0xffff0000, v87
	v_and_b32_e32 v86, 0xffff0000, v86
	s_waitcnt vmcnt(12)
	v_lshlrev_b32_e32 v139, 16, v90
	v_mul_f32_e32 v138, v75, v75
	v_pk_mul_f32 v[142:143], v[86:87], v[86:87]
	v_mul_f32_e32 v144, v71, v71
	v_mov_b32_e32 v145, v139
	v_lshlrev_b32_e32 v136, 16, v88
	v_and_b32_e32 v137, 0xffff0000, v88
	v_lshlrev_b32_e32 v88, 16, v89
	v_and_b32_e32 v89, 0xffff0000, v89
	v_mov_b32_e32 v150, v84
	v_mov_b32_e32 v151, v86
	v_mov_b32_e32 v86, v85
	v_pk_fma_f32 v[152:153], v[74:75], v[74:75], v[138:139] op_sel_hi:[1,1,0]
	v_pk_fma_f32 v[84:85], v[84:85], v[84:85], v[142:143]
	v_pk_fma_f32 v[142:143], v[70:71], v[70:71], v[144:145] op_sel_hi:[1,1,0]
	v_and_b32_e32 v141, 0xffff0000, v90
	v_lshlrev_b32_e32 v90, 16, v91
	v_and_b32_e32 v91, 0xffff0000, v91
	v_mul_f32_e32 v146, v137, v137
	v_mul_f32_e32 v148, v89, v89
	v_mov_b32_e32 v138, v142
	v_mov_b32_e32 v144, v152
	v_mul_f32_e32 v83, v141, v141
	v_mul_f32_e32 v160, v90, v90
	v_mul_f32_e32 v162, v91, v91
	v_mov_b32_e32 v140, v139
	v_pk_fma_f32 v[146:147], v[136:137], v[136:137], v[146:147] op_sel_hi:[1,1,0]
	v_pk_fma_f32 v[148:149], v[88:89], v[88:89], v[148:149] op_sel_hi:[1,1,0]
	v_pk_add_f32 v[142:143], v[142:143], v[152:153]
	v_pk_add_f32 v[84:85], v[84:85], v[84:85] op_sel:[0,1] op_sel_hi:[1,0]
	v_pk_mul_f32 v[138:139], v[138:139], v[144:145]
	v_mov_b32_e32 v147, v160
	v_mov_b32_e32 v149, v162
	v_mov_b32_e32 v85, v83
	v_mov_b32_e32 v143, v139
	v_pk_add_f32 v[144:145], v[146:147], v[148:149]
	v_pk_add_f32 v[84:85], v[142:143], v[84:85]
	s_waitcnt vmcnt(7)
	v_lshlrev_b32_e32 v154, 16, v108
	v_pk_add_f32 v[84:85], v[84:85], v[144:145]
	v_and_b32_e32 v155, 0xffff0000, v108
	v_add_f32_e32 v83, v84, v85
	v_lshlrev_b32_e32 v108, 16, v109
	v_and_b32_e32 v109, 0xffff0000, v109
	v_add_f32_dpp v83, v83, v83 quad_perm:[1,0,3,2] row_mask:0xf bank_mask:0xf bound_ctrl:1
	v_lshlrev_b32_e32 v157, 16, v111
	v_lshlrev_b32_e32 v156, 16, v110
	v_add_f32_dpp v83, v83, v83 quad_perm:[2,3,0,1] row_mask:0xf bank_mask:0xf bound_ctrl:1
	v_and_b32_e32 v111, 0xffff0000, v111
	v_and_b32_e32 v110, 0xffff0000, v110
	v_add_f32_dpp v83, v83, v83 row_half_mirror row_mask:0xf bank_mask:0xf bound_ctrl:1
	s_waitcnt vmcnt(6)
	v_lshlrev_b32_e32 v161, 16, v114
	v_mul_f32_e32 v152, v109, v109
	v_add_f32_dpp v83, v83, v83 row_mirror row_mask:0xf bank_mask:0xf bound_ctrl:1
	v_pk_mul_f32 v[164:165], v[110:111], v[110:111]
	v_readlane_b32 s26, v83, 16
	v_readlane_b32 s27, v83, 48
	v_readlane_b32 s0, v83, 0
	v_readlane_b32 s1, v83, 32
	v_mov_b32_e32 v84, s26
	v_mov_b32_e32 v85, s27
	v_pk_add_f32 v[84:85], s[0:1], v[84:85]
	v_mul_f32_e32 v160, v155, v155
	v_add_f32_e32 v83, v84, v85
	v_fmamk_f32 v83, v83, 0x3a800000, v82
	v_rsq_f32_e32 v84, v83
	v_mov_b32_e32 v153, v161
	v_lshlrev_b32_e32 v158, 16, v112
	v_and_b32_e32 v159, 0xffff0000, v112
	v_pk_mul_f32 v[70:71], v[84:85], v[70:71] op_sel_hi:[0,1]
	v_pk_mul_f32 v[142:143], v[84:85], v[150:151] op_sel_hi:[0,1]
	v_pk_mul_f32 v[86:87], v[84:85], v[86:87] op_sel_hi:[0,1]
	v_pk_mul_f32 v[74:75], v[84:85], v[74:75] op_sel_hi:[0,1]
	v_pk_fma_f32 v[24:25], v[70:71], v[186:187], v[92:93]
	v_pk_fma_f32 v[70:71], v[86:87], v[184:185], v[98:99]
	v_pk_fma_f32 v[22:23], v[142:143], v[182:183], v[96:97]
	v_pk_mul_f32 v[136:137], v[84:85], v[136:137] op_sel_hi:[0,1]
	v_pk_mul_f32 v[88:89], v[84:85], v[88:89] op_sel_hi:[0,1]
	v_pk_mul_f32 v[140:141], v[84:85], v[140:141] op_sel_hi:[0,1]
	v_pk_mul_f32 v[84:85], v[84:85], v[90:91] op_sel_hi:[0,1]
	v_pk_fma_f32 v[26:27], v[74:75], v[188:189], v[94:95]
	v_cvt_pk_bf16_f32 v20, v24, v25
	v_pk_fma_f32 v[34:35], v[88:89], v[196:197], v[102:103]
	v_cvt_pk_bf16_f32 v21, v26, v27
	v_cvt_pk_bf16_f32 v22, v22, v23
	v_cvt_pk_bf16_f32 v23, v70, v71
	v_pk_fma_f32 v[32:33], v[136:137], v[194:195], v[100:101]
	v_pk_fma_f32 v[30:31], v[84:85], v[192:193], v[106:107]
	v_pk_fma_f32 v[28:29], v[140:141], v[190:191], v[104:105]
	global_store_dwordx4 v[72:73], v[20:23], off offset:-1024
	v_lshlrev_b32_e32 v112, 16, v113
	v_and_b32_e32 v113, 0xffff0000, v113
	v_cvt_pk_bf16_f32 v20, v32, v33
	v_cvt_pk_bf16_f32 v21, v34, v35
	v_cvt_pk_bf16_f32 v22, v28, v29
	v_cvt_pk_bf16_f32 v23, v30, v31
	global_store_dwordx4 v[72:73], v[20:23], off
	s_nop 0
	v_mov_b32_e32 v170, v156
	v_mov_b32_e32 v171, v110
	v_mov_b32_e32 v110, v157
	v_pk_fma_f32 v[146:147], v[108:109], v[108:109], v[152:153] op_sel_hi:[1,1,0]
	v_pk_fma_f32 v[148:149], v[156:157], v[156:157], v[164:165]
	v_pk_fma_f32 v[156:157], v[154:155], v[154:155], v[160:161] op_sel_hi:[1,1,0]
	v_and_b32_e32 v163, 0xffff0000, v114
	v_lshlrev_b32_e32 v114, 16, v115
	v_and_b32_e32 v115, 0xffff0000, v115
	v_mul_f32_e32 v166, v159, v159
	v_mul_f32_e32 v168, v113, v113
	v_mov_b32_e32 v160, v156
	v_mov_b32_e32 v152, v146
	v_mul_f32_e32 v176, v163, v163
	v_mul_f32_e32 v178, v114, v114
	v_mul_f32_e32 v180, v115, v115
	v_pk_fma_f32 v[164:165], v[158:159], v[158:159], v[166:167] op_sel_hi:[1,1,0]
	v_pk_fma_f32 v[166:167], v[112:113], v[112:113], v[168:169] op_sel_hi:[1,1,0]
	v_pk_add_f32 v[138:139], v[156:157], v[146:147]
	v_pk_add_f32 v[146:147], v[148:149], v[148:149] op_sel:[0,1] op_sel_hi:[1,0]
	v_pk_mul_f32 v[72:73], v[160:161], v[152:153]
	v_mov_b32_e32 v165, v178
	v_mov_b32_e32 v167, v180
	v_mov_b32_e32 v147, v176
	v_mov_b32_e32 v139, v73
	v_pk_add_f32 v[74:75], v[164:165], v[166:167]
	v_pk_add_f32 v[72:73], v[138:139], v[146:147]
	v_mov_b32_e32 v162, v161
	v_pk_add_f32 v[72:73], v[72:73], v[74:75]
	s_waitcnt vmcnt(3)
	v_lshlrev_b32_e32 v168, 16, v128
	v_add_f32_e32 v71, v72, v73
	v_and_b32_e32 v169, 0xffff0000, v128
	v_lshlrev_b32_e32 v128, 16, v129
	v_add_f32_dpp v71, v71, v71 quad_perm:[1,0,3,2] row_mask:0xf bank_mask:0xf bound_ctrl:1
	v_and_b32_e32 v129, 0xffff0000, v129
	v_lshlrev_b32_e32 v173, 16, v131
	v_add_f32_dpp v71, v71, v71 quad_perm:[2,3,0,1] row_mask:0xf bank_mask:0xf bound_ctrl:1
	v_lshlrev_b32_e32 v172, 16, v130
	v_and_b32_e32 v131, 0xffff0000, v131
	v_add_f32_dpp v71, v71, v71 row_half_mirror row_mask:0xf bank_mask:0xf bound_ctrl:1
	v_and_b32_e32 v130, 0xffff0000, v130
	s_waitcnt vmcnt(2)
	v_and_b32_e32 v175, 0xffff0000, v132
	v_add_f32_dpp v71, v71, v71 row_mirror row_mask:0xf bank_mask:0xf bound_ctrl:1
	v_lshlrev_b32_e32 v177, 16, v134
	v_readlane_b32 s26, v71, 16
	v_readlane_b32 s27, v71, 48
	v_readlane_b32 s0, v71, 0
	v_readlane_b32 s1, v71, 32
	v_mov_b32_e32 v72, s26
	v_mov_b32_e32 v73, s27
	v_pk_add_f32 v[72:73], s[0:1], v[72:73]
	v_mul_f32_e32 v148, v129, v129
	v_add_f32_e32 v71, v72, v73
	v_fmamk_f32 v71, v71, 0x3a800000, v82
	v_rsq_f32_e32 v72, v71
	v_mul_f32_e32 v70, v169, v169
	v_lshlrev_b32_e32 v174, 16, v132
	v_lshlrev_b32_e32 v132, 16, v133
	v_pk_mul_f32 v[74:75], v[72:73], v[154:155] op_sel_hi:[0,1]
	v_pk_mul_f32 v[84:85], v[72:73], v[108:109] op_sel_hi:[0,1]
	v_pk_mul_f32 v[86:87], v[72:73], v[170:171] op_sel_hi:[0,1]
	v_pk_mul_f32 v[88:89], v[72:73], v[110:111] op_sel_hi:[0,1]
	v_pk_mul_f32 v[90:91], v[72:73], v[158:159] op_sel_hi:[0,1]
	v_pk_mul_f32 v[92:93], v[72:73], v[112:113] op_sel_hi:[0,1]
	v_pk_mul_f32 v[94:95], v[72:73], v[162:163] op_sel_hi:[0,1]
	v_pk_mul_f32 v[72:73], v[72:73], v[114:115] op_sel_hi:[0,1]
	v_and_b32_e32 v133, 0xffff0000, v133
	v_pk_mul_f32 v[156:157], v[130:131], v[130:131]
	v_pk_fma_f32 v[70:71], v[168:169], v[168:169], v[70:71] op_sel_hi:[1,1,0]
	v_and_b32_e32 v179, 0xffff0000, v134
	v_lshlrev_b32_e32 v134, 16, v135
	v_and_b32_e32 v135, 0xffff0000, v135
	v_mov_b32_e32 v176, v70
	v_mul_f32_e32 v83, v179, v179
	v_mul_f32_e32 v96, v134, v134
	v_mul_f32_e32 v97, v135, v135
	v_pk_fma_f32 v[22:23], v[84:85], v[188:189], v[118:119]
	v_pk_fma_f32 v[20:21], v[74:75], v[186:187], v[116:117]
	v_pk_fma_f32 v[26:27], v[88:89], v[184:185], v[68:69]
	v_pk_fma_f32 v[24:25], v[86:87], v[182:183], v[66:67]
	v_cvt_pk_bf16_f32 v20, v20, v21
	v_cvt_pk_bf16_f32 v21, v22, v23
	v_pk_fma_f32 v[30:31], v[92:93], v[196:197], v[122:123]
	v_cvt_pk_bf16_f32 v22, v24, v25
	v_cvt_pk_bf16_f32 v23, v26, v27
	v_pk_fma_f32 v[28:29], v[90:91], v[194:195], v[120:121]
	v_pk_fma_f32 v[34:35], v[72:73], v[192:193], v[126:127]
	v_pk_fma_f32 v[32:33], v[94:95], v[190:191], v[124:125]
	global_store_dwordx4 v[76:77], v[20:23], off offset:-1024
	v_mov_b32_e32 v67, v177
	v_mul_f32_e32 v66, v175, v175
	v_cvt_pk_bf16_f32 v20, v28, v29
	v_cvt_pk_bf16_f32 v21, v30, v31
	v_cvt_pk_bf16_f32 v22, v32, v33
	v_cvt_pk_bf16_f32 v23, v34, v35
	global_store_dwordx4 v[76:77], v[20:23], off
	s_nop 0
	v_pk_fma_f32 v[74:75], v[128:129], v[128:129], v[148:149] op_sel_hi:[1,1,0]
	v_mul_f32_e32 v68, v133, v133
	v_pk_fma_f32 v[76:77], v[172:173], v[172:173], v[156:157]
	v_pk_fma_f32 v[84:85], v[174:175], v[174:175], v[66:67] op_sel_hi:[1,1,0]
	v_mov_b32_e32 v66, v74
	v_pk_fma_f32 v[68:69], v[132:133], v[132:133], v[68:69] op_sel_hi:[1,1,0]
	v_pk_add_f32 v[70:71], v[70:71], v[74:75]
	v_pk_add_f32 v[74:75], v[76:77], v[76:77] op_sel:[0,1] op_sel_hi:[1,0]
	v_pk_mul_f32 v[66:67], v[176:177], v[66:67]
	v_mov_b32_e32 v85, v96
	v_mov_b32_e32 v69, v97
	v_mov_b32_e32 v75, v83
	v_mov_b32_e32 v71, v67
	v_pk_add_f32 v[68:69], v[84:85], v[68:69]
	v_pk_add_f32 v[66:67], v[70:71], v[74:75]
	v_mov_b32_e32 v72, v172
	v_pk_add_f32 v[66:67], v[66:67], v[68:69]
	v_mov_b32_e32 v73, v130
	v_add_f32_e32 v66, v66, v67
	v_mov_b32_e32 v130, v173
	v_mov_b32_e32 v178, v177
	v_add_f32_dpp v66, v66, v66 quad_perm:[1,0,3,2] row_mask:0xf bank_mask:0xf bound_ctrl:1
	s_nop 1
	v_add_f32_dpp v66, v66, v66 quad_perm:[2,3,0,1] row_mask:0xf bank_mask:0xf bound_ctrl:1
	s_nop 1
	v_add_f32_dpp v66, v66, v66 row_half_mirror row_mask:0xf bank_mask:0xf bound_ctrl:1
	s_nop 1
	v_add_f32_dpp v66, v66, v66 row_mirror row_mask:0xf bank_mask:0xf bound_ctrl:1
	s_nop 0
	v_readlane_b32 s26, v66, 16
	v_readlane_b32 s27, v66, 48
	v_readlane_b32 s0, v66, 0
	v_readlane_b32 s1, v66, 32
	v_mov_b32_e32 v66, s26
	v_mov_b32_e32 v67, s27
	v_pk_add_f32 v[66:67], s[0:1], v[66:67]
	s_nop 0
	v_add_f32_e32 v66, v66, v67
	v_fmamk_f32 v66, v66, 0x3a800000, v82
	v_rsq_f32_e32 v66, v66
	s_nop 0
	v_pk_mul_f32 v[68:69], v[66:67], v[168:169] op_sel_hi:[0,1]
	v_pk_mul_f32 v[70:71], v[66:67], v[128:129] op_sel_hi:[0,1]
	v_pk_mul_f32 v[72:73], v[66:67], v[72:73] op_sel_hi:[0,1]
	v_pk_mul_f32 v[74:75], v[66:67], v[130:131] op_sel_hi:[0,1]
	v_pk_mul_f32 v[76:77], v[66:67], v[174:175] op_sel_hi:[0,1]
	v_pk_mul_f32 v[84:85], v[66:67], v[132:133] op_sel_hi:[0,1]
	v_pk_mul_f32 v[86:87], v[66:67], v[178:179] op_sel_hi:[0,1]
	v_pk_mul_f32 v[66:67], v[66:67], v[134:135] op_sel_hi:[0,1]
	v_pk_fma_f32 v[22:23], v[70:71], v[188:189], v[54:55]
	v_pk_fma_f32 v[20:21], v[68:69], v[186:187], v[52:53]
	v_pk_fma_f32 v[26:27], v[74:75], v[184:185], v[50:51]
	v_pk_fma_f32 v[24:25], v[72:73], v[182:183], v[48:49]
	v_cvt_pk_bf16_f32 v20, v20, v21
	v_cvt_pk_bf16_f32 v21, v22, v23
	v_pk_fma_f32 v[30:31], v[84:85], v[196:197], v[46:47]
	v_cvt_pk_bf16_f32 v22, v24, v25
	v_cvt_pk_bf16_f32 v23, v26, v27
	v_pk_fma_f32 v[28:29], v[76:77], v[194:195], v[44:45]
	v_pk_fma_f32 v[34:35], v[66:67], v[192:193], v[42:43]
	v_pk_fma_f32 v[32:33], v[86:87], v[190:191], v[40:41]
	global_store_dwordx4 v[78:79], v[20:23], off offset:-1024
	v_lshlrev_b32_e32 v43, 16, v18
	v_mul_f32_e32 v42, v37, v37
	v_cvt_pk_bf16_f32 v20, v28, v29
	v_cvt_pk_bf16_f32 v21, v30, v31
	v_cvt_pk_bf16_f32 v22, v32, v33
	v_cvt_pk_bf16_f32 v23, v34, v35
	global_store_dwordx4 v[78:79], v[20:23], off
	s_nop 0
	v_pk_mul_f32 v[46:47], v[38:39], v[38:39]
	v_mul_f32_e32 v48, v63, v63
	v_mov_b32_e32 v49, v43
	v_lshlrev_b32_e32 v40, 16, v16
	v_and_b32_e32 v41, 0xffff0000, v16
	v_lshlrev_b32_e32 v16, 16, v17
	v_and_b32_e32 v17, 0xffff0000, v17
	v_mov_b32_e32 v54, v64
	v_mov_b32_e32 v55, v38
	v_mov_b32_e32 v38, v65
	v_pk_fma_f32 v[66:67], v[36:37], v[36:37], v[42:43] op_sel_hi:[1,1,0]
	v_pk_fma_f32 v[46:47], v[64:65], v[64:65], v[46:47]
	v_pk_fma_f32 v[64:65], v[62:63], v[62:63], v[48:49] op_sel_hi:[1,1,0]
	v_and_b32_e32 v45, 0xffff0000, v18
	v_lshlrev_b32_e32 v18, 16, v19
	v_and_b32_e32 v19, 0xffff0000, v19
	v_mul_f32_e32 v50, v41, v41
	v_mul_f32_e32 v52, v17, v17
	v_mov_b32_e32 v42, v64
	v_mov_b32_e32 v48, v66
	v_mul_f32_e32 v68, v45, v45
	v_mul_f32_e32 v69, v18, v18
	v_mul_f32_e32 v70, v19, v19
	v_mov_b32_e32 v44, v43
	v_pk_fma_f32 v[50:51], v[40:41], v[40:41], v[50:51] op_sel_hi:[1,1,0]
	v_pk_fma_f32 v[52:53], v[16:17], v[16:17], v[52:53] op_sel_hi:[1,1,0]
	v_pk_add_f32 v[64:65], v[64:65], v[66:67]
	v_pk_add_f32 v[46:47], v[46:47], v[46:47] op_sel:[0,1] op_sel_hi:[1,0]
	v_pk_mul_f32 v[42:43], v[42:43], v[48:49]
	v_mov_b32_e32 v51, v69
	v_mov_b32_e32 v53, v70
	v_mov_b32_e32 v47, v68
	v_mov_b32_e32 v65, v43
	v_pk_add_f32 v[48:49], v[50:51], v[52:53]
	v_pk_add_f32 v[42:43], v[64:65], v[46:47]
	s_nop 0
	v_pk_add_f32 v[42:43], v[42:43], v[48:49]
	s_nop 0
	v_add_f32_e32 v42, v42, v43
	s_nop 1
	v_add_f32_dpp v42, v42, v42 quad_perm:[1,0,3,2] row_mask:0xf bank_mask:0xf bound_ctrl:1
	s_nop 1
	v_add_f32_dpp v42, v42, v42 quad_perm:[2,3,0,1] row_mask:0xf bank_mask:0xf bound_ctrl:1
	s_nop 1
	v_add_f32_dpp v42, v42, v42 row_half_mirror row_mask:0xf bank_mask:0xf bound_ctrl:1
	s_nop 1
	v_add_f32_dpp v42, v42, v42 row_mirror row_mask:0xf bank_mask:0xf bound_ctrl:1
	s_nop 0
	v_readlane_b32 s26, v42, 16
	v_readlane_b32 s27, v42, 48
	v_readlane_b32 s0, v42, 0
	v_readlane_b32 s1, v42, 32
	v_mov_b32_e32 v42, s26
	v_mov_b32_e32 v43, s27
	v_pk_add_f32 v[42:43], s[0:1], v[42:43]
	s_nop 0
	v_add_f32_e32 v42, v42, v43
	v_fmamk_f32 v42, v42, 0x3a800000, v82
	v_rsq_f32_e32 v42, v42
	s_nop 0
	v_pk_mul_f32 v[46:47], v[42:43], v[62:63] op_sel_hi:[0,1]
	v_pk_mul_f32 v[36:37], v[42:43], v[36:37] op_sel_hi:[0,1]
	v_pk_mul_f32 v[48:49], v[42:43], v[54:55] op_sel_hi:[0,1]
	v_pk_mul_f32 v[38:39], v[42:43], v[38:39] op_sel_hi:[0,1]
	v_pk_mul_f32 v[16:17], v[42:43], v[16:17] op_sel_hi:[0,1]
	v_pk_mul_f32 v[44:45], v[42:43], v[44:45] op_sel_hi:[0,1]
	v_pk_mul_f32 v[18:19], v[42:43], v[18:19] op_sel_hi:[0,1]
	v_pk_mul_f32 v[40:41], v[42:43], v[40:41] op_sel_hi:[0,1]
	v_pk_fma_f32 v[14:15], v[36:37], v[188:189], v[14:15]
	v_pk_fma_f32 v[12:13], v[46:47], v[186:187], v[12:13]
	v_pk_fma_f32 v[6:7], v[38:39], v[184:185], v[6:7]
	v_pk_fma_f32 v[4:5], v[48:49], v[182:183], v[4:5]
	v_pk_fma_f32 v[10:11], v[16:17], v[196:197], v[10:11]
	v_pk_fma_f32 v[16:17], v[18:19], v[192:193], v[2:3]
	v_pk_fma_f32 v[18:19], v[44:45], v[190:191], v[0:1]
	v_cvt_pk_bf16_f32 v0, v12, v13
	v_cvt_pk_bf16_f32 v1, v14, v15
	v_cvt_pk_bf16_f32 v2, v4, v5
	v_cvt_pk_bf16_f32 v3, v6, v7
	v_pk_fma_f32 v[8:9], v[40:41], v[194:195], v[8:9]
	global_store_dwordx4 v[80:81], v[0:3], off offset:-1024
	s_nop 1
	v_cvt_pk_bf16_f32 v0, v8, v9
	v_cvt_pk_bf16_f32 v1, v10, v11
	v_cvt_pk_bf16_f32 v2, v18, v19
	v_cvt_pk_bf16_f32 v3, v16, v17
	global_store_dwordx4 v[80:81], v[0:3], off
	s_cbranch_scc0 .LBB0_1031

.LBB0_1612:
	s_or_b64 exec, exec, s[0:1]
	s_waitcnt lgkmcnt(0)
	v_mov_b32_e32 v0, v226
	s_barrier
	s_nop 0
	v_readfirstlane_b32 s0, v0
	s_ashr_i32 s0, s0, 6
	s_add_i32 s6, s85, s0
	s_cmp_lt_i32 s6, s73
	s_cbranch_scc1 .LBB0_1615
	v_lshlrev_b32_e32 v1, 5, v0
	v_readlane_b32 s8, v254, 46
	v_and_b32_e32 v2, 0x7e0, v1
	v_mov_b32_e32 v3, 0
	v_readlane_b32 s14, v254, 52
	v_readlane_b32 s15, v254, 53
	v_readlane_b32 s10, v254, 48
	v_readlane_b32 s11, v254, 49
	v_lshl_add_u64 v[2:3], s[14:15], 0, v[2:3]
	s_mov_b64 s[0:1], 0x1000
	s_ashr_i32 s7, s6, 31
	v_readlane_b32 s9, v254, 47
	v_lshl_add_u64 v[24:25], v[2:3], 0, s[0:1]
	s_lshl_b64 s[0:1], s[6:7], 11
	v_and_b32_e32 v0, 63, v0
	s_mov_b32 s10, 0xffe00000
	v_lshl_or_b32 v26, v0, 4, s0
	v_mov_b32_e32 v27, s1
	s_lshl_b64 s[8:9], s[6:7], 2
	v_mov_b32_e32 v36, 0x358637bd
	v_mov_b32_e32 v37, 0x1e00000
	s_mov_b32 s4, 0xfa00000
	s_mov_b32 s5, 0xfa80000
	s_mov_b32 s7, 0xfb00000
	s_mov_b32 s14, 0xfb80000
	s_mov_b32 s11, -1
	v_readlane_b32 s12, v254, 50
	v_readlane_b32 s13, v254, 51
	v_readlane_b32 s16, v254, 54
	v_readlane_b32 s17, v254, 55
	v_readlane_b32 s18, v254, 56
	v_readlane_b32 s19, v254, 57
	v_readlane_b32 s20, v254, 58
	v_readlane_b32 s21, v254, 59
	v_readlane_b32 s22, v254, 60
	v_readlane_b32 s23, v254, 61
	global_load_dwordx4 v[184:187], v[24:25], off offset:16
	global_load_dwordx4 v[188:191], v[24:25], off
	global_load_dwordx4 v[192:195], v[24:25], off offset:2064
	global_load_dwordx4 v[196:199], v[24:25], off offset:2048
	s_waitcnt vmcnt(0)
.LBB0_1614:
	v_lshl_add_u64 v[16:17], s[92:93], 0, v[26:27]
	v_add_co_u32_e32 v18, vcc, 0x7900000, v16
	s_add_u32 s12, s92, s8
	s_nop 0
	v_addc_co_u32_e32 v19, vcc, 0, v17, vcc
	s_addc_u32 s13, s93, s9
	v_add_co_u32_e32 v20, vcc, 0x37f00000, v16
	global_load_dword v94, v37, s[12:13]
	global_load_dwordx4 v[38:41], v[18:19], off nt
	global_load_dwordx4 v[42:45], v[18:19], off offset:1024 nt
	v_addc_co_u32_e32 v21, vcc, 0, v17, vcc
	v_add_co_u32_e32 v18, vcc, 0x7980000, v16
	global_load_dwordx4 v[46:49], v[20:21], off nt
	global_load_dwordx4 v[50:53], v[20:21], off offset:1024 nt
	v_addc_co_u32_e32 v19, vcc, 0, v17, vcc
	global_load_dwordx4 v[54:57], v[18:19], off nt
	global_load_dwordx4 v[58:61], v[18:19], off offset:1024 nt
	v_add_co_u32_e32 v20, vcc, 0x37f80000, v16
	v_add_co_u32_e64 v34, s[0:1], s4, v16
	s_nop 0
	v_addc_co_u32_e32 v21, vcc, 0, v17, vcc
	v_add_co_u32_e32 v18, vcc, 0x7a00000, v16
	v_addc_co_u32_e64 v35, s[0:1], 0, v17, s[0:1]
	s_nop 0
	v_addc_co_u32_e32 v19, vcc, 0, v17, vcc
	global_load_dwordx4 v[62:65], v[20:21], off nt
	global_load_dwordx4 v[66:69], v[20:21], off offset:1024 nt
	v_add_co_u32_e32 v20, vcc, 0x38000000, v16
	v_add_co_u32_e64 v32, s[0:1], s5, v16
	s_nop 0
	v_addc_co_u32_e32 v21, vcc, 0, v17, vcc
	v_addc_co_u32_e64 v33, s[0:1], 0, v17, s[0:1]
	global_load_dwordx4 v[70:73], v[18:19], off nt
	global_load_dwordx4 v[74:77], v[18:19], off offset:1024 nt
	v_add_co_u32_e32 v18, vcc, 0x7a80000, v16
	v_add_co_u32_e64 v30, s[0:1], s7, v16
	s_nop 0
	v_addc_co_u32_e32 v19, vcc, 0, v17, vcc
	v_addc_co_u32_e64 v31, s[0:1], 0, v17, s[0:1]
	v_add_co_u32_e32 v96, vcc, 0x38080000, v16
	v_add_co_u32_e64 v28, s[0:1], s14, v16
	s_nop 0
	v_addc_co_u32_e32 v97, vcc, 0, v17, vcc
	v_addc_co_u32_e64 v29, s[0:1], 0, v17, s[0:1]
	global_load_dwordx4 v[78:81], v[20:21], off nt
	global_load_dwordx4 v[82:85], v[20:21], off offset:1024 nt
	global_load_dwordx4 v[86:89], v[18:19], off nt
	global_load_dwordx4 v[90:93], v[18:19], off offset:1024 nt
	s_nop 0
	global_load_dwordx4 v[20:23], v[96:97], off nt
	global_load_dwordx4 v[16:19], v[96:97], off offset:1024 nt
	s_addk_i32 s6, 0xfc00
	s_add_u32 s8, s8, 0xfffff000
	s_addc_u32 s9, s9, -1
	v_lshl_add_u64 v[26:27], v[26:27], 0, s[10:11]
	s_cmp_lt_i32 s6, s73
	s_waitcnt vmcnt(15)
	v_lshlrev_b32_e32 v96, 16, v38
	v_and_b32_e32 v97, 0xffff0000, v38
	v_lshlrev_b32_e32 v38, 16, v39
	v_and_b32_e32 v39, 0xffff0000, v39
	v_lshlrev_b32_e32 v99, 16, v41
	v_lshlrev_b32_e32 v98, 16, v40
	v_and_b32_e32 v41, 0xffff0000, v41
	v_and_b32_e32 v40, 0xffff0000, v40
	s_waitcnt vmcnt(14)
	v_lshlrev_b32_e32 v95, 16, v44
	v_lshlrev_b32_e32 v100, 16, v42
	v_and_b32_e32 v101, 0xffff0000, v42
	v_lshlrev_b32_e32 v42, 16, v43
	v_and_b32_e32 v43, 0xffff0000, v43
	v_mul_f32_e32 v104, v39, v39
	v_pk_mul_f32 v[106:107], v[40:41], v[40:41]
	v_mul_f32_e32 v108, v97, v97
	v_mov_b32_e32 v105, v95
	v_and_b32_e32 v103, 0xffff0000, v44
	v_lshlrev_b32_e32 v44, 16, v45
	v_and_b32_e32 v45, 0xffff0000, v45
	v_mul_f32_e32 v110, v101, v101
	v_mul_f32_e32 v112, v43, v43
	s_waitcnt vmcnt(13)
	v_lshlrev_b32_e32 v114, 16, v46
	v_and_b32_e32 v115, 0xffff0000, v46
	v_lshlrev_b32_e32 v46, 16, v47
	v_and_b32_e32 v47, 0xffff0000, v47
	v_lshlrev_b32_e32 v116, 16, v48
	v_and_b32_e32 v117, 0xffff0000, v48
	v_lshlrev_b32_e32 v48, 16, v49
	v_and_b32_e32 v49, 0xffff0000, v49
	v_mov_b32_e32 v118, v98
	v_mov_b32_e32 v119, v40
	v_mov_b32_e32 v40, v99
	s_waitcnt vmcnt(12)
	v_lshlrev_b32_e32 v120, 16, v50
	v_and_b32_e32 v121, 0xffff0000, v50
	v_lshlrev_b32_e32 v50, 16, v51
	v_and_b32_e32 v51, 0xffff0000, v51
	v_lshlrev_b32_e32 v122, 16, v52
	v_and_b32_e32 v123, 0xffff0000, v52
	v_lshlrev_b32_e32 v52, 16, v53
	v_and_b32_e32 v53, 0xffff0000, v53
	v_pk_fma_f32 v[124:125], v[38:39], v[38:39], v[104:105] op_sel_hi:[1,1,0]
	v_pk_fma_f32 v[98:99], v[98:99], v[98:99], v[106:107]
	v_pk_fma_f32 v[106:107], v[96:97], v[96:97], v[108:109] op_sel_hi:[1,1,0]
	v_mul_f32_e32 v130, v44, v44
	v_mul_f32_e32 v132, v45, v45
	v_pk_fma_f32 v[108:109], v[100:101], v[100:101], v[110:111] op_sel_hi:[1,1,0]
	v_pk_fma_f32 v[110:111], v[42:43], v[42:43], v[112:113] op_sel_hi:[1,1,0]
	v_pk_mul_f32 v[112:113], v[94:95], v[114:115] op_sel_hi:[0,1]
	v_pk_mul_f32 v[46:47], v[94:95], v[46:47] op_sel_hi:[0,1]
	v_pk_mul_f32 v[114:115], v[94:95], v[116:117] op_sel_hi:[0,1]
	v_pk_mul_f32 v[48:49], v[94:95], v[48:49] op_sel_hi:[0,1]
	v_pk_mul_f32 v[116:117], v[94:95], v[120:121] op_sel_hi:[0,1]
	v_pk_mul_f32 v[50:51], v[94:95], v[50:51] op_sel_hi:[0,1]
	v_pk_mul_f32 v[120:121], v[94:95], v[122:123] op_sel_hi:[0,1]
	v_pk_mul_f32 v[52:53], v[94:95], v[52:53] op_sel_hi:[0,1]
	s_waitcnt vmcnt(11)
	v_lshlrev_b32_e32 v122, 16, v54
	v_and_b32_e32 v123, 0xffff0000, v54
	v_lshlrev_b32_e32 v54, 16, v55
	v_and_b32_e32 v55, 0xffff0000, v55
	v_lshlrev_b32_e32 v127, 16, v57
	v_lshlrev_b32_e32 v126, 16, v56
	v_and_b32_e32 v57, 0xffff0000, v57
	v_and_b32_e32 v56, 0xffff0000, v56
	s_waitcnt vmcnt(10)
	v_lshlrev_b32_e32 v131, 16, v60
	v_mov_b32_e32 v94, v106
	v_mov_b32_e32 v104, v124
	v_mul_f32_e32 v137, v103, v103
	v_mov_b32_e32 v102, v95
	v_pk_add_f32 v[106:107], v[106:107], v[124:125]
	v_pk_add_f32 v[98:99], v[98:99], v[98:99] op_sel:[0,1] op_sel_hi:[1,0]
	v_mov_b32_e32 v109, v130
	v_mov_b32_e32 v111, v132
	v_mul_f32_e32 v124, v55, v55
	v_pk_mul_f32 v[134:135], v[56:57], v[56:57]
	v_mul_f32_e32 v130, v123, v123
	v_mov_b32_e32 v125, v131
	v_pk_mul_f32 v[94:95], v[94:95], v[104:105]
	v_lshlrev_b32_e32 v128, 16, v58
	v_and_b32_e32 v129, 0xffff0000, v58
	v_lshlrev_b32_e32 v58, 16, v59
	v_and_b32_e32 v59, 0xffff0000, v59
	v_mov_b32_e32 v144, v126
	v_mov_b32_e32 v145, v56
	v_mov_b32_e32 v56, v127
	v_mov_b32_e32 v99, v137
	v_pk_add_f32 v[104:105], v[108:109], v[110:111]
	v_pk_fma_f32 v[108:109], v[54:55], v[54:55], v[124:125] op_sel_hi:[1,1,0]
	v_pk_fma_f32 v[110:111], v[126:127], v[126:127], v[134:135]
	v_pk_fma_f32 v[126:127], v[122:123], v[122:123], v[130:131] op_sel_hi:[1,1,0]
	v_mov_b32_e32 v107, v95
	v_and_b32_e32 v133, 0xffff0000, v60
	v_lshlrev_b32_e32 v60, 16, v61
	v_and_b32_e32 v61, 0xffff0000, v61
	v_mul_f32_e32 v136, v129, v129
	v_mul_f32_e32 v138, v59, v59
	v_mov_b32_e32 v130, v126
	v_mov_b32_e32 v124, v108
	v_pk_add_f32 v[98:99], v[106:107], v[98:99]
	v_mul_f32_e32 v159, v133, v133
	v_mul_f32_e32 v154, v60, v60
	v_mul_f32_e32 v156, v61, v61
	v_pk_fma_f32 v[134:135], v[128:129], v[128:129], v[136:137] op_sel_hi:[1,1,0]
	v_pk_fma_f32 v[136:137], v[58:59], v[58:59], v[138:139] op_sel_hi:[1,1,0]
	v_pk_add_f32 v[94:95], v[126:127], v[108:109]
	v_pk_add_f32 v[108:109], v[110:111], v[110:111] op_sel:[0,1] op_sel_hi:[1,0]
	v_pk_mul_f32 v[106:107], v[130:131], v[124:125]
	v_pk_add_f32 v[98:99], v[98:99], v[104:105]
	v_mov_b32_e32 v135, v154
	v_mov_b32_e32 v137, v156
	v_mov_b32_e32 v109, v159
	v_mov_b32_e32 v95, v107
	v_add_f32_e32 v98, v98, v99
	v_pk_add_f32 v[124:125], v[134:135], v[136:137]
	v_pk_add_f32 v[94:95], v[94:95], v[108:109]
	v_add_f32_dpp v98, v98, v98 quad_perm:[1,0,3,2] row_mask:0xf bank_mask:0xf bound_ctrl:1
	v_pk_add_f32 v[94:95], v[94:95], v[124:125]
	s_waitcnt vmcnt(9)
	v_lshlrev_b32_e32 v140, 16, v62
	v_add_f32_dpp v98, v98, v98 quad_perm:[2,3,0,1] row_mask:0xf bank_mask:0xf bound_ctrl:1
	v_add_f32_e32 v94, v94, v95
	v_and_b32_e32 v141, 0xffff0000, v62
	v_add_f32_dpp v95, v98, v98 row_half_mirror row_mask:0xf bank_mask:0xf bound_ctrl:1
	v_add_f32_dpp v94, v94, v94 quad_perm:[1,0,3,2] row_mask:0xf bank_mask:0xf bound_ctrl:1
	v_lshlrev_b32_e32 v62, 16, v63
	v_add_f32_dpp v95, v95, v95 row_mirror row_mask:0xf bank_mask:0xf bound_ctrl:1
	v_add_f32_dpp v94, v94, v94 quad_perm:[2,3,0,1] row_mask:0xf bank_mask:0xf bound_ctrl:1
	v_readlane_b32 s15, v95, 16
	v_readlane_b32 s16, v95, 48
	v_readlane_b32 s0, v95, 0
	v_readlane_b32 s1, v95, 32
	v_add_f32_dpp v98, v94, v94 row_half_mirror row_mask:0xf bank_mask:0xf bound_ctrl:1
	v_mov_b32_e32 v94, s15
	v_mov_b32_e32 v95, s16
	v_add_f32_dpp v98, v98, v98 row_mirror row_mask:0xf bank_mask:0xf bound_ctrl:1
	v_pk_add_f32 v[94:95], s[0:1], v[94:95]
	v_readlane_b32 s0, v98, 0
	v_readlane_b32 s15, v98, 16
	v_readlane_b32 s1, v98, 32
	v_readlane_b32 s16, v98, 48
	v_add_f32_e32 v98, v94, v95
	v_fmamk_f32 v98, v98, 0x3a800000, v36
	v_rsq_f32_e32 v98, v98
	v_mov_b32_e32 v94, s15
	v_mov_b32_e32 v95, s16
	v_pk_add_f32 v[94:95], s[0:1], v[94:95]
	v_pk_mul_f32 v[38:39], v[98:99], v[38:39] op_sel_hi:[0,1]
	v_pk_mul_f32 v[108:109], v[98:99], v[118:119] op_sel_hi:[0,1]
	v_pk_mul_f32 v[40:41], v[98:99], v[40:41] op_sel_hi:[0,1]
	v_pk_mul_f32 v[96:97], v[98:99], v[96:97] op_sel_hi:[0,1]
	v_pk_fma_f32 v[6:7], v[38:39], v[190:191], v[46:47]
	v_pk_fma_f32 v[38:39], v[40:41], v[186:187], v[48:49]
	v_pk_fma_f32 v[2:3], v[108:109], v[184:185], v[114:115]
	v_pk_mul_f32 v[100:101], v[98:99], v[100:101] op_sel_hi:[0,1]
	v_pk_mul_f32 v[42:43], v[98:99], v[42:43] op_sel_hi:[0,1]
	v_pk_mul_f32 v[102:103], v[98:99], v[102:103] op_sel_hi:[0,1]
	v_pk_mul_f32 v[44:45], v[98:99], v[44:45] op_sel_hi:[0,1]
	v_pk_fma_f32 v[4:5], v[96:97], v[188:189], v[112:113]
	v_pk_fma_f32 v[14:15], v[42:43], v[198:199], v[50:51]
	v_cvt_pk_bf16_f32 v0, v4, v5
	v_cvt_pk_bf16_f32 v1, v6, v7
	v_cvt_pk_bf16_f32 v2, v2, v3
	v_cvt_pk_bf16_f32 v3, v38, v39
	v_pk_fma_f32 v[12:13], v[100:101], v[196:197], v[116:117]
	v_pk_fma_f32 v[10:11], v[44:45], v[194:195], v[52:53]
	v_pk_fma_f32 v[8:9], v[102:103], v[192:193], v[120:121]
	global_store_dwordx4 v[34:35], v[0:3], off
	v_and_b32_e32 v63, 0xffff0000, v63
	v_lshlrev_b32_e32 v142, 16, v64
	v_cvt_pk_bf16_f32 v0, v12, v13
	v_cvt_pk_bf16_f32 v1, v14, v15
	v_cvt_pk_bf16_f32 v2, v8, v9
	v_cvt_pk_bf16_f32 v3, v10, v11
	global_store_dwordx4 v[34:35], v[0:3], off offset:1024
	global_load_dword v34, v37, s[12:13] offset:1024
	s_nop 0
	v_add_f32_e32 v35, v94, v95
	v_fmamk_f32 v35, v35, 0x3a800000, v36
	v_rsq_f32_e32 v38, v35
	v_and_b32_e32 v143, 0xffff0000, v64
	v_lshlrev_b32_e32 v64, 16, v65
	v_and_b32_e32 v65, 0xffff0000, v65
	v_mov_b32_e32 v132, v131
	v_pk_mul_f32 v[40:41], v[38:39], v[122:123] op_sel_hi:[0,1]
	v_pk_mul_f32 v[42:43], v[38:39], v[54:55] op_sel_hi:[0,1]
	v_pk_mul_f32 v[46:47], v[38:39], v[56:57] op_sel_hi:[0,1]
	s_waitcnt vmcnt(11)
	v_lshlrev_b32_e32 v146, 16, v66
	v_and_b32_e32 v147, 0xffff0000, v66
	v_lshlrev_b32_e32 v66, 16, v67
	v_and_b32_e32 v67, 0xffff0000, v67
	v_lshlrev_b32_e32 v148, 16, v68
	v_and_b32_e32 v149, 0xffff0000, v68
	v_lshlrev_b32_e32 v68, 16, v69
	v_and_b32_e32 v69, 0xffff0000, v69
	v_pk_mul_f32 v[44:45], v[38:39], v[144:145] op_sel_hi:[0,1]
	v_pk_mul_f32 v[48:49], v[38:39], v[128:129] op_sel_hi:[0,1]
	v_pk_mul_f32 v[50:51], v[38:39], v[58:59] op_sel_hi:[0,1]
	v_pk_mul_f32 v[52:53], v[38:39], v[132:133] op_sel_hi:[0,1]
	v_pk_mul_f32 v[38:39], v[38:39], v[60:61] op_sel_hi:[0,1]
	s_waitcnt vmcnt(10)
	v_lshlrev_b32_e32 v138, 16, v70
	v_and_b32_e32 v139, 0xffff0000, v70
	v_lshlrev_b32_e32 v70, 16, v71
	v_and_b32_e32 v71, 0xffff0000, v71
	s_waitcnt vmcnt(9)
	v_lshlrev_b32_e32 v155, 16, v76
	v_lshlrev_b32_e32 v151, 16, v73
	v_lshlrev_b32_e32 v150, 16, v72
	v_and_b32_e32 v73, 0xffff0000, v73
	v_and_b32_e32 v72, 0xffff0000, v72
	v_mul_f32_e32 v110, v71, v71
	v_mul_f32_e32 v154, v139, v139
	v_mov_b32_e32 v111, v155
	v_lshlrev_b32_e32 v152, 16, v74
	v_and_b32_e32 v153, 0xffff0000, v74
	v_lshlrev_b32_e32 v74, 16, v75
	v_and_b32_e32 v75, 0xffff0000, v75
	v_pk_mul_f32 v[126:127], v[72:73], v[72:73]
	v_pk_fma_f32 v[130:131], v[70:71], v[70:71], v[110:111] op_sel_hi:[1,1,0]
	v_pk_fma_f32 v[134:135], v[138:139], v[138:139], v[154:155] op_sel_hi:[1,1,0]
	v_and_b32_e32 v157, 0xffff0000, v76
	v_lshlrev_b32_e32 v76, 16, v77
	v_and_b32_e32 v77, 0xffff0000, v77
	v_mul_f32_e32 v158, v153, v153
	v_mul_f32_e32 v160, v75, v75
	v_pk_fma_f32 v[126:127], v[150:151], v[150:151], v[126:127]
	v_mov_b32_e32 v154, v134
	v_mov_b32_e32 v110, v130
	v_mul_f32_e32 v176, v157, v157
	v_mul_f32_e32 v174, v76, v76
	v_mul_f32_e32 v178, v77, v77
	v_mov_b32_e32 v166, v150
	v_mov_b32_e32 v167, v72
	v_mov_b32_e32 v72, v151
	v_pk_fma_f32 v[136:137], v[152:153], v[152:153], v[158:159] op_sel_hi:[1,1,0]
	v_pk_fma_f32 v[150:151], v[74:75], v[74:75], v[160:161] op_sel_hi:[1,1,0]
	v_pk_add_f32 v[104:105], v[134:135], v[130:131]
	v_pk_add_f32 v[106:107], v[126:127], v[126:127] op_sel:[0,1] op_sel_hi:[1,0]
	v_mov_b32_e32 v137, v174
	v_mov_b32_e32 v151, v178
	v_mov_b32_e32 v107, v176
	s_waitcnt vmcnt(8)
	v_lshlrev_b32_e32 v162, 16, v78
	v_and_b32_e32 v163, 0xffff0000, v78
	v_lshlrev_b32_e32 v78, 16, v79
	v_and_b32_e32 v79, 0xffff0000, v79
	v_lshlrev_b32_e32 v164, 16, v80
	v_and_b32_e32 v165, 0xffff0000, v80
	v_lshlrev_b32_e32 v80, 16, v81
	v_and_b32_e32 v81, 0xffff0000, v81
	s_waitcnt vmcnt(7)
	v_lshlrev_b32_e32 v168, 16, v82
	v_and_b32_e32 v169, 0xffff0000, v82
	v_lshlrev_b32_e32 v82, 16, v83
	v_and_b32_e32 v83, 0xffff0000, v83
	s_waitcnt vmcnt(0)
	v_pk_mul_f32 v[54:55], v[34:35], v[140:141] op_sel_hi:[0,1]
	v_pk_mul_f32 v[56:57], v[34:35], v[62:63] op_sel_hi:[0,1]
	v_pk_mul_f32 v[58:59], v[34:35], v[142:143] op_sel_hi:[0,1]
	v_pk_mul_f32 v[60:61], v[34:35], v[64:65] op_sel_hi:[0,1]
	v_pk_fma_f32 v[2:3], v[42:43], v[190:191], v[56:57]
	v_pk_fma_f32 v[0:1], v[40:41], v[188:189], v[54:55]
	v_pk_mul_f32 v[62:63], v[34:35], v[146:147] op_sel_hi:[0,1]
	v_pk_mul_f32 v[64:65], v[34:35], v[66:67] op_sel_hi:[0,1]
	v_pk_mul_f32 v[66:67], v[34:35], v[148:149] op_sel_hi:[0,1]
	v_pk_mul_f32 v[34:35], v[34:35], v[68:69] op_sel_hi:[0,1]
	v_pk_fma_f32 v[6:7], v[46:47], v[186:187], v[60:61]
	v_pk_fma_f32 v[4:5], v[44:45], v[184:185], v[58:59]
	v_cvt_pk_bf16_f32 v0, v0, v1
	v_cvt_pk_bf16_f32 v1, v2, v3
	v_pk_fma_f32 v[10:11], v[50:51], v[198:199], v[64:65]
	v_cvt_pk_bf16_f32 v2, v4, v5
	v_cvt_pk_bf16_f32 v3, v6, v7
	v_pk_fma_f32 v[8:9], v[48:49], v[196:197], v[62:63]
	v_pk_fma_f32 v[14:15], v[38:39], v[194:195], v[34:35]
	v_pk_fma_f32 v[12:13], v[52:53], v[192:193], v[66:67]
	global_store_dwordx4 v[32:33], v[0:3], off
	v_pk_mul_f32 v[38:39], v[154:155], v[110:111]
	v_pk_add_f32 v[40:41], v[136:137], v[150:151]
	v_cvt_pk_bf16_f32 v0, v8, v9
	v_cvt_pk_bf16_f32 v1, v10, v11
	v_cvt_pk_bf16_f32 v2, v12, v13
	v_cvt_pk_bf16_f32 v3, v14, v15
	global_store_dwordx4 v[32:33], v[0:3], off offset:1024
	global_load_dword v32, v37, s[12:13] offset:2048
	s_nop 0
	v_mov_b32_e32 v105, v39
	v_pk_add_f32 v[38:39], v[104:105], v[106:107]
	v_lshlrev_b32_e32 v170, 16, v84
	v_pk_add_f32 v[38:39], v[38:39], v[40:41]
	v_and_b32_e32 v171, 0xffff0000, v84
	v_add_f32_e32 v33, v38, v39
	v_lshlrev_b32_e32 v84, 16, v85
	v_and_b32_e32 v85, 0xffff0000, v85
	v_add_f32_dpp v33, v33, v33 quad_perm:[1,0,3,2] row_mask:0xf bank_mask:0xf bound_ctrl:1
	v_mov_b32_e32 v156, v155
	v_lshlrev_b32_e32 v158, 16, v86
	v_add_f32_dpp v33, v33, v33 quad_perm:[2,3,0,1] row_mask:0xf bank_mask:0xf bound_ctrl:1
	v_and_b32_e32 v159, 0xffff0000, v86
	v_lshlrev_b32_e32 v86, 16, v87
	v_add_f32_dpp v33, v33, v33 row_half_mirror row_mask:0xf bank_mask:0xf bound_ctrl:1
	v_and_b32_e32 v87, 0xffff0000, v87
	v_lshlrev_b32_e32 v175, 16, v92
	v_add_f32_dpp v33, v33, v33 row_mirror row_mask:0xf bank_mask:0xf bound_ctrl:1
	v_and_b32_e32 v177, 0xffff0000, v92
	v_readlane_b32 s15, v33, 16
	v_readlane_b32 s16, v33, 48
	v_readlane_b32 s0, v33, 0
	v_readlane_b32 s1, v33, 32
	v_mov_b32_e32 v38, s15
	v_mov_b32_e32 v39, s16
	v_pk_add_f32 v[38:39], s[0:1], v[38:39]
	v_lshlrev_b32_e32 v161, 16, v89
	v_add_f32_e32 v33, v38, v39
	v_fmamk_f32 v33, v33, 0x3a800000, v36
	v_rsq_f32_e32 v38, v33
	v_lshlrev_b32_e32 v160, 16, v88
	v_and_b32_e32 v89, 0xffff0000, v89
	v_and_b32_e32 v88, 0xffff0000, v88
	v_pk_mul_f32 v[40:41], v[38:39], v[138:139] op_sel_hi:[0,1]
	v_pk_mul_f32 v[42:43], v[38:39], v[70:71] op_sel_hi:[0,1]
	v_pk_mul_f32 v[44:45], v[38:39], v[166:167] op_sel_hi:[0,1]
	v_pk_mul_f32 v[46:47], v[38:39], v[72:73] op_sel_hi:[0,1]
	v_pk_mul_f32 v[48:49], v[38:39], v[152:153] op_sel_hi:[0,1]
	v_pk_mul_f32 v[50:51], v[38:39], v[74:75] op_sel_hi:[0,1]
	v_pk_mul_f32 v[52:53], v[38:39], v[156:157] op_sel_hi:[0,1]
	v_pk_mul_f32 v[38:39], v[38:39], v[76:77] op_sel_hi:[0,1]
	v_and_b32_e32 v173, 0xffff0000, v90
	v_mul_f32_e32 v126, v87, v87
	v_mul_f32_e32 v135, v177, v177
	v_mul_f32_e32 v134, v159, v159
	v_mov_b32_e32 v127, v175
	v_lshlrev_b32_e32 v172, 16, v90
	v_lshlrev_b32_e32 v90, 16, v91
	v_and_b32_e32 v91, 0xffff0000, v91
	v_lshlrev_b32_e32 v92, 16, v93
	v_pk_mul_f32 v[130:131], v[88:89], v[88:89]
	v_mul_f32_e32 v174, v173, v173
	v_and_b32_e32 v93, 0xffff0000, v93
	v_mul_f32_e32 v179, v92, v92
	v_mul_f32_e32 v178, v91, v91
	v_mul_f32_e32 v182, v93, v93
	v_lshlrev_b32_e32 v180, 16, v20
	v_and_b32_e32 v181, 0xffff0000, v20
	v_lshlrev_b32_e32 v20, 16, v21
	v_and_b32_e32 v21, 0xffff0000, v21
	v_lshlrev_b32_e32 v34, 16, v22
	v_and_b32_e32 v35, 0xffff0000, v22
	v_lshlrev_b32_e32 v22, 16, v23
	v_and_b32_e32 v23, 0xffff0000, v23
	v_mov_b32_e32 v176, v175
	s_waitcnt vmcnt(0)
	v_pk_mul_f32 v[54:55], v[32:33], v[162:163] op_sel_hi:[0,1]
	v_pk_mul_f32 v[56:57], v[32:33], v[78:79] op_sel_hi:[0,1]
	v_pk_mul_f32 v[58:59], v[32:33], v[164:165] op_sel_hi:[0,1]
	v_pk_mul_f32 v[60:61], v[32:33], v[80:81] op_sel_hi:[0,1]
	v_pk_fma_f32 v[2:3], v[42:43], v[190:191], v[56:57]
	v_pk_fma_f32 v[0:1], v[40:41], v[188:189], v[54:55]
	v_pk_mul_f32 v[62:63], v[32:33], v[168:169] op_sel_hi:[0,1]
	v_pk_mul_f32 v[64:65], v[32:33], v[82:83] op_sel_hi:[0,1]
	v_pk_mul_f32 v[66:67], v[32:33], v[170:171] op_sel_hi:[0,1]
	v_pk_mul_f32 v[32:33], v[32:33], v[84:85] op_sel_hi:[0,1]
	v_pk_fma_f32 v[6:7], v[46:47], v[186:187], v[60:61]
	v_pk_fma_f32 v[4:5], v[44:45], v[184:185], v[58:59]
	v_cvt_pk_bf16_f32 v0, v0, v1
	v_cvt_pk_bf16_f32 v1, v2, v3
	v_pk_fma_f32 v[10:11], v[50:51], v[198:199], v[64:65]
	v_cvt_pk_bf16_f32 v2, v4, v5
	v_cvt_pk_bf16_f32 v3, v6, v7
	v_pk_fma_f32 v[8:9], v[48:49], v[196:197], v[62:63]
	v_pk_fma_f32 v[14:15], v[38:39], v[194:195], v[32:33]
	v_pk_fma_f32 v[12:13], v[52:53], v[192:193], v[66:67]
	global_store_dwordx4 v[30:31], v[0:3], off
	v_pk_fma_f32 v[42:43], v[86:87], v[86:87], v[126:127] op_sel_hi:[1,1,0]
	v_pk_fma_f32 v[46:47], v[158:159], v[158:159], v[134:135] op_sel_hi:[1,1,0]
	v_cvt_pk_bf16_f32 v0, v8, v9
	v_cvt_pk_bf16_f32 v1, v10, v11
	v_cvt_pk_bf16_f32 v2, v12, v13
	v_cvt_pk_bf16_f32 v3, v14, v15
	global_store_dwordx4 v[30:31], v[0:3], off offset:1024
	global_load_dword v30, v37, s[12:13] offset:3072
	s_nop 0
	v_pk_fma_f32 v[44:45], v[160:161], v[160:161], v[130:131]
	v_pk_fma_f32 v[48:49], v[172:173], v[172:173], v[174:175] op_sel_hi:[1,1,0]
	v_mov_b32_e32 v174, v46
	v_mov_b32_e32 v126, v42
	v_pk_fma_f32 v[50:51], v[90:91], v[90:91], v[178:179] op_sel_hi:[1,1,0]
	v_pk_add_f32 v[42:43], v[46:47], v[42:43]
	v_pk_add_f32 v[44:45], v[44:45], v[44:45] op_sel:[0,1] op_sel_hi:[1,0]
	v_pk_mul_f32 v[46:47], v[174:175], v[126:127]
	v_mov_b32_e32 v49, v179
	v_mov_b32_e32 v51, v182
	v_mov_b32_e32 v45, v135
	v_mov_b32_e32 v43, v47
	v_pk_add_f32 v[48:49], v[48:49], v[50:51]
	v_pk_add_f32 v[42:43], v[42:43], v[44:45]
	v_mov_b32_e32 v32, v160
	v_pk_add_f32 v[42:43], v[42:43], v[48:49]
	v_mov_b32_e32 v33, v88
	v_add_f32_e32 v31, v42, v43
	v_mov_b32_e32 v88, v161
	v_lshlrev_b32_e32 v38, 16, v16
	v_add_f32_dpp v31, v31, v31 quad_perm:[1,0,3,2] row_mask:0xf bank_mask:0xf bound_ctrl:1
	v_and_b32_e32 v39, 0xffff0000, v16
	v_lshlrev_b32_e32 v16, 16, v17
	v_add_f32_dpp v31, v31, v31 quad_perm:[2,3,0,1] row_mask:0xf bank_mask:0xf bound_ctrl:1
	v_and_b32_e32 v17, 0xffff0000, v17
	v_lshlrev_b32_e32 v40, 16, v18
	v_add_f32_dpp v31, v31, v31 row_half_mirror row_mask:0xf bank_mask:0xf bound_ctrl:1
	v_and_b32_e32 v41, 0xffff0000, v18
	v_lshlrev_b32_e32 v18, 16, v19
	v_add_f32_dpp v31, v31, v31 row_mirror row_mask:0xf bank_mask:0xf bound_ctrl:1
	v_and_b32_e32 v19, 0xffff0000, v19
	v_readlane_b32 s12, v31, 16
	v_readlane_b32 s13, v31, 48
	v_readlane_b32 s0, v31, 0
	v_readlane_b32 s1, v31, 32
	v_mov_b32_e32 v42, s12
	v_mov_b32_e32 v43, s13
	v_pk_add_f32 v[42:43], s[0:1], v[42:43]
	s_nop 0
	v_add_f32_e32 v31, v42, v43
	v_fmamk_f32 v31, v31, 0x3a800000, v36
	v_rsq_f32_e32 v42, v31
	s_waitcnt vmcnt(0)
	v_pk_mul_f32 v[56:57], v[30:31], v[180:181] op_sel_hi:[0,1]
	v_pk_mul_f32 v[44:45], v[42:43], v[158:159] op_sel_hi:[0,1]
	v_pk_mul_f32 v[46:47], v[42:43], v[86:87] op_sel_hi:[0,1]
	v_pk_mul_f32 v[20:21], v[30:31], v[20:21] op_sel_hi:[0,1]
	v_pk_mul_f32 v[32:33], v[42:43], v[32:33] op_sel_hi:[0,1]
	v_pk_mul_f32 v[48:49], v[42:43], v[88:89] op_sel_hi:[0,1]
	v_pk_mul_f32 v[34:35], v[30:31], v[34:35] op_sel_hi:[0,1]
	v_pk_mul_f32 v[22:23], v[30:31], v[22:23] op_sel_hi:[0,1]
	v_pk_fma_f32 v[2:3], v[46:47], v[190:191], v[20:21]
	v_pk_fma_f32 v[0:1], v[44:45], v[188:189], v[56:57]
	v_pk_mul_f32 v[50:51], v[42:43], v[172:173] op_sel_hi:[0,1]
	v_pk_mul_f32 v[52:53], v[42:43], v[90:91] op_sel_hi:[0,1]
	v_pk_mul_f32 v[54:55], v[42:43], v[176:177] op_sel_hi:[0,1]
	v_pk_mul_f32 v[42:43], v[42:43], v[92:93] op_sel_hi:[0,1]
	v_pk_mul_f32 v[38:39], v[30:31], v[38:39] op_sel_hi:[0,1]
	v_pk_mul_f32 v[16:17], v[30:31], v[16:17] op_sel_hi:[0,1]
	v_pk_mul_f32 v[40:41], v[30:31], v[40:41] op_sel_hi:[0,1]
	v_pk_mul_f32 v[18:19], v[30:31], v[18:19] op_sel_hi:[0,1]
	v_pk_fma_f32 v[6:7], v[48:49], v[186:187], v[22:23]
	v_pk_fma_f32 v[4:5], v[32:33], v[184:185], v[34:35]
	v_cvt_pk_bf16_f32 v0, v0, v1
	v_cvt_pk_bf16_f32 v1, v2, v3
	v_pk_fma_f32 v[10:11], v[52:53], v[198:199], v[16:17]
	v_cvt_pk_bf16_f32 v2, v4, v5
	v_cvt_pk_bf16_f32 v3, v6, v7
	v_pk_fma_f32 v[8:9], v[50:51], v[196:197], v[38:39]
	v_pk_fma_f32 v[14:15], v[42:43], v[194:195], v[18:19]
	v_pk_fma_f32 v[12:13], v[54:55], v[192:193], v[40:41]
	global_store_dwordx4 v[28:29], v[0:3], off
	s_nop 1
	v_cvt_pk_bf16_f32 v0, v8, v9
	v_cvt_pk_bf16_f32 v1, v10, v11
	v_cvt_pk_bf16_f32 v2, v12, v13
	v_cvt_pk_bf16_f32 v3, v14, v15
	global_store_dwordx4 v[28:29], v[0:3], off offset:1024
	s_cbranch_scc0 .LBB0_1614

.LBB0_1759:
	s_or_b64 exec, exec, s[0:1]
	s_waitcnt lgkmcnt(0)
	s_barrier
	s_nop 0
	v_readfirstlane_b32 s0, v226
	s_ashr_i32 s0, s0, 6
	s_add_i32 s0, s85, s0
	s_cmp_lt_i32 s0, s73
	s_cbranch_scc1 .LBB0_1762
	v_readlane_b32 s4, v254, 0
	v_lshlrev_b32_e32 v0, 3, v226
	v_readlane_b32 s5, v254, 1
	v_readlane_b32 s6, v254, 2
	v_readlane_b32 s7, v254, 3
	v_readlane_b32 s8, v254, 4
	v_readlane_b32 s9, v254, 5
	v_and_b32_e32 v4, 0x1f8, v0
	v_readlane_b32 s10, v254, 6
	v_readlane_b32 s11, v254, 7
	s_mov_b64 s[4:5], s[8:9]
	s_add_u32 s2, s4, 0x1000
	v_lshlrev_b32_e32 v0, 2, v4
	v_mov_b32_e32 v1, 0
	s_addc_u32 s3, s5, 0
	v_or_b32_e32 v2, 16, v0
	v_mov_b32_e32 v3, v1
	v_lshl_add_u64 v[52:53], s[2:3], 0, v[0:1]
	v_lshl_add_u64 v[54:55], s[2:3], 0, v[2:3]
	v_or_b32_e32 v2, 0x800, v0
	v_or_b32_e32 v0, 0x810, v0
	s_ashr_i32 s1, s0, 31
	v_lshl_add_u64 v[56:57], s[2:3], 0, v[2:3]
	v_lshl_add_u64 v[58:59], s[2:3], 0, v[0:1]
	s_lshl_b64 s[2:3], s[0:1], 11
	v_and_b32_e32 v0, 63, v226
	v_lshl_or_b32 v60, v0, 4, s2
	v_mov_b32_e32 v61, s3
	s_mov_b64 s[2:3], 0x17b00000
	s_mov_b64 s[6:7], s[10:11]
	v_lshl_add_u64 v[62:63], v[60:61], 0, s[2:3]
	s_lshl_b64 s[2:3], s[0:1], 12
	s_add_u32 s2, s6, s2
	v_lshlrev_b32_e32 v0, 5, v0
	s_addc_u32 s3, s7, s3
	v_lshl_add_u64 v[64:65], s[2:3], 0, v[0:1]
	s_lshl_b64 s[2:3], s[0:1], 10
	s_mov_b32 s4, 0xffe00000
	s_mov_b32 s6, 0xffc00000
	s_mov_b32 s8, 0xfff00000
	v_or_b32_e32 v66, s2, v4
	v_mov_b32_e32 v67, s3
	s_mov_b32 s2, 0x3b808081
	v_mov_b32_e32 v85, 0x358637bd
	s_mov_b32 s1, 0x100000
	s_mov_b32 s3, 0x200000
	s_mov_b32 s10, 0x300000
	s_mov_b32 s5, -1
	s_mov_b32 s7, -1
	s_mov_b32 s9, -1
	global_load_dwordx4 v[126:129], v[52:53], off
	global_load_dwordx4 v[130:133], v[54:55], off
	global_load_dwordx4 v[134:137], v[56:57], off
	global_load_dwordx4 v[138:141], v[58:59], off
	s_waitcnt vmcnt(0)
.LBB0_1761:
	v_lshl_add_u64 v[8:9], s[92:93], 0, v[60:61]
	v_add_co_u32_e32 v2, vcc, 0xfa00000, v8
	v_lshl_add_u64 v[10:11], s[92:93], 0, v[66:67]
	v_lshl_add_u64 v[0:1], s[92:93], 0, v[62:63]
	v_addc_co_u32_e32 v3, vcc, 0, v9, vcc
	global_load_dwordx4 v[80:83], v[0:1], off nt
	global_load_dwordx4 v[90:93], v[0:1], off offset:1024 nt
	v_add_co_u32_e32 v0, vcc, 0x1fc00000, v10
	global_load_dwordx4 v[94:97], v[2:3], off nt
	global_load_dwordx4 v[48:51], v[2:3], off offset:1024 nt
	v_addc_co_u32_e32 v1, vcc, 0, v11, vcc
	global_load_dwordx2 v[98:99], v[0:1], off nt
	global_load_dwordx2 v[100:101], v[0:1], off offset:512 nt
	v_add_co_u32_e32 v2, vcc, 0xfa80000, v8
	s_addk_i32 s0, 0xfc00
	s_nop 0
	v_addc_co_u32_e32 v3, vcc, 0, v9, vcc
	v_add_co_u32_e32 v0, vcc, 0x1fc40000, v10
	global_load_dwordx4 v[36:39], v[2:3], off nt
	global_load_dwordx4 v[32:35], v[2:3], off offset:1024 nt
	v_addc_co_u32_e32 v1, vcc, 0, v11, vcc
	v_add_co_u32_e32 v2, vcc, 0x17b80000, v8
	global_load_dwordx2 v[78:79], v[0:1], off nt
	global_load_dwordx2 v[76:77], v[0:1], off offset:512 nt
	v_addc_co_u32_e32 v3, vcc, 0, v9, vcc
	v_add_co_u32_e32 v0, vcc, 0xfb00000, v8
	global_load_dwordx4 v[44:47], v[2:3], off nt
	global_load_dwordx4 v[40:43], v[2:3], off offset:1024 nt
	v_addc_co_u32_e32 v1, vcc, 0, v9, vcc
	v_add_co_u32_e32 v2, vcc, 0x1fc80000, v10
	global_load_dwordx4 v[20:23], v[0:1], off nt
	global_load_dwordx4 v[16:19], v[0:1], off offset:1024 nt
	v_addc_co_u32_e32 v3, vcc, 0, v11, vcc
	v_add_co_u32_e32 v0, vcc, 0x17c00000, v8
	global_load_dwordx2 v[74:75], v[2:3], off nt
	global_load_dwordx2 v[72:73], v[2:3], off offset:512 nt
	v_addc_co_u32_e32 v1, vcc, 0, v9, vcc
	v_add_co_u32_e32 v12, vcc, 0xfb80000, v8
	global_load_dwordx4 v[28:31], v[0:1], off nt
	global_load_dwordx4 v[24:27], v[0:1], off offset:1024 nt
	v_addc_co_u32_e32 v13, vcc, 0, v9, vcc
	v_add_co_u32_e32 v10, vcc, 0x1fcc0000, v10
	global_load_dwordx4 v[4:7], v[12:13], off nt
	global_load_dwordx4 v[0:3], v[12:13], off offset:1024 nt
	v_addc_co_u32_e32 v11, vcc, 0, v11, vcc
	v_add_co_u32_e32 v102, vcc, 0x17c80000, v8
	global_load_dwordx2 v[70:71], v[10:11], off nt
	global_load_dwordx2 v[68:69], v[10:11], off offset:512 nt
	v_addc_co_u32_e32 v103, vcc, 0, v9, vcc
	global_load_dwordx4 v[12:15], v[102:103], off nt
	global_load_dwordx4 v[8:11], v[102:103], off offset:1024 nt
	v_lshl_add_u64 v[62:63], v[62:63], 0, s[4:5]
	v_lshl_add_u64 v[60:61], v[60:61], 0, s[4:5]
	v_lshl_add_u64 v[66:67], v[66:67], 0, s[8:9]
	s_cmp_lt_i32 s0, s73
	s_waitcnt vmcnt(23)
	v_lshlrev_b32_e32 v102, 16, v80
	v_and_b32_e32 v103, 0xffff0000, v80
	v_lshlrev_b32_e32 v80, 16, v81
	v_and_b32_e32 v81, 0xffff0000, v81
	v_lshlrev_b32_e32 v104, 16, v82
	v_and_b32_e32 v105, 0xffff0000, v82
	s_waitcnt vmcnt(19)
	v_cvt_f32_ubyte1_e32 v113, v98
	v_cvt_f32_ubyte0_e32 v112, v98
	v_cvt_f32_ubyte3_e32 v115, v98
	v_cvt_f32_ubyte2_e32 v114, v98
	v_cvt_f32_ubyte1_e32 v117, v99
	v_cvt_f32_ubyte0_e32 v116, v99
	v_cvt_f32_ubyte3_e32 v119, v99
	v_cvt_f32_ubyte2_e32 v118, v99
	v_lshlrev_b32_e32 v82, 16, v83
	v_and_b32_e32 v83, 0xffff0000, v83
	s_waitcnt vmcnt(18)
	v_cvt_f32_ubyte3_e32 v99, v100
	v_cvt_f32_ubyte2_e32 v98, v100
	v_cvt_f32_ubyte1_e32 v121, v100
	v_cvt_f32_ubyte0_e32 v120, v100
	v_cvt_f32_ubyte3_e32 v123, v101
	v_cvt_f32_ubyte2_e32 v122, v101
	v_cvt_f32_ubyte1_e32 v125, v101
	v_cvt_f32_ubyte0_e32 v124, v101
	v_pk_mul_f32 v[100:101], v[114:115], s[2:3] op_sel_hi:[1,0]
	v_pk_mul_f32 v[112:113], v[112:113], s[2:3] op_sel_hi:[1,0]
	v_pk_mul_f32 v[114:115], v[118:119], s[2:3] op_sel_hi:[1,0]
	v_pk_mul_f32 v[116:117], v[116:117], s[2:3] op_sel_hi:[1,0]
	v_lshlrev_b32_e32 v106, 16, v90
	v_and_b32_e32 v107, 0xffff0000, v90
	v_lshlrev_b32_e32 v90, 16, v91
	v_and_b32_e32 v91, 0xffff0000, v91
	v_lshlrev_b32_e32 v108, 16, v92
	v_and_b32_e32 v109, 0xffff0000, v92
	v_lshlrev_b32_e32 v92, 16, v93
	v_and_b32_e32 v93, 0xffff0000, v93
	v_pk_mul_f32 v[118:119], v[120:121], s[2:3] op_sel_hi:[1,0]
	v_pk_mul_f32 v[98:99], v[98:99], s[2:3] op_sel_hi:[1,0]
	v_pk_mul_f32 v[120:121], v[124:125], s[2:3] op_sel_hi:[1,0]
	v_pk_mul_f32 v[122:123], v[122:123], s[2:3] op_sel_hi:[1,0]
	v_pk_mul_f32 v[102:103], v[112:113], v[102:103]
	v_pk_mul_f32 v[100:101], v[100:101], v[80:81]
	v_pk_mul_f32 v[104:105], v[116:117], v[104:105]
	v_pk_mul_f32 v[112:113], v[114:115], v[82:83]
	v_pk_mul_f32 v[90:91], v[98:99], v[90:91]
	v_pk_mul_f32 v[98:99], v[118:119], v[106:107]
	v_pk_mul_f32 v[80:81], v[122:123], v[92:93]
	v_pk_mul_f32 v[82:83], v[120:121], v[108:109]
	v_pk_mul_f32 v[92:93], v[100:101], v[100:101]
	v_pk_mul_f32 v[106:107], v[102:103], v[102:103]
	v_pk_mul_f32 v[108:109], v[112:113], v[112:113]
	v_pk_mul_f32 v[114:115], v[104:105], v[104:105]
	v_pk_mov_b32 v[118:119], v[106:107], v[92:93] op_sel:[1,0]
	v_mov_b32_e32 v107, v93
	v_pk_mov_b32 v[92:93], v[114:115], v[108:109] op_sel:[1,0]
	v_mov_b32_e32 v115, v109
	v_mul_f32_e32 v84, v99, v99
	v_mul_f32_e32 v116, v91, v91
	v_pk_add_f32 v[106:107], v[118:119], v[106:107]
	v_pk_add_f32 v[92:93], v[92:93], v[114:115]
	v_mul_f32_e32 v120, v82, v82
	v_mul_f32_e32 v121, v83, v83
	v_mul_f32_e32 v122, v80, v80
	v_mul_f32_e32 v123, v81, v81
	v_pk_fma_f32 v[108:109], v[98:99], v[98:99], v[84:85] op_sel_hi:[1,1,0]
	v_pk_fma_f32 v[116:117], v[90:91], v[90:91], v[116:117] op_sel_hi:[1,1,0]
	v_pk_add_f32 v[106:107], v[106:107], v[106:107] op_sel:[0,1] op_sel_hi:[1,0]
	v_pk_add_f32 v[92:93], v[92:93], v[92:93] op_sel:[0,1] op_sel_hi:[1,0]
	v_mov_b32_e32 v109, v122
	v_mov_b32_e32 v117, v123
	v_mov_b32_e32 v107, v120
	v_mov_b32_e32 v93, v121
	v_pk_add_f32 v[108:109], v[108:109], v[116:117]
	v_pk_add_f32 v[92:93], v[106:107], v[92:93]
	v_lshlrev_b32_e32 v110, 16, v94
	v_pk_add_f32 v[92:93], v[92:93], v[108:109]
	v_and_b32_e32 v111, 0xffff0000, v94
	v_add_f32_e32 v84, v92, v93
	v_lshlrev_b32_e32 v94, 16, v95
	v_and_b32_e32 v95, 0xffff0000, v95
	v_add_f32_dpp v84, v84, v84 quad_perm:[1,0,3,2] row_mask:0xf bank_mask:0xf bound_ctrl:1
	s_waitcnt vmcnt(14)
	v_cvt_f32_ubyte1_e32 v107, v77
	v_cvt_f32_ubyte0_e32 v106, v77
	v_add_f32_dpp v84, v84, v84 quad_perm:[2,3,0,1] row_mask:0xf bank_mask:0xf bound_ctrl:1
	s_waitcnt vmcnt(13)
	v_lshlrev_b32_e32 v108, 16, v45
	v_and_b32_e32 v109, 0xffff0000, v45
	v_add_f32_dpp v84, v84, v84 row_half_mirror row_mask:0xf bank_mask:0xf bound_ctrl:1
	s_nop 1
	v_add_f32_dpp v84, v84, v84 row_mirror row_mask:0xf bank_mask:0xf bound_ctrl:1
	s_nop 0
	v_readlane_b32 s11, v84, 16
	v_readlane_b32 s14, v84, 48
	v_readlane_b32 s12, v84, 0
	v_readlane_b32 s13, v84, 32
	v_mov_b32_e32 v92, s11
	v_mov_b32_e32 v93, s14
	v_pk_add_f32 v[92:93], s[12:13], v[92:93]
	s_nop 0
	v_add_f32_e32 v84, v92, v93
	v_fmamk_f32 v84, v84, 0x3a800000, v85
	v_rsq_f32_e32 v84, v84
	s_nop 0
	v_pk_mul_f32 v[92:93], v[84:85], v[102:103] op_sel_hi:[0,1]
	v_pk_mul_f32 v[100:101], v[84:85], v[100:101] op_sel_hi:[0,1]
	v_pk_fma_f32 v[88:89], v[100:101], v[128:129], v[94:95]
	v_pk_fma_f32 v[86:87], v[92:93], v[126:127], v[110:111]
	global_store_dwordx4 v[64:65], v[86:89], off
	v_lshlrev_b32_e32 v92, 16, v96
	v_and_b32_e32 v93, 0xffff0000, v96
	v_lshlrev_b32_e32 v94, 16, v97
	v_and_b32_e32 v95, 0xffff0000, v97
	v_pk_mul_f32 v[96:97], v[84:85], v[112:113] op_sel_hi:[0,1]
	v_pk_mul_f32 v[100:101], v[84:85], v[104:105] op_sel_hi:[0,1]
	v_pk_mul_f32 v[90:91], v[84:85], v[90:91] op_sel_hi:[0,1]
	v_cvt_f32_ubyte1_e32 v103, v76
	v_cvt_f32_ubyte0_e32 v102, v76
	v_cvt_f32_ubyte3_e32 v105, v77
	v_cvt_f32_ubyte2_e32 v104, v77
	v_lshlrev_b32_e32 v110, 16, v46
	v_and_b32_e32 v111, 0xffff0000, v46
	v_lshlrev_b32_e32 v112, 16, v47
	v_and_b32_e32 v113, 0xffff0000, v47
	v_pk_mul_f32 v[46:47], v[84:85], v[80:81] op_sel_hi:[0,1]
	s_waitcnt vmcnt(13)
	v_lshlrev_b32_e32 v80, 16, v40
	v_and_b32_e32 v81, 0xffff0000, v40
	v_lshlrev_b32_e32 v40, 16, v41
	v_and_b32_e32 v41, 0xffff0000, v41
	v_pk_fma_f32 v[86:87], v[100:101], v[130:131], v[92:93]
	v_pk_fma_f32 v[88:89], v[96:97], v[132:133], v[94:95]
	global_store_dwordx4 v[64:65], v[86:89], off offset:16
	v_lshlrev_b32_e32 v92, 16, v48
	v_and_b32_e32 v93, 0xffff0000, v48
	v_lshlrev_b32_e32 v48, 16, v49
	v_and_b32_e32 v49, 0xffff0000, v49
	v_pk_mul_f32 v[94:95], v[84:85], v[98:99] op_sel_hi:[0,1]
	v_cvt_f32_ubyte3_e32 v97, v78
	v_cvt_f32_ubyte2_e32 v96, v78
	v_cvt_f32_ubyte1_e32 v99, v79
	v_cvt_f32_ubyte0_e32 v98, v79
	v_cvt_f32_ubyte3_e32 v101, v79
	v_cvt_f32_ubyte2_e32 v100, v79
	v_cvt_f32_ubyte3_e32 v79, v76
	v_pk_mul_f32 v[100:101], v[100:101], s[2:3] op_sel_hi:[1,0]
	v_pk_mul_f32 v[98:99], v[98:99], s[2:3] op_sel_hi:[1,0]
	v_pk_fma_f32 v[86:87], v[94:95], v[134:135], v[92:93]
	v_pk_fma_f32 v[88:89], v[90:91], v[136:137], v[48:49]
	global_store_dwordx4 v[64:65], v[86:89], off offset:2048
	v_lshlrev_b32_e32 v90, 16, v50
	v_and_b32_e32 v91, 0xffff0000, v50
	v_lshlrev_b32_e32 v50, 16, v51
	v_and_b32_e32 v51, 0xffff0000, v51
	v_lshlrev_b32_e32 v92, 16, v36
	v_and_b32_e32 v93, 0xffff0000, v36
	v_lshlrev_b32_e32 v94, 16, v37
	v_and_b32_e32 v95, 0xffff0000, v37
	v_cvt_f32_ubyte1_e32 v37, v78
	v_cvt_f32_ubyte0_e32 v36, v78
	v_cvt_f32_ubyte2_e32 v78, v76
	v_pk_mul_f32 v[76:77], v[96:97], s[2:3] op_sel_hi:[1,0]
	v_lshlrev_b32_e32 v96, 16, v44
	v_and_b32_e32 v97, 0xffff0000, v44
	v_pk_mul_f32 v[44:45], v[84:85], v[82:83] op_sel_hi:[0,1]
	v_pk_mul_f32 v[36:37], v[36:37], s[2:3] op_sel_hi:[1,0]
	v_pk_mul_f32 v[78:79], v[78:79], s[2:3] op_sel_hi:[1,0]
	v_pk_mul_f32 v[82:83], v[106:107], s[2:3] op_sel_hi:[1,0]
	v_pk_mul_f32 v[76:77], v[76:77], v[108:109]
	v_pk_mul_f32 v[78:79], v[78:79], v[40:41]
	v_add_co_u32_e32 v48, vcc, s1, v64
	v_pk_fma_f32 v[44:45], v[44:45], v[138:139], v[90:91]
	v_pk_fma_f32 v[46:47], v[46:47], v[140:141], v[50:51]
	global_store_dwordx4 v[64:65], v[44:47], off offset:2064
	v_pk_mul_f32 v[50:51], v[102:103], s[2:3] op_sel_hi:[1,0]
	v_pk_mul_f32 v[86:87], v[104:105], s[2:3] op_sel_hi:[1,0]
	v_lshlrev_b32_e32 v88, 16, v42
	v_and_b32_e32 v89, 0xffff0000, v42
	v_lshlrev_b32_e32 v42, 16, v43
	v_and_b32_e32 v43, 0xffff0000, v43
	v_pk_mul_f32 v[90:91], v[36:37], v[96:97]
	v_pk_mul_f32 v[96:97], v[98:99], v[110:111]
	v_pk_mul_f32 v[98:99], v[100:101], v[112:113]
	v_pk_mul_f32 v[50:51], v[50:51], v[80:81]
	v_pk_mul_f32 v[36:37], v[86:87], v[42:43]
	v_pk_mul_f32 v[40:41], v[82:83], v[88:89]
	v_pk_mul_f32 v[42:43], v[76:77], v[76:77]
	v_pk_mul_f32 v[80:81], v[90:91], v[90:91]
	v_pk_mul_f32 v[82:83], v[98:99], v[98:99]
	v_pk_mul_f32 v[86:87], v[96:97], v[96:97]
	v_pk_mov_b32 v[100:101], v[80:81], v[42:43] op_sel:[1,0]
	v_mov_b32_e32 v81, v43
	v_pk_mov_b32 v[42:43], v[86:87], v[82:83] op_sel:[1,0]
	v_mov_b32_e32 v87, v83
	v_mul_f32_e32 v84, v51, v51
	v_mul_f32_e32 v88, v79, v79
	v_pk_add_f32 v[80:81], v[100:101], v[80:81]
	v_pk_add_f32 v[42:43], v[42:43], v[86:87]
	v_mul_f32_e32 v102, v40, v40
	v_mul_f32_e32 v103, v41, v41
	v_mul_f32_e32 v104, v36, v36
	v_mul_f32_e32 v105, v37, v37
	v_pk_fma_f32 v[82:83], v[50:51], v[50:51], v[84:85] op_sel_hi:[1,1,0]
	v_pk_fma_f32 v[88:89], v[78:79], v[78:79], v[88:89] op_sel_hi:[1,1,0]
	v_pk_add_f32 v[80:81], v[80:81], v[80:81] op_sel:[0,1] op_sel_hi:[1,0]
	v_pk_add_f32 v[42:43], v[42:43], v[42:43] op_sel:[0,1] op_sel_hi:[1,0]
	v_mov_b32_e32 v83, v104
	v_mov_b32_e32 v89, v105
	v_mov_b32_e32 v81, v102
	v_mov_b32_e32 v43, v103
	v_pk_add_f32 v[82:83], v[82:83], v[88:89]
	v_pk_add_f32 v[42:43], v[80:81], v[42:43]
	v_addc_co_u32_e32 v49, vcc, 0, v65, vcc
	v_pk_add_f32 v[42:43], v[42:43], v[82:83]
	s_waitcnt vmcnt(12)
	v_cvt_f32_ubyte1_e32 v87, v72
	v_add_f32_e32 v42, v42, v43
	v_cvt_f32_ubyte0_e32 v86, v72
	v_cvt_f32_ubyte3_e32 v89, v73
	v_add_f32_dpp v42, v42, v42 quad_perm:[1,0,3,2] row_mask:0xf bank_mask:0xf bound_ctrl:1
	v_cvt_f32_ubyte2_e32 v88, v73
	s_nop 0
	v_add_f32_dpp v42, v42, v42 quad_perm:[2,3,0,1] row_mask:0xf bank_mask:0xf bound_ctrl:1
	s_nop 1
	v_add_f32_dpp v42, v42, v42 row_half_mirror row_mask:0xf bank_mask:0xf bound_ctrl:1
	s_nop 1
	v_add_f32_dpp v42, v42, v42 row_mirror row_mask:0xf bank_mask:0xf bound_ctrl:1
	s_nop 0
	v_readlane_b32 s11, v42, 16
	v_readlane_b32 s14, v42, 48
	v_readlane_b32 s12, v42, 0
	v_readlane_b32 s13, v42, 32
	v_mov_b32_e32 v42, s11
	v_mov_b32_e32 v43, s14
	v_pk_add_f32 v[42:43], s[12:13], v[42:43]
	s_nop 0
	v_add_f32_e32 v42, v42, v43
	v_fmamk_f32 v42, v42, 0x3a800000, v85
	v_rsq_f32_e32 v42, v42
	s_nop 0
	v_pk_mul_f32 v[76:77], v[42:43], v[76:77] op_sel_hi:[0,1]
	v_pk_mul_f32 v[80:81], v[42:43], v[90:91] op_sel_hi:[0,1]
	v_pk_mul_f32 v[82:83], v[42:43], v[96:97] op_sel_hi:[0,1]
	v_pk_mul_f32 v[50:51], v[42:43], v[50:51] op_sel_hi:[0,1]
	v_cvt_f32_ubyte1_e32 v91, v73
	v_cvt_f32_ubyte0_e32 v90, v73
	v_pk_mul_f32 v[36:37], v[42:43], v[36:37] op_sel_hi:[0,1]
	v_pk_fma_f32 v[44:45], v[80:81], v[126:127], v[92:93]
	v_pk_fma_f32 v[46:47], v[76:77], v[128:129], v[94:95]
	global_store_dwordx4 v[48:49], v[44:47], off
	v_lshlrev_b32_e32 v76, 16, v38
	v_and_b32_e32 v77, 0xffff0000, v38
	v_lshlrev_b32_e32 v38, 16, v39
	v_and_b32_e32 v39, 0xffff0000, v39
	v_pk_mul_f32 v[80:81], v[42:43], v[98:99] op_sel_hi:[0,1]
	s_waitcnt vmcnt(12)
	v_lshlrev_b32_e32 v92, 16, v28
	v_and_b32_e32 v93, 0xffff0000, v28
	v_lshlrev_b32_e32 v28, 16, v29
	v_and_b32_e32 v29, 0xffff0000, v29
	v_pk_fma_f32 v[44:45], v[82:83], v[130:131], v[76:77]
	v_pk_fma_f32 v[46:47], v[80:81], v[132:133], v[38:39]
	global_store_dwordx4 v[48:49], v[44:47], off offset:16
	v_lshlrev_b32_e32 v38, 16, v32
	v_and_b32_e32 v39, 0xffff0000, v32
	v_lshlrev_b32_e32 v32, 16, v33
	v_and_b32_e32 v33, 0xffff0000, v33
	v_pk_mul_f32 v[76:77], v[42:43], v[78:79] op_sel_hi:[0,1]
	v_lshlrev_b32_e32 v78, 16, v21
	v_and_b32_e32 v79, 0xffff0000, v21
	v_cvt_f32_ubyte1_e32 v21, v74
	v_cvt_f32_ubyte1_e32 v81, v75
	v_cvt_f32_ubyte0_e32 v80, v75
	v_cvt_f32_ubyte3_e32 v83, v75
	v_cvt_f32_ubyte2_e32 v82, v75
	v_cvt_f32_ubyte3_e32 v75, v72
	v_pk_mul_f32 v[82:83], v[82:83], s[2:3] op_sel_hi:[1,0]
	v_pk_mul_f32 v[80:81], v[80:81], s[2:3] op_sel_hi:[1,0]
	v_pk_fma_f32 v[44:45], v[50:51], v[134:135], v[38:39]
	v_pk_fma_f32 v[46:47], v[76:77], v[136:137], v[32:33]
	global_store_dwordx4 v[48:49], v[44:47], off offset:2048
	v_lshlrev_b32_e32 v38, 16, v34
	v_and_b32_e32 v39, 0xffff0000, v34
	v_lshlrev_b32_e32 v50, 16, v35
	v_and_b32_e32 v51, 0xffff0000, v35
	v_cvt_f32_ubyte3_e32 v35, v74
	v_cvt_f32_ubyte2_e32 v34, v74
	v_lshlrev_b32_e32 v76, 16, v20
	v_and_b32_e32 v77, 0xffff0000, v20
	v_cvt_f32_ubyte0_e32 v20, v74
	v_cvt_f32_ubyte2_e32 v74, v72
	v_pk_mul_f32 v[72:73], v[34:35], s[2:3] op_sel_hi:[1,0]
	v_pk_mul_f32 v[34:35], v[42:43], v[40:41] op_sel_hi:[0,1]
	v_pk_mul_f32 v[20:21], v[20:21], s[2:3] op_sel_hi:[1,0]
	v_pk_mul_f32 v[40:41], v[86:87], s[2:3] op_sel_hi:[1,0]
	v_pk_mul_f32 v[42:43], v[74:75], s[2:3] op_sel_hi:[1,0]
	v_pk_mul_f32 v[74:75], v[20:21], v[92:93]
	v_pk_mul_f32 v[28:29], v[72:73], v[28:29]
	v_add_co_u32_e32 v32, vcc, s3, v64
	v_pk_fma_f32 v[34:35], v[34:35], v[138:139], v[38:39]
	v_pk_fma_f32 v[36:37], v[36:37], v[140:141], v[50:51]
	global_store_dwordx4 v[48:49], v[34:37], off offset:2064
	v_lshlrev_b32_e32 v38, 16, v30
	v_and_b32_e32 v39, 0xffff0000, v30
	v_lshlrev_b32_e32 v30, 16, v31
	v_and_b32_e32 v31, 0xffff0000, v31
	s_waitcnt vmcnt(14)
	v_lshlrev_b32_e32 v44, 16, v24
	v_and_b32_e32 v45, 0xffff0000, v24
	v_lshlrev_b32_e32 v24, 16, v25
	v_and_b32_e32 v25, 0xffff0000, v25
	v_pk_mul_f32 v[46:47], v[90:91], s[2:3] op_sel_hi:[1,0]
	v_pk_mul_f32 v[48:49], v[88:89], s[2:3] op_sel_hi:[1,0]
	v_lshlrev_b32_e32 v50, 16, v26
	v_and_b32_e32 v51, 0xffff0000, v26
	v_lshlrev_b32_e32 v26, 16, v27
	v_and_b32_e32 v27, 0xffff0000, v27
	v_pk_mul_f32 v[38:39], v[80:81], v[38:39]
	v_pk_mul_f32 v[72:73], v[82:83], v[30:31]
	v_pk_mul_f32 v[42:43], v[42:43], v[24:25]
	v_pk_mul_f32 v[40:41], v[40:41], v[44:45]
	v_pk_mul_f32 v[20:21], v[48:49], v[26:27]
	v_pk_mul_f32 v[24:25], v[46:47], v[50:51]
	v_pk_mul_f32 v[26:27], v[28:29], v[28:29]
	v_pk_mul_f32 v[30:31], v[74:75], v[74:75]
	v_pk_mul_f32 v[44:45], v[72:73], v[72:73]
	v_pk_mul_f32 v[46:47], v[38:39], v[38:39]
	v_pk_mov_b32 v[80:81], v[30:31], v[26:27] op_sel:[1,0]
	v_mov_b32_e32 v31, v27
	v_pk_mov_b32 v[26:27], v[46:47], v[44:45] op_sel:[1,0]
	v_mov_b32_e32 v47, v45
	v_mul_f32_e32 v51, v24, v24
	v_mul_f32_e32 v48, v41, v41
	v_mul_f32_e32 v50, v43, v43
	v_pk_add_f32 v[30:31], v[80:81], v[30:31]
	v_pk_add_f32 v[26:27], v[26:27], v[46:47]
	v_mul_f32_e32 v82, v25, v25
	v_mul_f32_e32 v83, v20, v20
	v_mul_f32_e32 v84, v21, v21
	v_pk_fma_f32 v[44:45], v[40:41], v[40:41], v[48:49] op_sel_hi:[1,1,0]
	v_pk_fma_f32 v[48:49], v[42:43], v[42:43], v[50:51] op_sel_hi:[1,1,0]
	v_pk_add_f32 v[30:31], v[30:31], v[30:31] op_sel:[0,1] op_sel_hi:[1,0]
	v_pk_add_f32 v[26:27], v[26:27], v[26:27] op_sel:[0,1] op_sel_hi:[1,0]
	v_mov_b32_e32 v45, v83
	v_mov_b32_e32 v49, v84
	v_mov_b32_e32 v31, v51
	v_mov_b32_e32 v27, v82
	v_pk_add_f32 v[44:45], v[44:45], v[48:49]
	v_pk_add_f32 v[26:27], v[30:31], v[26:27]
	v_addc_co_u32_e32 v33, vcc, 0, v65, vcc
	v_pk_add_f32 v[26:27], v[26:27], v[44:45]
	s_waitcnt vmcnt(10)
	v_cvt_f32_ubyte3_e32 v45, v68
	v_add_f32_e32 v26, v26, v27
	v_cvt_f32_ubyte2_e32 v44, v68
	v_cvt_f32_ubyte1_e32 v47, v68
	v_add_f32_dpp v26, v26, v26 quad_perm:[1,0,3,2] row_mask:0xf bank_mask:0xf bound_ctrl:1
	v_cvt_f32_ubyte0_e32 v46, v68
	v_cvt_f32_ubyte3_e32 v49, v69
	v_add_f32_dpp v26, v26, v26 quad_perm:[2,3,0,1] row_mask:0xf bank_mask:0xf bound_ctrl:1
	v_cvt_f32_ubyte2_e32 v48, v69
	v_cvt_f32_ubyte1_e32 v51, v69
	v_add_f32_dpp v26, v26, v26 row_half_mirror row_mask:0xf bank_mask:0xf bound_ctrl:1
	v_cvt_f32_ubyte0_e32 v50, v69
	s_waitcnt vmcnt(9)
	v_lshlrev_b32_e32 v68, 16, v12
	v_add_f32_dpp v26, v26, v26 row_mirror row_mask:0xf bank_mask:0xf bound_ctrl:1
	v_and_b32_e32 v69, 0xffff0000, v12
	v_readlane_b32 s11, v26, 16
	v_readlane_b32 s14, v26, 48
	v_readlane_b32 s12, v26, 0
	v_readlane_b32 s13, v26, 32
	v_mov_b32_e32 v26, s11
	v_mov_b32_e32 v27, s14
	v_pk_add_f32 v[26:27], s[12:13], v[26:27]
	v_lshlrev_b32_e32 v12, 16, v13
	v_add_f32_e32 v26, v26, v27
	v_fmamk_f32 v26, v26, 0x3a800000, v85
	v_rsq_f32_e32 v26, v26
	v_and_b32_e32 v13, 0xffff0000, v13
	v_pk_mul_f32 v[30:31], v[26:27], v[28:29] op_sel_hi:[0,1]
	v_pk_mul_f32 v[28:29], v[26:27], v[74:75] op_sel_hi:[0,1]
	v_pk_fma_f32 v[28:29], v[28:29], v[126:127], v[76:77]
	v_pk_fma_f32 v[30:31], v[30:31], v[128:129], v[78:79]
	global_store_dwordx4 v[32:33], v[28:31], off
	v_lshlrev_b32_e32 v34, 16, v22
	v_and_b32_e32 v35, 0xffff0000, v22
	v_lshlrev_b32_e32 v22, 16, v23
	v_and_b32_e32 v23, 0xffff0000, v23
	v_pk_mul_f32 v[36:37], v[26:27], v[72:73] op_sel_hi:[0,1]
	v_pk_mul_f32 v[38:39], v[26:27], v[38:39] op_sel_hi:[0,1]
	v_pk_mul_f32 v[20:21], v[26:27], v[20:21] op_sel_hi:[0,1]
	v_pk_mul_f32 v[24:25], v[26:27], v[24:25] op_sel_hi:[0,1]
	v_pk_fma_f32 v[28:29], v[38:39], v[130:131], v[34:35]
	v_pk_fma_f32 v[30:31], v[36:37], v[132:133], v[22:23]
	global_store_dwordx4 v[32:33], v[28:31], off offset:16
	v_lshlrev_b32_e32 v22, 16, v16
	v_and_b32_e32 v23, 0xffff0000, v16
	v_lshlrev_b32_e32 v16, 16, v17
	v_and_b32_e32 v17, 0xffff0000, v17
	v_pk_mul_f32 v[34:35], v[26:27], v[42:43] op_sel_hi:[0,1]
	v_pk_mul_f32 v[36:37], v[26:27], v[40:41] op_sel_hi:[0,1]
	v_cvt_f32_ubyte3_e32 v39, v70
	v_cvt_f32_ubyte2_e32 v38, v70
	v_cvt_f32_ubyte1_e32 v41, v71
	v_cvt_f32_ubyte0_e32 v40, v71
	v_cvt_f32_ubyte3_e32 v43, v71
	v_cvt_f32_ubyte2_e32 v42, v71
	v_pk_mul_f32 v[38:39], v[38:39], s[2:3] op_sel_hi:[1,0]
	v_lshlrev_b32_e32 v26, 16, v14
	v_and_b32_e32 v27, 0xffff0000, v14
	v_lshlrev_b32_e32 v14, 16, v15
	v_and_b32_e32 v15, 0xffff0000, v15
	v_pk_mul_f32 v[12:13], v[38:39], v[12:13]
	v_pk_fma_f32 v[28:29], v[36:37], v[134:135], v[22:23]
	v_pk_fma_f32 v[30:31], v[34:35], v[136:137], v[16:17]
	global_store_dwordx4 v[32:33], v[28:31], off offset:2048
	v_lshlrev_b32_e32 v16, 16, v18
	v_and_b32_e32 v17, 0xffff0000, v18
	v_lshlrev_b32_e32 v18, 16, v19
	v_and_b32_e32 v19, 0xffff0000, v19
	v_cvt_f32_ubyte1_e32 v37, v70
	v_cvt_f32_ubyte0_e32 v36, v70
	v_pk_mul_f32 v[36:37], v[36:37], s[2:3] op_sel_hi:[1,0]
	v_add_co_u32_e32 v22, vcc, s10, v64
	v_pk_mul_f32 v[36:37], v[36:37], v[68:69]
	v_lshlrev_b32_e32 v34, 16, v4
	v_and_b32_e32 v35, 0xffff0000, v4
	v_lshlrev_b32_e32 v4, 16, v5
	v_and_b32_e32 v5, 0xffff0000, v5
	v_addc_co_u32_e32 v23, vcc, 0, v65, vcc
	v_lshl_add_u64 v[64:65], v[64:65], 0, s[6:7]
	v_pk_fma_f32 v[16:17], v[24:25], v[138:139], v[16:17]
	v_pk_fma_f32 v[18:19], v[20:21], v[140:141], v[18:19]
	global_store_dwordx4 v[32:33], v[16:19], off offset:2064
	v_pk_mul_f32 v[20:21], v[42:43], s[2:3] op_sel_hi:[1,0]
	v_pk_mul_f32 v[24:25], v[40:41], s[2:3] op_sel_hi:[1,0]
	v_pk_mul_f32 v[28:29], v[46:47], s[2:3] op_sel_hi:[1,0]
	v_pk_mul_f32 v[30:31], v[44:45], s[2:3] op_sel_hi:[1,0]
	s_waitcnt vmcnt(12)
	v_lshlrev_b32_e32 v32, 16, v8
	v_and_b32_e32 v33, 0xffff0000, v8
	v_lshlrev_b32_e32 v8, 16, v9
	v_and_b32_e32 v9, 0xffff0000, v9
	v_pk_mul_f32 v[42:43], v[48:49], s[2:3] op_sel_hi:[1,0]
	v_lshlrev_b32_e32 v44, 16, v10
	v_and_b32_e32 v45, 0xffff0000, v10
	v_lshlrev_b32_e32 v10, 16, v11
	v_and_b32_e32 v11, 0xffff0000, v11
	v_pk_mul_f32 v[24:25], v[24:25], v[26:27]
	v_pk_mul_f32 v[14:15], v[20:21], v[14:15]
	v_pk_mul_f32 v[40:41], v[50:51], s[2:3] op_sel_hi:[1,0]
	v_pk_mul_f32 v[20:21], v[30:31], v[8:9]
	v_pk_mul_f32 v[26:27], v[28:29], v[32:33]
	v_pk_mul_f32 v[28:29], v[42:43], v[10:11]
	v_pk_mul_f32 v[8:9], v[12:13], v[12:13]
	v_pk_mul_f32 v[10:11], v[36:37], v[36:37]
	v_pk_mul_f32 v[32:33], v[14:15], v[14:15]
	v_pk_mul_f32 v[38:39], v[24:25], v[24:25]
	v_pk_mul_f32 v[30:31], v[40:41], v[44:45]
	v_pk_mov_b32 v[44:45], v[10:11], v[8:9] op_sel:[1,0]
	v_mov_b32_e32 v11, v9
	v_pk_mov_b32 v[8:9], v[38:39], v[32:33] op_sel:[1,0]
	v_mov_b32_e32 v39, v33
	v_mul_f32_e32 v43, v30, v30
	v_mul_f32_e32 v40, v27, v27
	v_mul_f32_e32 v42, v21, v21
	v_pk_add_f32 v[10:11], v[44:45], v[10:11]
	v_pk_add_f32 v[8:9], v[8:9], v[38:39]
	v_mul_f32_e32 v46, v31, v31
	v_mul_f32_e32 v47, v28, v28
	v_mul_f32_e32 v48, v29, v29
	v_pk_fma_f32 v[32:33], v[26:27], v[26:27], v[40:41] op_sel_hi:[1,1,0]
	v_pk_fma_f32 v[40:41], v[20:21], v[20:21], v[42:43] op_sel_hi:[1,1,0]
	v_pk_add_f32 v[10:11], v[10:11], v[10:11] op_sel:[0,1] op_sel_hi:[1,0]
	v_pk_add_f32 v[8:9], v[8:9], v[8:9] op_sel:[0,1] op_sel_hi:[1,0]
	v_mov_b32_e32 v33, v47
	v_mov_b32_e32 v41, v48
	v_mov_b32_e32 v11, v43
	v_mov_b32_e32 v9, v46
	v_pk_add_f32 v[32:33], v[32:33], v[40:41]
	v_pk_add_f32 v[8:9], v[10:11], v[8:9]
	s_nop 0
	v_pk_add_f32 v[8:9], v[8:9], v[32:33]
	s_nop 0
	v_add_f32_e32 v8, v8, v9
	s_nop 1
	v_add_f32_dpp v8, v8, v8 quad_perm:[1,0,3,2] row_mask:0xf bank_mask:0xf bound_ctrl:1
	s_nop 1
	v_add_f32_dpp v8, v8, v8 quad_perm:[2,3,0,1] row_mask:0xf bank_mask:0xf bound_ctrl:1
	s_nop 1
	v_add_f32_dpp v8, v8, v8 row_half_mirror row_mask:0xf bank_mask:0xf bound_ctrl:1
	s_nop 1
	v_add_f32_dpp v8, v8, v8 row_mirror row_mask:0xf bank_mask:0xf bound_ctrl:1
	s_nop 0
	v_readlane_b32 s11, v8, 16
	v_readlane_b32 s14, v8, 48
	v_readlane_b32 s12, v8, 0
	v_readlane_b32 s13, v8, 32
	v_mov_b32_e32 v8, s11
	v_mov_b32_e32 v9, s14
	v_pk_add_f32 v[8:9], s[12:13], v[8:9]
	s_nop 0
	v_add_f32_e32 v8, v8, v9
	v_fmamk_f32 v8, v8, 0x3a800000, v85
	v_rsq_f32_e32 v32, v8
	s_nop 0
	v_pk_mul_f32 v[10:11], v[32:33], v[12:13] op_sel_hi:[0,1]
	v_pk_mul_f32 v[8:9], v[32:33], v[36:37] op_sel_hi:[0,1]
	v_pk_fma_f32 v[8:9], v[8:9], v[126:127], v[34:35]
	v_pk_fma_f32 v[10:11], v[10:11], v[128:129], v[4:5]
	global_store_dwordx4 v[22:23], v[8:11], off
	v_lshlrev_b32_e32 v4, 16, v6
	v_and_b32_e32 v5, 0xffff0000, v6
	v_lshlrev_b32_e32 v6, 16, v7
	v_and_b32_e32 v7, 0xffff0000, v7
	v_pk_mul_f32 v[12:13], v[32:33], v[14:15] op_sel_hi:[0,1]
	v_pk_mul_f32 v[14:15], v[32:33], v[24:25] op_sel_hi:[0,1]
	v_pk_fma_f32 v[4:5], v[14:15], v[130:131], v[4:5]
	v_pk_fma_f32 v[6:7], v[12:13], v[132:133], v[6:7]
	global_store_dwordx4 v[22:23], v[4:7], off offset:16
	v_lshlrev_b32_e32 v8, 16, v0
	v_and_b32_e32 v9, 0xffff0000, v0
	v_lshlrev_b32_e32 v0, 16, v1
	v_and_b32_e32 v1, 0xffff0000, v1
	v_pk_mul_f32 v[10:11], v[32:33], v[20:21] op_sel_hi:[0,1]
	v_pk_mul_f32 v[12:13], v[32:33], v[26:27] op_sel_hi:[0,1]
	v_pk_fma_f32 v[4:5], v[12:13], v[134:135], v[8:9]
	v_pk_fma_f32 v[6:7], v[10:11], v[136:137], v[0:1]
	global_store_dwordx4 v[22:23], v[4:7], off offset:2048
	v_lshlrev_b32_e32 v0, 16, v2
	v_and_b32_e32 v1, 0xffff0000, v2
	v_lshlrev_b32_e32 v2, 16, v3
	v_and_b32_e32 v3, 0xffff0000, v3
	v_pk_mul_f32 v[8:9], v[32:33], v[28:29] op_sel_hi:[0,1]
	v_pk_mul_f32 v[10:11], v[32:33], v[30:31] op_sel_hi:[0,1]
	v_pk_fma_f32 v[0:1], v[10:11], v[138:139], v[0:1]
	v_pk_fma_f32 v[2:3], v[8:9], v[140:141], v[2:3]
	global_store_dwordx4 v[22:23], v[0:3], off offset:2064
	s_cbranch_scc0 .LBB0_1761
